# previous + every 32-MFMA block in the GEMM K-loops padded (one s_nop in the preceding load segment where needed) to start 8-byte aligned
# speedup vs baseline: 1.0095x; 1.0013x over previous
.LBB0_287:
	ds_read_b128 v[160:163], v156
	ds_read_b128 v[164:167], v156 offset:1024
	ds_read_b128 v[168:171], v156 offset:2048
	ds_read_b128 v[172:175], v156 offset:3072
	ds_read_b128 v[176:179], v157
	ds_read_b128 v[180:183], v157 offset:1024
	ds_read_b128 v[184:187], v157 offset:2048
	ds_read_b128 v[188:191], v157 offset:3072
	s_add_u32 s28, s26, 0xfff00080
	s_addc_u32 s29, s27, -1
	s_cmp_eq_u32 s58, 60
	s_cselect_b32 s31, s21, s29
	s_cselect_b32 s30, s54, s28
	s_cselect_b32 s29, s19, s57
	s_cselect_b32 s28, s55, s56
	v_lshl_add_u64 v[192:193], s[26:27], 0, v[138:139]
	s_add_i32 m0, s17, 0xc000
	ds_read_b128 v[196:199], v158
	ds_read_b128 v[200:203], v158 offset:1024
	ds_read_b128 v[204:207], v158 offset:2048
	ds_read_b128 v[208:211], v158 offset:3072
	ds_read_b128 v[212:215], v158 offset:4096
	ds_read_b128 v[216:219], v158 offset:5120
	ds_read_b128 v[220:223], v158 offset:6144
	ds_read_b128 v[224:227], v158 offset:7168
	global_load_lds_dwordx4 v[192:193], off
	v_lshl_add_u64 v[192:193], s[26:27], 0, v[140:141]
	s_add_i32 m0, s17, 0xe000
	s_nop 0
	global_load_lds_dwordx4 v[192:193], off
	s_nop 0
	s_waitcnt vmcnt(8)
	s_waitcnt lgkmcnt(0)
	s_barrier
	s_setprio 1
	v_mfma_f32_16x16x32_bf16 v[126:129], v[160:163], v[196:199], v[126:129]
	v_mfma_f32_16x16x32_bf16 v[122:125], v[168:171], v[196:199], v[122:125]
	v_mfma_f32_16x16x32_bf16 v[118:121], v[160:163], v[204:207], v[118:121]
	v_mfma_f32_16x16x32_bf16 v[114:117], v[168:171], v[204:207], v[114:117]
	v_mfma_f32_16x16x32_bf16 v[102:105], v[160:163], v[212:215], v[102:105]
	v_mfma_f32_16x16x32_bf16 v[98:101], v[168:171], v[212:215], v[98:101]
	v_mfma_f32_16x16x32_bf16 v[86:89], v[160:163], v[220:223], v[86:89]
	v_mfma_f32_16x16x32_bf16 v[82:85], v[168:171], v[220:223], v[82:85]
	v_mfma_f32_16x16x32_bf16 v[126:129], v[164:167], v[200:203], v[126:129]
	v_mfma_f32_16x16x32_bf16 v[122:125], v[172:175], v[200:203], v[122:125]
	v_mfma_f32_16x16x32_bf16 v[118:121], v[164:167], v[208:211], v[118:121]
	v_mfma_f32_16x16x32_bf16 v[114:117], v[172:175], v[208:211], v[114:117]
	v_mfma_f32_16x16x32_bf16 v[102:105], v[164:167], v[216:219], v[102:105]
	v_mfma_f32_16x16x32_bf16 v[98:101], v[172:175], v[216:219], v[98:101]
	v_mfma_f32_16x16x32_bf16 v[86:89], v[164:167], v[224:227], v[86:89]
	v_mfma_f32_16x16x32_bf16 v[82:85], v[172:175], v[224:227], v[82:85]
	v_mfma_f32_16x16x32_bf16 v[110:113], v[176:179], v[196:199], v[110:113]
	v_mfma_f32_16x16x32_bf16 v[106:109], v[184:187], v[196:199], v[106:109]
	v_mfma_f32_16x16x32_bf16 v[94:97], v[176:179], v[204:207], v[94:97]
	v_mfma_f32_16x16x32_bf16 v[90:93], v[184:187], v[204:207], v[90:93]
	v_mfma_f32_16x16x32_bf16 v[78:81], v[176:179], v[212:215], v[78:81]
	v_mfma_f32_16x16x32_bf16 v[74:77], v[184:187], v[212:215], v[74:77]
	v_mfma_f32_16x16x32_bf16 v[70:73], v[176:179], v[220:223], v[70:73]
	v_mfma_f32_16x16x32_bf16 v[66:69], v[184:187], v[220:223], v[66:69]
	v_mfma_f32_16x16x32_bf16 v[110:113], v[180:183], v[200:203], v[110:113]
	v_mfma_f32_16x16x32_bf16 v[106:109], v[188:191], v[200:203], v[106:109]
	v_mfma_f32_16x16x32_bf16 v[94:97], v[180:183], v[208:211], v[94:97]
	v_mfma_f32_16x16x32_bf16 v[90:93], v[188:191], v[208:211], v[90:93]
	v_mfma_f32_16x16x32_bf16 v[78:81], v[180:183], v[216:219], v[78:81]
	v_mfma_f32_16x16x32_bf16 v[74:77], v[188:191], v[216:219], v[74:77]
	v_mfma_f32_16x16x32_bf16 v[70:73], v[180:183], v[224:227], v[70:73]
	v_mfma_f32_16x16x32_bf16 v[66:69], v[188:191], v[224:227], v[66:69]
	s_setprio 0
	s_barrier
	s_add_i32 s59, s50, s41
	v_lshl_add_u64 v[192:193], s[28:29], 0, v[134:135]
	s_mov_b32 m0, s59
	ds_read_b128 v[196:199], v158 offset:16384
	ds_read_b128 v[200:203], v158 offset:17408
	ds_read_b128 v[204:207], v158 offset:18432
	ds_read_b128 v[208:211], v158 offset:19456
	ds_read_b128 v[212:215], v158 offset:20480
	ds_read_b128 v[216:219], v158 offset:21504
	ds_read_b128 v[220:223], v158 offset:22528
	ds_read_b128 v[224:227], v158 offset:23552
	global_load_lds_dwordx4 v[192:193], off
	s_add_i32 m0, s59, 0x2000
	s_add_u32 s60, s28, 0x100000
	v_lshl_add_u64 v[228:229], s[28:29], 0, v[136:137]
	s_addc_u32 s61, s29, 0
	s_add_i32 s59, s51, s41
	global_load_lds_dwordx4 v[228:229], off
	v_lshl_add_u64 v[230:231], s[60:61], 0, v[134:135]
	s_mov_b32 m0, s59
	v_lshl_add_u64 v[232:233], s[30:31], 0, v[132:133]
	global_load_lds_dwordx4 v[230:231], off
	v_lshl_add_u64 v[230:231], s[60:61], 0, v[136:137]
	s_add_i32 m0, s59, 0x2000
	s_nop 0
	global_load_lds_dwordx4 v[230:231], off
	v_lshl_add_u64 v[230:231], s[30:31], 0, v[130:131]
	s_mov_b32 m0, s17
	s_nop 0
	global_load_lds_dwordx4 v[230:231], off
	s_mov_b32 m0, s42
	s_nop 0
	global_load_lds_dwordx4 v[232:233], off
	s_waitcnt vmcnt(8)
	s_waitcnt lgkmcnt(0)
	s_barrier
	s_setprio 1
	v_mfma_f32_16x16x32_bf16 v[62:65], v[160:163], v[196:199], v[62:65]
	v_mfma_f32_16x16x32_bf16 v[58:61], v[168:171], v[196:199], v[58:61]
	v_mfma_f32_16x16x32_bf16 v[54:57], v[160:163], v[204:207], v[54:57]
	v_mfma_f32_16x16x32_bf16 v[50:53], v[168:171], v[204:207], v[50:53]
	v_mfma_f32_16x16x32_bf16 v[38:41], v[160:163], v[212:215], v[38:41]
	v_mfma_f32_16x16x32_bf16 v[34:37], v[168:171], v[212:215], v[34:37]
	v_mfma_f32_16x16x32_bf16 v[22:25], v[160:163], v[220:223], v[22:25]
	v_mfma_f32_16x16x32_bf16 v[18:21], v[168:171], v[220:223], v[18:21]
	v_mfma_f32_16x16x32_bf16 v[62:65], v[164:167], v[200:203], v[62:65]
	v_mfma_f32_16x16x32_bf16 v[58:61], v[172:175], v[200:203], v[58:61]
	v_mfma_f32_16x16x32_bf16 v[54:57], v[164:167], v[208:211], v[54:57]
	v_mfma_f32_16x16x32_bf16 v[50:53], v[172:175], v[208:211], v[50:53]
	v_mfma_f32_16x16x32_bf16 v[38:41], v[164:167], v[216:219], v[38:41]
	v_mfma_f32_16x16x32_bf16 v[34:37], v[172:175], v[216:219], v[34:37]
	v_mfma_f32_16x16x32_bf16 v[22:25], v[164:167], v[224:227], v[22:25]
	v_mfma_f32_16x16x32_bf16 v[18:21], v[172:175], v[224:227], v[18:21]
	v_mfma_f32_16x16x32_bf16 v[46:49], v[176:179], v[196:199], v[46:49]
	v_mfma_f32_16x16x32_bf16 v[42:45], v[184:187], v[196:199], v[42:45]
	v_mfma_f32_16x16x32_bf16 v[30:33], v[176:179], v[204:207], v[30:33]
	v_mfma_f32_16x16x32_bf16 v[26:29], v[184:187], v[204:207], v[26:29]
	v_mfma_f32_16x16x32_bf16 v[14:17], v[176:179], v[212:215], v[14:17]
	v_mfma_f32_16x16x32_bf16 v[10:13], v[184:187], v[212:215], v[10:13]
	v_mfma_f32_16x16x32_bf16 v[6:9], v[176:179], v[220:223], v[6:9]
	v_mfma_f32_16x16x32_bf16 v[2:5], v[184:187], v[220:223], v[2:5]
	v_mfma_f32_16x16x32_bf16 v[46:49], v[180:183], v[200:203], v[46:49]
	v_mfma_f32_16x16x32_bf16 v[42:45], v[188:191], v[200:203], v[42:45]
	v_mfma_f32_16x16x32_bf16 v[30:33], v[180:183], v[208:211], v[30:33]
	v_mfma_f32_16x16x32_bf16 v[26:29], v[188:191], v[208:211], v[26:29]
	v_mfma_f32_16x16x32_bf16 v[14:17], v[180:183], v[216:219], v[14:17]
	v_mfma_f32_16x16x32_bf16 v[10:13], v[188:191], v[216:219], v[10:13]
	v_mfma_f32_16x16x32_bf16 v[6:9], v[180:183], v[224:227], v[6:9]
	v_mfma_f32_16x16x32_bf16 v[2:5], v[188:191], v[224:227], v[2:5]
	s_setprio 0
	s_barrier
	s_add_i32 s59, 0, 0x18000
	v_add_u32_e32 v159, s59, v154
	s_add_i32 s60, 0, 0x1c000
	ds_read_b128 v[160:163], v159
	ds_read_b128 v[164:167], v159 offset:1024
	ds_read_b128 v[168:171], v159 offset:2048
	ds_read_b128 v[172:175], v159 offset:3072
	v_add_u32_e32 v159, s60, v154
	ds_read_b128 v[176:179], v159
	ds_read_b128 v[180:183], v159 offset:1024
	ds_read_b128 v[184:187], v159 offset:2048
	ds_read_b128 v[188:191], v159 offset:3072
	s_add_u32 s30, s30, 0x100000
	s_addc_u32 s31, s31, 0
	s_mov_b32 m0, s43
	v_lshl_add_u64 v[234:235], s[30:31], 0, v[130:131]
	ds_read_b128 v[196:199], v158 offset:32768
	ds_read_b128 v[200:203], v158 offset:33792
	ds_read_b128 v[204:207], v158 offset:34816
	ds_read_b128 v[208:211], v158 offset:35840
	ds_read_b128 v[212:215], v158 offset:36864
	ds_read_b128 v[216:219], v158 offset:37888
	ds_read_b128 v[220:223], v158 offset:38912
	ds_read_b128 v[224:227], v158 offset:39936
	global_load_lds_dwordx4 v[234:235], off
	v_lshl_add_u64 v[234:235], s[30:31], 0, v[132:133]
	s_mov_b32 m0, s45
	s_nop 0
	global_load_lds_dwordx4 v[234:235], off
	s_waitcnt vmcnt(8)
	s_waitcnt lgkmcnt(0)
	s_barrier
	s_setprio 1
	v_mfma_f32_16x16x32_bf16 v[126:129], v[160:163], v[196:199], v[126:129]
	v_mfma_f32_16x16x32_bf16 v[122:125], v[168:171], v[196:199], v[122:125]
	v_mfma_f32_16x16x32_bf16 v[118:121], v[160:163], v[204:207], v[118:121]
	v_mfma_f32_16x16x32_bf16 v[114:117], v[168:171], v[204:207], v[114:117]
	v_mfma_f32_16x16x32_bf16 v[102:105], v[160:163], v[212:215], v[102:105]
	v_mfma_f32_16x16x32_bf16 v[98:101], v[168:171], v[212:215], v[98:101]
	v_mfma_f32_16x16x32_bf16 v[86:89], v[160:163], v[220:223], v[86:89]
	v_mfma_f32_16x16x32_bf16 v[82:85], v[168:171], v[220:223], v[82:85]
	v_mfma_f32_16x16x32_bf16 v[126:129], v[164:167], v[200:203], v[126:129]
	v_mfma_f32_16x16x32_bf16 v[122:125], v[172:175], v[200:203], v[122:125]
	v_mfma_f32_16x16x32_bf16 v[118:121], v[164:167], v[208:211], v[118:121]
	v_mfma_f32_16x16x32_bf16 v[114:117], v[172:175], v[208:211], v[114:117]
	v_mfma_f32_16x16x32_bf16 v[102:105], v[164:167], v[216:219], v[102:105]
	v_mfma_f32_16x16x32_bf16 v[98:101], v[172:175], v[216:219], v[98:101]
	v_mfma_f32_16x16x32_bf16 v[86:89], v[164:167], v[224:227], v[86:89]
	v_mfma_f32_16x16x32_bf16 v[82:85], v[172:175], v[224:227], v[82:85]
	v_mfma_f32_16x16x32_bf16 v[110:113], v[176:179], v[196:199], v[110:113]
	v_mfma_f32_16x16x32_bf16 v[106:109], v[184:187], v[196:199], v[106:109]
	v_mfma_f32_16x16x32_bf16 v[94:97], v[176:179], v[204:207], v[94:97]
	v_mfma_f32_16x16x32_bf16 v[90:93], v[184:187], v[204:207], v[90:93]
	v_mfma_f32_16x16x32_bf16 v[78:81], v[176:179], v[212:215], v[78:81]
	v_mfma_f32_16x16x32_bf16 v[74:77], v[184:187], v[212:215], v[74:77]
	v_mfma_f32_16x16x32_bf16 v[70:73], v[176:179], v[220:223], v[70:73]
	v_mfma_f32_16x16x32_bf16 v[66:69], v[184:187], v[220:223], v[66:69]
	v_mfma_f32_16x16x32_bf16 v[110:113], v[180:183], v[200:203], v[110:113]
	v_mfma_f32_16x16x32_bf16 v[106:109], v[188:191], v[200:203], v[106:109]
	v_mfma_f32_16x16x32_bf16 v[94:97], v[180:183], v[208:211], v[94:97]
	v_mfma_f32_16x16x32_bf16 v[90:93], v[188:191], v[208:211], v[90:93]
	v_mfma_f32_16x16x32_bf16 v[78:81], v[180:183], v[216:219], v[78:81]
	v_mfma_f32_16x16x32_bf16 v[74:77], v[188:191], v[216:219], v[74:77]
	v_mfma_f32_16x16x32_bf16 v[70:73], v[180:183], v[224:227], v[70:73]
	v_mfma_f32_16x16x32_bf16 v[66:69], v[188:191], v[224:227], v[66:69]
	s_setprio 0
	s_barrier
	s_add_i32 s30, s59, s41
	v_lshl_add_u64 v[192:193], v[192:193], 0, s[12:13]
	s_mov_b32 m0, s30
	ds_read_b128 v[196:199], v158 offset:49152
	ds_read_b128 v[200:203], v158 offset:50176
	ds_read_b128 v[204:207], v158 offset:51200
	ds_read_b128 v[208:211], v158 offset:52224
	ds_read_b128 v[212:215], v158 offset:53248
	ds_read_b128 v[216:219], v158 offset:54272
	ds_read_b128 v[220:223], v158 offset:55296
	ds_read_b128 v[224:227], v158 offset:56320
	global_load_lds_dwordx4 v[192:193], off
	s_add_i32 m0, s30, 0x2000
	s_add_u32 s28, s28, 0x100080
	v_lshl_add_u64 v[192:193], v[228:229], 0, s[12:13]
	s_addc_u32 s29, s29, 0
	s_add_i32 s30, s60, s41
	global_load_lds_dwordx4 v[192:193], off
	v_lshl_add_u64 v[192:193], s[28:29], 0, v[134:135]
	s_mov_b32 m0, s30
	s_nop 0
	global_load_lds_dwordx4 v[192:193], off
	v_lshl_add_u64 v[192:193], s[28:29], 0, v[136:137]
	s_add_i32 m0, s30, 0x2000
	s_nop 0
	global_load_lds_dwordx4 v[192:193], off
	v_lshl_add_u64 v[192:193], v[230:231], 0, s[12:13]
	s_mov_b32 m0, s47
	s_nop 0
	global_load_lds_dwordx4 v[192:193], off
	v_lshl_add_u64 v[192:193], v[232:233], 0, s[12:13]
	s_mov_b32 m0, s48
	s_nop 0
	global_load_lds_dwordx4 v[192:193], off
	s_nop 0
	s_waitcnt vmcnt(8)
	s_waitcnt lgkmcnt(0)
	s_barrier
	s_setprio 1
	v_mfma_f32_16x16x32_bf16 v[62:65], v[160:163], v[196:199], v[62:65]
	v_mfma_f32_16x16x32_bf16 v[58:61], v[168:171], v[196:199], v[58:61]
	v_mfma_f32_16x16x32_bf16 v[54:57], v[160:163], v[204:207], v[54:57]
	v_mfma_f32_16x16x32_bf16 v[50:53], v[168:171], v[204:207], v[50:53]
	v_mfma_f32_16x16x32_bf16 v[38:41], v[160:163], v[212:215], v[38:41]
	v_mfma_f32_16x16x32_bf16 v[34:37], v[168:171], v[212:215], v[34:37]
	v_mfma_f32_16x16x32_bf16 v[22:25], v[160:163], v[220:223], v[22:25]
	v_mfma_f32_16x16x32_bf16 v[18:21], v[168:171], v[220:223], v[18:21]
	v_mfma_f32_16x16x32_bf16 v[62:65], v[164:167], v[200:203], v[62:65]
	v_mfma_f32_16x16x32_bf16 v[58:61], v[172:175], v[200:203], v[58:61]
	v_mfma_f32_16x16x32_bf16 v[54:57], v[164:167], v[208:211], v[54:57]
	v_mfma_f32_16x16x32_bf16 v[50:53], v[172:175], v[208:211], v[50:53]
	v_mfma_f32_16x16x32_bf16 v[38:41], v[164:167], v[216:219], v[38:41]
	v_mfma_f32_16x16x32_bf16 v[34:37], v[172:175], v[216:219], v[34:37]
	v_mfma_f32_16x16x32_bf16 v[22:25], v[164:167], v[224:227], v[22:25]
	v_mfma_f32_16x16x32_bf16 v[18:21], v[172:175], v[224:227], v[18:21]
	v_mfma_f32_16x16x32_bf16 v[46:49], v[176:179], v[196:199], v[46:49]
	v_mfma_f32_16x16x32_bf16 v[42:45], v[184:187], v[196:199], v[42:45]
	v_mfma_f32_16x16x32_bf16 v[30:33], v[176:179], v[204:207], v[30:33]
	v_mfma_f32_16x16x32_bf16 v[26:29], v[184:187], v[204:207], v[26:29]
	v_mfma_f32_16x16x32_bf16 v[14:17], v[176:179], v[212:215], v[14:17]
	v_mfma_f32_16x16x32_bf16 v[10:13], v[184:187], v[212:215], v[10:13]
	v_mfma_f32_16x16x32_bf16 v[6:9], v[176:179], v[220:223], v[6:9]
	v_mfma_f32_16x16x32_bf16 v[2:5], v[184:187], v[220:223], v[2:5]
	v_mfma_f32_16x16x32_bf16 v[46:49], v[180:183], v[200:203], v[46:49]
	v_mfma_f32_16x16x32_bf16 v[42:45], v[188:191], v[200:203], v[42:45]
	v_mfma_f32_16x16x32_bf16 v[30:33], v[180:183], v[208:211], v[30:33]
	v_mfma_f32_16x16x32_bf16 v[26:29], v[188:191], v[208:211], v[26:29]
	v_mfma_f32_16x16x32_bf16 v[14:17], v[180:183], v[216:219], v[14:17]
	v_mfma_f32_16x16x32_bf16 v[10:13], v[188:191], v[216:219], v[10:13]
	v_mfma_f32_16x16x32_bf16 v[6:9], v[180:183], v[224:227], v[6:9]
	v_mfma_f32_16x16x32_bf16 v[2:5], v[188:191], v[224:227], v[2:5]
	s_setprio 0
	s_barrier
	s_add_i32 s58, s58, 2
	s_add_u32 s26, s26, 0x100
	s_addc_u32 s27, s27, 0
	s_add_u32 s56, s56, 0x100
	s_addc_u32 s57, s57, 0
	s_cmp_gt_u32 s58, 61
	s_cbranch_scc0 .LBB0_287
	s_and_b64 vcc, exec, s[14:15]
	s_cbranch_vccz .LBB0_290
	s_barrier

.LBB0_311:
	ds_read_b128 v[152:155], v144
	ds_read_b128 v[156:159], v144 offset:1024
	ds_read_b128 v[160:163], v144 offset:2048
	ds_read_b128 v[164:167], v144 offset:3072
	ds_read_b128 v[168:171], v145
	ds_read_b128 v[172:175], v145 offset:1024
	ds_read_b128 v[176:179], v145 offset:2048
	ds_read_b128 v[180:183], v145 offset:3072
	s_add_u32 s42, s40, 0xfff00080
	s_addc_u32 s43, s41, -1
	s_cmp_eq_u32 s70, 60
	s_cselect_b32 s47, s27, s43
	s_cselect_b32 s46, s66, s42
	s_cselect_b32 s43, s25, s69
	s_cselect_b32 s42, s67, s68
	v_lshl_add_u64 v[192:193], s[40:41], 0, v[134:135]
	s_add_i32 m0, s29, 0xc000
	ds_read_b128 v[184:187], v151
	ds_read_b128 v[188:191], v151 offset:1024
	ds_read_b128 v[196:199], v151 offset:2048
	ds_read_b128 v[200:203], v151 offset:3072
	ds_read_b128 v[204:207], v151 offset:4096
	ds_read_b128 v[208:211], v151 offset:5120
	ds_read_b128 v[212:215], v151 offset:6144
	ds_read_b128 v[216:219], v151 offset:7168
	global_load_lds_dwordx4 v[192:193], off
	v_lshl_add_u64 v[192:193], s[40:41], 0, v[136:137]
	s_add_i32 m0, s29, 0xe000
	s_nop 0
	global_load_lds_dwordx4 v[192:193], off
	s_waitcnt vmcnt(8)
	s_waitcnt lgkmcnt(0)
	s_barrier
	s_setprio 1
	v_mfma_f32_16x16x32_bf16 v[126:129], v[152:155], v[184:187], v[126:129]
	v_mfma_f32_16x16x32_bf16 v[122:125], v[160:163], v[184:187], v[122:125]
	v_mfma_f32_16x16x32_bf16 v[118:121], v[152:155], v[196:199], v[118:121]
	v_mfma_f32_16x16x32_bf16 v[110:113], v[160:163], v[196:199], v[110:113]
	v_mfma_f32_16x16x32_bf16 v[102:105], v[152:155], v[204:207], v[102:105]
	v_mfma_f32_16x16x32_bf16 v[94:97], v[160:163], v[204:207], v[94:97]
	v_mfma_f32_16x16x32_bf16 v[86:89], v[152:155], v[212:215], v[86:89]
	v_mfma_f32_16x16x32_bf16 v[78:81], v[160:163], v[212:215], v[78:81]
	v_mfma_f32_16x16x32_bf16 v[126:129], v[156:159], v[188:191], v[126:129]
	v_mfma_f32_16x16x32_bf16 v[122:125], v[164:167], v[188:191], v[122:125]
	v_mfma_f32_16x16x32_bf16 v[118:121], v[156:159], v[200:203], v[118:121]
	v_mfma_f32_16x16x32_bf16 v[110:113], v[164:167], v[200:203], v[110:113]
	v_mfma_f32_16x16x32_bf16 v[102:105], v[156:159], v[208:211], v[102:105]
	v_mfma_f32_16x16x32_bf16 v[94:97], v[164:167], v[208:211], v[94:97]
	v_mfma_f32_16x16x32_bf16 v[86:89], v[156:159], v[216:219], v[86:89]
	v_mfma_f32_16x16x32_bf16 v[78:81], v[164:167], v[216:219], v[78:81]
	v_mfma_f32_16x16x32_bf16 v[114:117], v[168:171], v[184:187], v[114:117]
	v_mfma_f32_16x16x32_bf16 v[106:109], v[176:179], v[184:187], v[106:109]
	v_mfma_f32_16x16x32_bf16 v[98:101], v[168:171], v[196:199], v[98:101]
	v_mfma_f32_16x16x32_bf16 v[90:93], v[176:179], v[196:199], v[90:93]
	v_mfma_f32_16x16x32_bf16 v[82:85], v[168:171], v[204:207], v[82:85]
	v_mfma_f32_16x16x32_bf16 v[74:77], v[176:179], v[204:207], v[74:77]
	v_mfma_f32_16x16x32_bf16 v[70:73], v[168:171], v[212:215], v[70:73]
	v_mfma_f32_16x16x32_bf16 v[66:69], v[176:179], v[212:215], v[66:69]
	v_mfma_f32_16x16x32_bf16 v[114:117], v[172:175], v[188:191], v[114:117]
	v_mfma_f32_16x16x32_bf16 v[106:109], v[180:183], v[188:191], v[106:109]
	v_mfma_f32_16x16x32_bf16 v[98:101], v[172:175], v[200:203], v[98:101]
	v_mfma_f32_16x16x32_bf16 v[90:93], v[180:183], v[200:203], v[90:93]
	v_mfma_f32_16x16x32_bf16 v[82:85], v[172:175], v[208:211], v[82:85]
	v_mfma_f32_16x16x32_bf16 v[74:77], v[180:183], v[208:211], v[74:77]
	v_mfma_f32_16x16x32_bf16 v[70:73], v[172:175], v[216:219], v[70:73]
	v_mfma_f32_16x16x32_bf16 v[66:69], v[180:183], v[216:219], v[66:69]
	s_setprio 0
	s_barrier
	s_add_i32 s71, s62, s54
	v_lshl_add_u64 v[192:193], s[42:43], 0, v[130:131]
	s_mov_b32 m0, s71
	ds_read_b128 v[184:187], v151 offset:16384
	ds_read_b128 v[188:191], v151 offset:17408
	ds_read_b128 v[196:199], v151 offset:18432
	ds_read_b128 v[200:203], v151 offset:19456
	ds_read_b128 v[204:207], v151 offset:20480
	ds_read_b128 v[208:211], v151 offset:21504
	ds_read_b128 v[212:215], v151 offset:22528
	ds_read_b128 v[216:219], v151 offset:23552
	global_load_lds_dwordx4 v[192:193], off
	s_add_i32 m0, s71, 0x2000
	s_add_u32 s72, s42, 0x100000
	v_lshl_add_u64 v[220:221], s[42:43], 0, v[132:133]
	s_addc_u32 s73, s43, 0
	s_add_i32 s71, s63, s54
	global_load_lds_dwordx4 v[220:221], off
	v_lshl_add_u64 v[222:223], s[72:73], 0, v[130:131]
	s_mov_b32 m0, s71
	v_lshl_add_u64 v[224:225], s[46:47], 0, v[132:133]
	global_load_lds_dwordx4 v[222:223], off
	v_lshl_add_u64 v[222:223], s[72:73], 0, v[132:133]
	s_add_i32 m0, s71, 0x2000
	s_nop 0
	global_load_lds_dwordx4 v[222:223], off
	v_lshl_add_u64 v[222:223], s[46:47], 0, v[130:131]
	s_mov_b32 m0, s29
	s_nop 0
	global_load_lds_dwordx4 v[222:223], off
	s_mov_b32 m0, s55
	s_nop 0
	global_load_lds_dwordx4 v[224:225], off
	s_waitcnt vmcnt(8)
	s_waitcnt lgkmcnt(0)
	s_barrier
	s_setprio 1
	v_mfma_f32_16x16x32_bf16 v[62:65], v[152:155], v[184:187], v[62:65]
	v_mfma_f32_16x16x32_bf16 v[58:61], v[160:163], v[184:187], v[58:61]
	v_mfma_f32_16x16x32_bf16 v[54:57], v[152:155], v[196:199], v[54:57]
	v_mfma_f32_16x16x32_bf16 v[46:49], v[160:163], v[196:199], v[46:49]
	v_mfma_f32_16x16x32_bf16 v[38:41], v[152:155], v[204:207], v[38:41]
	v_mfma_f32_16x16x32_bf16 v[30:33], v[160:163], v[204:207], v[30:33]
	v_mfma_f32_16x16x32_bf16 v[22:25], v[152:155], v[212:215], v[22:25]
	v_mfma_f32_16x16x32_bf16 v[14:17], v[160:163], v[212:215], v[14:17]
	v_mfma_f32_16x16x32_bf16 v[62:65], v[156:159], v[188:191], v[62:65]
	v_mfma_f32_16x16x32_bf16 v[58:61], v[164:167], v[188:191], v[58:61]
	v_mfma_f32_16x16x32_bf16 v[54:57], v[156:159], v[200:203], v[54:57]
	v_mfma_f32_16x16x32_bf16 v[46:49], v[164:167], v[200:203], v[46:49]
	v_mfma_f32_16x16x32_bf16 v[38:41], v[156:159], v[208:211], v[38:41]
	v_mfma_f32_16x16x32_bf16 v[30:33], v[164:167], v[208:211], v[30:33]
	v_mfma_f32_16x16x32_bf16 v[22:25], v[156:159], v[216:219], v[22:25]
	v_mfma_f32_16x16x32_bf16 v[14:17], v[164:167], v[216:219], v[14:17]
	v_mfma_f32_16x16x32_bf16 v[50:53], v[168:171], v[184:187], v[50:53]
	v_mfma_f32_16x16x32_bf16 v[42:45], v[176:179], v[184:187], v[42:45]
	v_mfma_f32_16x16x32_bf16 v[34:37], v[168:171], v[196:199], v[34:37]
	v_mfma_f32_16x16x32_bf16 v[26:29], v[176:179], v[196:199], v[26:29]
	v_mfma_f32_16x16x32_bf16 v[18:21], v[168:171], v[204:207], v[18:21]
	v_mfma_f32_16x16x32_bf16 v[10:13], v[176:179], v[204:207], v[10:13]
	v_mfma_f32_16x16x32_bf16 v[6:9], v[168:171], v[212:215], v[6:9]
	v_mfma_f32_16x16x32_bf16 v[2:5], v[176:179], v[212:215], v[2:5]
	v_mfma_f32_16x16x32_bf16 v[50:53], v[172:175], v[188:191], v[50:53]
	v_mfma_f32_16x16x32_bf16 v[42:45], v[180:183], v[188:191], v[42:45]
	v_mfma_f32_16x16x32_bf16 v[34:37], v[172:175], v[200:203], v[34:37]
	v_mfma_f32_16x16x32_bf16 v[26:29], v[180:183], v[200:203], v[26:29]
	v_mfma_f32_16x16x32_bf16 v[18:21], v[172:175], v[208:211], v[18:21]
	v_mfma_f32_16x16x32_bf16 v[10:13], v[180:183], v[208:211], v[10:13]
	v_mfma_f32_16x16x32_bf16 v[6:9], v[172:175], v[216:219], v[6:9]
	v_mfma_f32_16x16x32_bf16 v[2:5], v[180:183], v[216:219], v[2:5]
	s_setprio 0
	s_barrier
	s_add_i32 s71, 0, 0x18000
	s_add_i32 s72, 0, 0x1c000
	v_add_u32_e32 v164, s71, v142
	v_add_u32_e32 v180, s72, v142
	ds_read_b128 v[152:155], v164
	ds_read_b128 v[156:159], v164 offset:1024
	ds_read_b128 v[160:163], v164 offset:2048
	ds_read_b128 v[164:167], v164 offset:3072
	ds_read_b128 v[168:171], v180
	ds_read_b128 v[172:175], v180 offset:1024
	ds_read_b128 v[176:179], v180 offset:2048
	ds_read_b128 v[180:183], v180 offset:3072
	s_add_u32 s46, s46, 0x100000
	s_addc_u32 s47, s47, 0
	s_mov_b32 m0, s56
	v_lshl_add_u64 v[226:227], s[46:47], 0, v[130:131]
	ds_read_b128 v[184:187], v151 offset:32768
	ds_read_b128 v[188:191], v151 offset:33792
	ds_read_b128 v[196:199], v151 offset:34816
	ds_read_b128 v[200:203], v151 offset:35840
	ds_read_b128 v[204:207], v151 offset:36864
	ds_read_b128 v[208:211], v151 offset:37888
	ds_read_b128 v[212:215], v151 offset:38912
	ds_read_b128 v[216:219], v151 offset:39936
	global_load_lds_dwordx4 v[226:227], off
	v_lshl_add_u64 v[226:227], s[46:47], 0, v[132:133]
	s_mov_b32 m0, s57
	s_nop 0
	global_load_lds_dwordx4 v[226:227], off
	s_waitcnt vmcnt(8)
	s_waitcnt lgkmcnt(0)
	s_barrier
	s_setprio 1
	v_mfma_f32_16x16x32_bf16 v[126:129], v[152:155], v[184:187], v[126:129]
	v_mfma_f32_16x16x32_bf16 v[122:125], v[160:163], v[184:187], v[122:125]
	v_mfma_f32_16x16x32_bf16 v[118:121], v[152:155], v[196:199], v[118:121]
	v_mfma_f32_16x16x32_bf16 v[110:113], v[160:163], v[196:199], v[110:113]
	v_mfma_f32_16x16x32_bf16 v[102:105], v[152:155], v[204:207], v[102:105]
	v_mfma_f32_16x16x32_bf16 v[94:97], v[160:163], v[204:207], v[94:97]
	v_mfma_f32_16x16x32_bf16 v[86:89], v[152:155], v[212:215], v[86:89]
	v_mfma_f32_16x16x32_bf16 v[78:81], v[160:163], v[212:215], v[78:81]
	v_mfma_f32_16x16x32_bf16 v[126:129], v[156:159], v[188:191], v[126:129]
	v_mfma_f32_16x16x32_bf16 v[122:125], v[164:167], v[188:191], v[122:125]
	v_mfma_f32_16x16x32_bf16 v[118:121], v[156:159], v[200:203], v[118:121]
	v_mfma_f32_16x16x32_bf16 v[110:113], v[164:167], v[200:203], v[110:113]
	v_mfma_f32_16x16x32_bf16 v[102:105], v[156:159], v[208:211], v[102:105]
	v_mfma_f32_16x16x32_bf16 v[94:97], v[164:167], v[208:211], v[94:97]
	v_mfma_f32_16x16x32_bf16 v[86:89], v[156:159], v[216:219], v[86:89]
	v_mfma_f32_16x16x32_bf16 v[78:81], v[164:167], v[216:219], v[78:81]
	v_mfma_f32_16x16x32_bf16 v[114:117], v[168:171], v[184:187], v[114:117]
	v_mfma_f32_16x16x32_bf16 v[106:109], v[176:179], v[184:187], v[106:109]
	v_mfma_f32_16x16x32_bf16 v[98:101], v[168:171], v[196:199], v[98:101]
	v_mfma_f32_16x16x32_bf16 v[90:93], v[176:179], v[196:199], v[90:93]
	v_mfma_f32_16x16x32_bf16 v[82:85], v[168:171], v[204:207], v[82:85]
	v_mfma_f32_16x16x32_bf16 v[74:77], v[176:179], v[204:207], v[74:77]
	v_mfma_f32_16x16x32_bf16 v[70:73], v[168:171], v[212:215], v[70:73]
	v_mfma_f32_16x16x32_bf16 v[66:69], v[176:179], v[212:215], v[66:69]
	v_mfma_f32_16x16x32_bf16 v[114:117], v[172:175], v[188:191], v[114:117]
	v_mfma_f32_16x16x32_bf16 v[106:109], v[180:183], v[188:191], v[106:109]
	v_mfma_f32_16x16x32_bf16 v[98:101], v[172:175], v[200:203], v[98:101]
	v_mfma_f32_16x16x32_bf16 v[90:93], v[180:183], v[200:203], v[90:93]
	v_mfma_f32_16x16x32_bf16 v[82:85], v[172:175], v[208:211], v[82:85]
	v_mfma_f32_16x16x32_bf16 v[74:77], v[180:183], v[208:211], v[74:77]
	v_mfma_f32_16x16x32_bf16 v[70:73], v[172:175], v[216:219], v[70:73]
	v_mfma_f32_16x16x32_bf16 v[66:69], v[180:183], v[216:219], v[66:69]
	s_setprio 0
	s_barrier
	s_add_i32 s46, s71, s54
	v_lshl_add_u64 v[192:193], v[192:193], 0, s[10:11]
	s_mov_b32 m0, s46
	ds_read_b128 v[184:187], v151 offset:49152
	ds_read_b128 v[188:191], v151 offset:50176
	ds_read_b128 v[196:199], v151 offset:51200
	ds_read_b128 v[200:203], v151 offset:52224
	ds_read_b128 v[204:207], v151 offset:53248
	ds_read_b128 v[208:211], v151 offset:54272
	ds_read_b128 v[212:215], v151 offset:55296
	ds_read_b128 v[216:219], v151 offset:56320
	global_load_lds_dwordx4 v[192:193], off
	s_add_i32 m0, s46, 0x2000
	s_add_u32 s42, s42, 0x100080
	v_lshl_add_u64 v[192:193], v[220:221], 0, s[10:11]
	s_addc_u32 s43, s43, 0
	s_add_i32 s46, s72, s54
	global_load_lds_dwordx4 v[192:193], off
	v_lshl_add_u64 v[192:193], s[42:43], 0, v[130:131]
	s_mov_b32 m0, s46
	s_nop 0
	global_load_lds_dwordx4 v[192:193], off
	v_lshl_add_u64 v[192:193], s[42:43], 0, v[132:133]
	s_add_i32 m0, s46, 0x2000
	s_nop 0
	global_load_lds_dwordx4 v[192:193], off
	v_lshl_add_u64 v[192:193], v[222:223], 0, s[10:11]
	s_mov_b32 m0, s59
	s_nop 0
	global_load_lds_dwordx4 v[192:193], off
	v_lshl_add_u64 v[192:193], v[224:225], 0, s[10:11]
	s_mov_b32 m0, s60
	s_nop 0
	global_load_lds_dwordx4 v[192:193], off
	s_nop 0
	s_waitcnt vmcnt(8)
	s_waitcnt lgkmcnt(0)
	s_barrier
	s_setprio 1
	v_mfma_f32_16x16x32_bf16 v[62:65], v[152:155], v[184:187], v[62:65]
	v_mfma_f32_16x16x32_bf16 v[58:61], v[160:163], v[184:187], v[58:61]
	v_mfma_f32_16x16x32_bf16 v[54:57], v[152:155], v[196:199], v[54:57]
	v_mfma_f32_16x16x32_bf16 v[46:49], v[160:163], v[196:199], v[46:49]
	v_mfma_f32_16x16x32_bf16 v[38:41], v[152:155], v[204:207], v[38:41]
	v_mfma_f32_16x16x32_bf16 v[30:33], v[160:163], v[204:207], v[30:33]
	v_mfma_f32_16x16x32_bf16 v[22:25], v[152:155], v[212:215], v[22:25]
	v_mfma_f32_16x16x32_bf16 v[14:17], v[160:163], v[212:215], v[14:17]
	v_mfma_f32_16x16x32_bf16 v[62:65], v[156:159], v[188:191], v[62:65]
	v_mfma_f32_16x16x32_bf16 v[58:61], v[164:167], v[188:191], v[58:61]
	v_mfma_f32_16x16x32_bf16 v[54:57], v[156:159], v[200:203], v[54:57]
	v_mfma_f32_16x16x32_bf16 v[46:49], v[164:167], v[200:203], v[46:49]
	v_mfma_f32_16x16x32_bf16 v[38:41], v[156:159], v[208:211], v[38:41]
	v_mfma_f32_16x16x32_bf16 v[30:33], v[164:167], v[208:211], v[30:33]
	v_mfma_f32_16x16x32_bf16 v[22:25], v[156:159], v[216:219], v[22:25]
	v_mfma_f32_16x16x32_bf16 v[14:17], v[164:167], v[216:219], v[14:17]
	v_mfma_f32_16x16x32_bf16 v[50:53], v[168:171], v[184:187], v[50:53]
	v_mfma_f32_16x16x32_bf16 v[42:45], v[176:179], v[184:187], v[42:45]
	v_mfma_f32_16x16x32_bf16 v[34:37], v[168:171], v[196:199], v[34:37]
	v_mfma_f32_16x16x32_bf16 v[26:29], v[176:179], v[196:199], v[26:29]
	v_mfma_f32_16x16x32_bf16 v[18:21], v[168:171], v[204:207], v[18:21]
	v_mfma_f32_16x16x32_bf16 v[10:13], v[176:179], v[204:207], v[10:13]
	v_mfma_f32_16x16x32_bf16 v[6:9], v[168:171], v[212:215], v[6:9]
	v_mfma_f32_16x16x32_bf16 v[2:5], v[176:179], v[212:215], v[2:5]
	v_mfma_f32_16x16x32_bf16 v[50:53], v[172:175], v[188:191], v[50:53]
	v_mfma_f32_16x16x32_bf16 v[42:45], v[180:183], v[188:191], v[42:45]
	v_mfma_f32_16x16x32_bf16 v[34:37], v[172:175], v[200:203], v[34:37]
	v_mfma_f32_16x16x32_bf16 v[26:29], v[180:183], v[200:203], v[26:29]
	v_mfma_f32_16x16x32_bf16 v[18:21], v[172:175], v[208:211], v[18:21]
	v_mfma_f32_16x16x32_bf16 v[10:13], v[180:183], v[208:211], v[10:13]
	v_mfma_f32_16x16x32_bf16 v[6:9], v[172:175], v[216:219], v[6:9]
	v_mfma_f32_16x16x32_bf16 v[2:5], v[180:183], v[216:219], v[2:5]
	s_setprio 0
	s_barrier
	s_add_i32 s70, s70, 2
	s_add_u32 s40, s40, 0x100
	s_addc_u32 s41, s41, 0
	s_add_u32 s68, s68, 0x100
	s_addc_u32 s69, s69, 0
	s_cmp_gt_u32 s70, 61
	s_cbranch_scc0 .LBB0_311
	s_and_b64 vcc, exec, s[12:13]
	s_cbranch_vccz .LBB0_314
	s_barrier

.LBB0_335:
	ds_read_b128 v[144:147], v140
	ds_read_b128 v[148:151], v140 offset:1024
	ds_read_b128 v[152:155], v140 offset:2048
	ds_read_b128 v[156:159], v140 offset:3072
	ds_read_b128 v[160:163], v142
	ds_read_b128 v[164:167], v142 offset:1024
	ds_read_b128 v[168:171], v142 offset:2048
	ds_read_b128 v[172:175], v142 offset:3072
	s_add_u32 s42, s40, 0xfff00080
	s_addc_u32 s43, s41, -1
	s_cmp_eq_u32 s67, 60
	s_cselect_b32 s47, s27, s43
	s_cselect_b32 s46, s63, s42
	s_cselect_b32 s43, s25, s66
	s_cselect_b32 s42, s64, s65
	v_lshl_add_u64 v[192:193], s[40:41], 0, v[134:135]
	s_add_i32 m0, s29, 0xc000
	ds_read_b128 v[176:179], v143
	ds_read_b128 v[180:183], v143 offset:1024
	ds_read_b128 v[184:187], v143 offset:2048
	ds_read_b128 v[188:191], v143 offset:3072
	ds_read_b128 v[196:199], v143 offset:4096
	ds_read_b128 v[200:203], v143 offset:5120
	ds_read_b128 v[204:207], v143 offset:6144
	ds_read_b128 v[208:211], v143 offset:7168
	global_load_lds_dwordx4 v[192:193], off
	v_lshl_add_u64 v[192:193], s[40:41], 0, v[136:137]
	s_add_i32 m0, s29, 0xe000
	s_nop 0
	global_load_lds_dwordx4 v[192:193], off
	s_waitcnt vmcnt(8)
	s_waitcnt lgkmcnt(0)
	s_barrier
	s_setprio 1
	v_mfma_f32_16x16x32_bf16 v[126:129], v[144:147], v[176:179], v[126:129]
	v_mfma_f32_16x16x32_bf16 v[122:125], v[152:155], v[176:179], v[122:125]
	v_mfma_f32_16x16x32_bf16 v[118:121], v[144:147], v[184:187], v[118:121]
	v_mfma_f32_16x16x32_bf16 v[110:113], v[152:155], v[184:187], v[110:113]
	v_mfma_f32_16x16x32_bf16 v[102:105], v[144:147], v[196:199], v[102:105]
	v_mfma_f32_16x16x32_bf16 v[94:97], v[152:155], v[196:199], v[94:97]
	v_mfma_f32_16x16x32_bf16 v[86:89], v[144:147], v[204:207], v[86:89]
	v_mfma_f32_16x16x32_bf16 v[78:81], v[152:155], v[204:207], v[78:81]
	v_mfma_f32_16x16x32_bf16 v[126:129], v[148:151], v[180:183], v[126:129]
	v_mfma_f32_16x16x32_bf16 v[122:125], v[156:159], v[180:183], v[122:125]
	v_mfma_f32_16x16x32_bf16 v[118:121], v[148:151], v[188:191], v[118:121]
	v_mfma_f32_16x16x32_bf16 v[110:113], v[156:159], v[188:191], v[110:113]
	v_mfma_f32_16x16x32_bf16 v[102:105], v[148:151], v[200:203], v[102:105]
	v_mfma_f32_16x16x32_bf16 v[94:97], v[156:159], v[200:203], v[94:97]
	v_mfma_f32_16x16x32_bf16 v[86:89], v[148:151], v[208:211], v[86:89]
	v_mfma_f32_16x16x32_bf16 v[78:81], v[156:159], v[208:211], v[78:81]
	v_mfma_f32_16x16x32_bf16 v[114:117], v[160:163], v[176:179], v[114:117]
	v_mfma_f32_16x16x32_bf16 v[106:109], v[168:171], v[176:179], v[106:109]
	v_mfma_f32_16x16x32_bf16 v[98:101], v[160:163], v[184:187], v[98:101]
	v_mfma_f32_16x16x32_bf16 v[90:93], v[168:171], v[184:187], v[90:93]
	v_mfma_f32_16x16x32_bf16 v[82:85], v[160:163], v[196:199], v[82:85]
	v_mfma_f32_16x16x32_bf16 v[74:77], v[168:171], v[196:199], v[74:77]
	v_mfma_f32_16x16x32_bf16 v[70:73], v[160:163], v[204:207], v[70:73]
	v_mfma_f32_16x16x32_bf16 v[66:69], v[168:171], v[204:207], v[66:69]
	v_mfma_f32_16x16x32_bf16 v[114:117], v[164:167], v[180:183], v[114:117]
	v_mfma_f32_16x16x32_bf16 v[106:109], v[172:175], v[180:183], v[106:109]
	v_mfma_f32_16x16x32_bf16 v[98:101], v[164:167], v[188:191], v[98:101]
	v_mfma_f32_16x16x32_bf16 v[90:93], v[172:175], v[188:191], v[90:93]
	v_mfma_f32_16x16x32_bf16 v[82:85], v[164:167], v[200:203], v[82:85]
	v_mfma_f32_16x16x32_bf16 v[74:77], v[172:175], v[200:203], v[74:77]
	v_mfma_f32_16x16x32_bf16 v[70:73], v[164:167], v[208:211], v[70:73]
	v_mfma_f32_16x16x32_bf16 v[66:69], v[172:175], v[208:211], v[66:69]
	s_setprio 0
	s_barrier
	s_add_i32 s68, s59, s51
	v_lshl_add_u64 v[192:193], s[42:43], 0, v[130:131]
	s_mov_b32 m0, s68
	ds_read_b128 v[176:179], v143 offset:16384
	ds_read_b128 v[180:183], v143 offset:17408
	ds_read_b128 v[184:187], v143 offset:18432
	ds_read_b128 v[188:191], v143 offset:19456
	ds_read_b128 v[196:199], v143 offset:20480
	ds_read_b128 v[200:203], v143 offset:21504
	ds_read_b128 v[204:207], v143 offset:22528
	ds_read_b128 v[208:211], v143 offset:23552
	global_load_lds_dwordx4 v[192:193], off
	s_add_i32 m0, s68, 0x2000
	s_add_u32 s68, s42, 0x100000
	v_lshl_add_u64 v[212:213], s[42:43], 0, v[132:133]
	s_addc_u32 s69, s43, 0
	s_add_i32 s70, s60, s51
	global_load_lds_dwordx4 v[212:213], off
	v_lshl_add_u64 v[214:215], s[68:69], 0, v[130:131]
	s_mov_b32 m0, s70
	v_lshl_add_u64 v[216:217], s[46:47], 0, v[132:133]
	global_load_lds_dwordx4 v[214:215], off
	v_lshl_add_u64 v[214:215], s[68:69], 0, v[132:133]
	s_add_i32 m0, s70, 0x2000
	s_nop 0
	global_load_lds_dwordx4 v[214:215], off
	v_lshl_add_u64 v[214:215], s[46:47], 0, v[130:131]
	s_mov_b32 m0, s29
	s_nop 0
	global_load_lds_dwordx4 v[214:215], off
	s_mov_b32 m0, s52
	s_nop 0
	global_load_lds_dwordx4 v[216:217], off
	s_waitcnt vmcnt(8)
	s_waitcnt lgkmcnt(0)
	s_barrier
	s_setprio 1
	v_mfma_f32_16x16x32_bf16 v[62:65], v[144:147], v[176:179], v[62:65]
	v_mfma_f32_16x16x32_bf16 v[58:61], v[152:155], v[176:179], v[58:61]
	v_mfma_f32_16x16x32_bf16 v[54:57], v[144:147], v[184:187], v[54:57]
	v_mfma_f32_16x16x32_bf16 v[46:49], v[152:155], v[184:187], v[46:49]
	v_mfma_f32_16x16x32_bf16 v[38:41], v[144:147], v[196:199], v[38:41]
	v_mfma_f32_16x16x32_bf16 v[30:33], v[152:155], v[196:199], v[30:33]
	v_mfma_f32_16x16x32_bf16 v[22:25], v[144:147], v[204:207], v[22:25]
	v_mfma_f32_16x16x32_bf16 v[14:17], v[152:155], v[204:207], v[14:17]
	v_mfma_f32_16x16x32_bf16 v[62:65], v[148:151], v[180:183], v[62:65]
	v_mfma_f32_16x16x32_bf16 v[58:61], v[156:159], v[180:183], v[58:61]
	v_mfma_f32_16x16x32_bf16 v[54:57], v[148:151], v[188:191], v[54:57]
	v_mfma_f32_16x16x32_bf16 v[46:49], v[156:159], v[188:191], v[46:49]
	v_mfma_f32_16x16x32_bf16 v[38:41], v[148:151], v[200:203], v[38:41]
	v_mfma_f32_16x16x32_bf16 v[30:33], v[156:159], v[200:203], v[30:33]
	v_mfma_f32_16x16x32_bf16 v[22:25], v[148:151], v[208:211], v[22:25]
	v_mfma_f32_16x16x32_bf16 v[14:17], v[156:159], v[208:211], v[14:17]
	v_mfma_f32_16x16x32_bf16 v[50:53], v[160:163], v[176:179], v[50:53]
	v_mfma_f32_16x16x32_bf16 v[42:45], v[168:171], v[176:179], v[42:45]
	v_mfma_f32_16x16x32_bf16 v[34:37], v[160:163], v[184:187], v[34:37]
	v_mfma_f32_16x16x32_bf16 v[26:29], v[168:171], v[184:187], v[26:29]
	v_mfma_f32_16x16x32_bf16 v[18:21], v[160:163], v[196:199], v[18:21]
	v_mfma_f32_16x16x32_bf16 v[10:13], v[168:171], v[196:199], v[10:13]
	v_mfma_f32_16x16x32_bf16 v[6:9], v[160:163], v[204:207], v[6:9]
	v_mfma_f32_16x16x32_bf16 v[2:5], v[168:171], v[204:207], v[2:5]
	v_mfma_f32_16x16x32_bf16 v[50:53], v[164:167], v[180:183], v[50:53]
	v_mfma_f32_16x16x32_bf16 v[42:45], v[172:175], v[180:183], v[42:45]
	v_mfma_f32_16x16x32_bf16 v[34:37], v[164:167], v[188:191], v[34:37]
	v_mfma_f32_16x16x32_bf16 v[26:29], v[172:175], v[188:191], v[26:29]
	v_mfma_f32_16x16x32_bf16 v[18:21], v[164:167], v[200:203], v[18:21]
	v_mfma_f32_16x16x32_bf16 v[10:13], v[172:175], v[200:203], v[10:13]
	v_mfma_f32_16x16x32_bf16 v[6:9], v[164:167], v[208:211], v[6:9]
	v_mfma_f32_16x16x32_bf16 v[2:5], v[172:175], v[208:211], v[2:5]
	s_setprio 0
	s_barrier
	s_add_i32 s68, 0, 0x18000
	s_add_i32 s69, 0, 0x1c000
	v_add_u32_e32 v156, s68, v139
	v_add_u32_e32 v172, s69, v139
	ds_read_b128 v[144:147], v156
	ds_read_b128 v[148:151], v156 offset:1024
	ds_read_b128 v[152:155], v156 offset:2048
	ds_read_b128 v[156:159], v156 offset:3072
	ds_read_b128 v[160:163], v172
	ds_read_b128 v[164:167], v172 offset:1024
	ds_read_b128 v[168:171], v172 offset:2048
	ds_read_b128 v[172:175], v172 offset:3072
	s_add_u32 s46, s46, 0x100000
	s_addc_u32 s47, s47, 0
	s_mov_b32 m0, s53
	v_lshl_add_u64 v[218:219], s[46:47], 0, v[130:131]
	ds_read_b128 v[176:179], v143 offset:32768
	ds_read_b128 v[180:183], v143 offset:33792
	ds_read_b128 v[184:187], v143 offset:34816
	ds_read_b128 v[188:191], v143 offset:35840
	ds_read_b128 v[196:199], v143 offset:36864
	ds_read_b128 v[200:203], v143 offset:37888
	ds_read_b128 v[204:207], v143 offset:38912
	ds_read_b128 v[208:211], v143 offset:39936
	global_load_lds_dwordx4 v[218:219], off
	v_lshl_add_u64 v[218:219], s[46:47], 0, v[132:133]
	s_mov_b32 m0, s54
	s_nop 0
	global_load_lds_dwordx4 v[218:219], off
	s_waitcnt vmcnt(8)
	s_waitcnt lgkmcnt(0)
	s_barrier
	s_setprio 1
	v_mfma_f32_16x16x32_bf16 v[126:129], v[144:147], v[176:179], v[126:129]
	v_mfma_f32_16x16x32_bf16 v[122:125], v[152:155], v[176:179], v[122:125]
	v_mfma_f32_16x16x32_bf16 v[118:121], v[144:147], v[184:187], v[118:121]
	v_mfma_f32_16x16x32_bf16 v[110:113], v[152:155], v[184:187], v[110:113]
	v_mfma_f32_16x16x32_bf16 v[102:105], v[144:147], v[196:199], v[102:105]
	v_mfma_f32_16x16x32_bf16 v[94:97], v[152:155], v[196:199], v[94:97]
	v_mfma_f32_16x16x32_bf16 v[86:89], v[144:147], v[204:207], v[86:89]
	v_mfma_f32_16x16x32_bf16 v[78:81], v[152:155], v[204:207], v[78:81]
	v_mfma_f32_16x16x32_bf16 v[126:129], v[148:151], v[180:183], v[126:129]
	v_mfma_f32_16x16x32_bf16 v[122:125], v[156:159], v[180:183], v[122:125]
	v_mfma_f32_16x16x32_bf16 v[118:121], v[148:151], v[188:191], v[118:121]
	v_mfma_f32_16x16x32_bf16 v[110:113], v[156:159], v[188:191], v[110:113]
	v_mfma_f32_16x16x32_bf16 v[102:105], v[148:151], v[200:203], v[102:105]
	v_mfma_f32_16x16x32_bf16 v[94:97], v[156:159], v[200:203], v[94:97]
	v_mfma_f32_16x16x32_bf16 v[86:89], v[148:151], v[208:211], v[86:89]
	v_mfma_f32_16x16x32_bf16 v[78:81], v[156:159], v[208:211], v[78:81]
	v_mfma_f32_16x16x32_bf16 v[114:117], v[160:163], v[176:179], v[114:117]
	v_mfma_f32_16x16x32_bf16 v[106:109], v[168:171], v[176:179], v[106:109]
	v_mfma_f32_16x16x32_bf16 v[98:101], v[160:163], v[184:187], v[98:101]
	v_mfma_f32_16x16x32_bf16 v[90:93], v[168:171], v[184:187], v[90:93]
	v_mfma_f32_16x16x32_bf16 v[82:85], v[160:163], v[196:199], v[82:85]
	v_mfma_f32_16x16x32_bf16 v[74:77], v[168:171], v[196:199], v[74:77]
	v_mfma_f32_16x16x32_bf16 v[70:73], v[160:163], v[204:207], v[70:73]
	v_mfma_f32_16x16x32_bf16 v[66:69], v[168:171], v[204:207], v[66:69]
	v_mfma_f32_16x16x32_bf16 v[114:117], v[164:167], v[180:183], v[114:117]
	v_mfma_f32_16x16x32_bf16 v[106:109], v[172:175], v[180:183], v[106:109]
	v_mfma_f32_16x16x32_bf16 v[98:101], v[164:167], v[188:191], v[98:101]
	v_mfma_f32_16x16x32_bf16 v[90:93], v[172:175], v[188:191], v[90:93]
	v_mfma_f32_16x16x32_bf16 v[82:85], v[164:167], v[200:203], v[82:85]
	v_mfma_f32_16x16x32_bf16 v[74:77], v[172:175], v[200:203], v[74:77]
	v_mfma_f32_16x16x32_bf16 v[70:73], v[164:167], v[208:211], v[70:73]
	v_mfma_f32_16x16x32_bf16 v[66:69], v[172:175], v[208:211], v[66:69]
	s_setprio 0
	s_barrier
	s_add_i32 s46, s68, s51
	v_lshl_add_u64 v[192:193], v[192:193], 0, s[10:11]
	s_mov_b32 m0, s46
	ds_read_b128 v[176:179], v143 offset:49152
	ds_read_b128 v[180:183], v143 offset:50176
	ds_read_b128 v[184:187], v143 offset:51200
	ds_read_b128 v[188:191], v143 offset:52224
	ds_read_b128 v[196:199], v143 offset:53248
	ds_read_b128 v[200:203], v143 offset:54272
	ds_read_b128 v[204:207], v143 offset:55296
	ds_read_b128 v[208:211], v143 offset:56320
	global_load_lds_dwordx4 v[192:193], off
	s_add_i32 m0, s46, 0x2000
	s_add_u32 s42, s42, 0x100080
	v_lshl_add_u64 v[192:193], v[212:213], 0, s[10:11]
	s_addc_u32 s43, s43, 0
	s_add_i32 s46, s69, s51
	global_load_lds_dwordx4 v[192:193], off
	v_lshl_add_u64 v[192:193], s[42:43], 0, v[130:131]
	s_mov_b32 m0, s46
	s_nop 0
	global_load_lds_dwordx4 v[192:193], off
	v_lshl_add_u64 v[192:193], s[42:43], 0, v[132:133]
	s_add_i32 m0, s46, 0x2000
	s_nop 0
	global_load_lds_dwordx4 v[192:193], off
	v_lshl_add_u64 v[192:193], v[214:215], 0, s[10:11]
	s_mov_b32 m0, s56
	s_nop 0
	global_load_lds_dwordx4 v[192:193], off
	v_lshl_add_u64 v[192:193], v[216:217], 0, s[10:11]
	s_mov_b32 m0, s57
	s_nop 0
	global_load_lds_dwordx4 v[192:193], off
	s_nop 0
	s_waitcnt vmcnt(8)
	s_waitcnt lgkmcnt(0)
	s_barrier
	s_setprio 1
	v_mfma_f32_16x16x32_bf16 v[62:65], v[144:147], v[176:179], v[62:65]
	v_mfma_f32_16x16x32_bf16 v[58:61], v[152:155], v[176:179], v[58:61]
	v_mfma_f32_16x16x32_bf16 v[54:57], v[144:147], v[184:187], v[54:57]
	v_mfma_f32_16x16x32_bf16 v[46:49], v[152:155], v[184:187], v[46:49]
	v_mfma_f32_16x16x32_bf16 v[38:41], v[144:147], v[196:199], v[38:41]
	v_mfma_f32_16x16x32_bf16 v[30:33], v[152:155], v[196:199], v[30:33]
	v_mfma_f32_16x16x32_bf16 v[22:25], v[144:147], v[204:207], v[22:25]
	v_mfma_f32_16x16x32_bf16 v[14:17], v[152:155], v[204:207], v[14:17]
	v_mfma_f32_16x16x32_bf16 v[62:65], v[148:151], v[180:183], v[62:65]
	v_mfma_f32_16x16x32_bf16 v[58:61], v[156:159], v[180:183], v[58:61]
	v_mfma_f32_16x16x32_bf16 v[54:57], v[148:151], v[188:191], v[54:57]
	v_mfma_f32_16x16x32_bf16 v[46:49], v[156:159], v[188:191], v[46:49]
	v_mfma_f32_16x16x32_bf16 v[38:41], v[148:151], v[200:203], v[38:41]
	v_mfma_f32_16x16x32_bf16 v[30:33], v[156:159], v[200:203], v[30:33]
	v_mfma_f32_16x16x32_bf16 v[22:25], v[148:151], v[208:211], v[22:25]
	v_mfma_f32_16x16x32_bf16 v[14:17], v[156:159], v[208:211], v[14:17]
	v_mfma_f32_16x16x32_bf16 v[50:53], v[160:163], v[176:179], v[50:53]
	v_mfma_f32_16x16x32_bf16 v[42:45], v[168:171], v[176:179], v[42:45]
	v_mfma_f32_16x16x32_bf16 v[34:37], v[160:163], v[184:187], v[34:37]
	v_mfma_f32_16x16x32_bf16 v[26:29], v[168:171], v[184:187], v[26:29]
	v_mfma_f32_16x16x32_bf16 v[18:21], v[160:163], v[196:199], v[18:21]
	v_mfma_f32_16x16x32_bf16 v[10:13], v[168:171], v[196:199], v[10:13]
	v_mfma_f32_16x16x32_bf16 v[6:9], v[160:163], v[204:207], v[6:9]
	v_mfma_f32_16x16x32_bf16 v[2:5], v[168:171], v[204:207], v[2:5]
	v_mfma_f32_16x16x32_bf16 v[50:53], v[164:167], v[180:183], v[50:53]
	v_mfma_f32_16x16x32_bf16 v[42:45], v[172:175], v[180:183], v[42:45]
	v_mfma_f32_16x16x32_bf16 v[34:37], v[164:167], v[188:191], v[34:37]
	v_mfma_f32_16x16x32_bf16 v[26:29], v[172:175], v[188:191], v[26:29]
	v_mfma_f32_16x16x32_bf16 v[18:21], v[164:167], v[200:203], v[18:21]
	v_mfma_f32_16x16x32_bf16 v[10:13], v[172:175], v[200:203], v[10:13]
	v_mfma_f32_16x16x32_bf16 v[6:9], v[164:167], v[208:211], v[6:9]
	v_mfma_f32_16x16x32_bf16 v[2:5], v[172:175], v[208:211], v[2:5]
	s_setprio 0
	s_barrier
	s_add_i32 s67, s67, 2
	s_add_u32 s40, s40, 0x100
	s_addc_u32 s41, s41, 0
	s_add_u32 s65, s65, 0x100
	s_addc_u32 s66, s66, 0
	s_cmp_gt_u32 s67, 61
	s_cbranch_scc0 .LBB0_335
	s_and_b64 vcc, exec, s[12:13]
	s_cbranch_vccz .LBB0_338
	s_barrier

.LBB0_657:
	ds_read_b128 v[158:161], v155
	ds_read_b128 v[162:165], v155 offset:1024
	ds_read_b128 v[166:169], v155 offset:2048
	ds_read_b128 v[170:173], v155 offset:3072
	ds_read_b128 v[174:177], v156
	ds_read_b128 v[178:181], v156 offset:1024
	ds_read_b128 v[182:185], v156 offset:2048
	ds_read_b128 v[186:189], v156 offset:3072
	s_add_u32 s28, s26, 0xfff00080
	s_addc_u32 s29, s27, -1
	s_cmp_eq_u32 s58, 60
	s_cselect_b32 s31, s21, s29
	s_cselect_b32 s30, s54, s28
	s_cselect_b32 s29, s19, s57
	s_cselect_b32 s28, s55, s56
	v_lshl_add_u64 v[224:225], s[26:27], 0, v[138:139]
	s_add_i32 m0, s17, 0xc000
	ds_read_b128 v[190:193], v157
	ds_read_b128 v[196:199], v157 offset:1024
	ds_read_b128 v[200:203], v157 offset:2048
	ds_read_b128 v[204:207], v157 offset:3072
	ds_read_b128 v[208:211], v157 offset:4096
	ds_read_b128 v[212:215], v157 offset:5120
	ds_read_b128 v[216:219], v157 offset:6144
	ds_read_b128 v[220:223], v157 offset:7168
	global_load_lds_dwordx4 v[224:225], off
	v_lshl_add_u64 v[224:225], s[26:27], 0, v[140:141]
	s_add_i32 m0, s17, 0xe000
	s_nop 0
	global_load_lds_dwordx4 v[224:225], off
	s_nop 0
	s_waitcnt vmcnt(8)
	s_waitcnt lgkmcnt(0)
	s_barrier
	s_setprio 1
	v_mfma_f32_16x16x32_bf16 v[126:129], v[158:161], v[190:193], v[126:129]
	v_mfma_f32_16x16x32_bf16 v[122:125], v[166:169], v[190:193], v[122:125]
	v_mfma_f32_16x16x32_bf16 v[118:121], v[158:161], v[200:203], v[118:121]
	v_mfma_f32_16x16x32_bf16 v[114:117], v[166:169], v[200:203], v[114:117]
	v_mfma_f32_16x16x32_bf16 v[102:105], v[158:161], v[208:211], v[102:105]
	v_mfma_f32_16x16x32_bf16 v[98:101], v[166:169], v[208:211], v[98:101]
	v_mfma_f32_16x16x32_bf16 v[86:89], v[158:161], v[216:219], v[86:89]
	v_mfma_f32_16x16x32_bf16 v[82:85], v[166:169], v[216:219], v[82:85]
	v_mfma_f32_16x16x32_bf16 v[126:129], v[162:165], v[196:199], v[126:129]
	v_mfma_f32_16x16x32_bf16 v[122:125], v[170:173], v[196:199], v[122:125]
	v_mfma_f32_16x16x32_bf16 v[118:121], v[162:165], v[204:207], v[118:121]
	v_mfma_f32_16x16x32_bf16 v[114:117], v[170:173], v[204:207], v[114:117]
	v_mfma_f32_16x16x32_bf16 v[102:105], v[162:165], v[212:215], v[102:105]
	v_mfma_f32_16x16x32_bf16 v[98:101], v[170:173], v[212:215], v[98:101]
	v_mfma_f32_16x16x32_bf16 v[86:89], v[162:165], v[220:223], v[86:89]
	v_mfma_f32_16x16x32_bf16 v[82:85], v[170:173], v[220:223], v[82:85]
	v_mfma_f32_16x16x32_bf16 v[110:113], v[174:177], v[190:193], v[110:113]
	v_mfma_f32_16x16x32_bf16 v[106:109], v[182:185], v[190:193], v[106:109]
	v_mfma_f32_16x16x32_bf16 v[94:97], v[174:177], v[200:203], v[94:97]
	v_mfma_f32_16x16x32_bf16 v[90:93], v[182:185], v[200:203], v[90:93]
	v_mfma_f32_16x16x32_bf16 v[78:81], v[174:177], v[208:211], v[78:81]
	v_mfma_f32_16x16x32_bf16 v[74:77], v[182:185], v[208:211], v[74:77]
	v_mfma_f32_16x16x32_bf16 v[70:73], v[174:177], v[216:219], v[70:73]
	v_mfma_f32_16x16x32_bf16 v[66:69], v[182:185], v[216:219], v[66:69]
	v_mfma_f32_16x16x32_bf16 v[110:113], v[178:181], v[196:199], v[110:113]
	v_mfma_f32_16x16x32_bf16 v[106:109], v[186:189], v[196:199], v[106:109]
	v_mfma_f32_16x16x32_bf16 v[94:97], v[178:181], v[204:207], v[94:97]
	v_mfma_f32_16x16x32_bf16 v[90:93], v[186:189], v[204:207], v[90:93]
	v_mfma_f32_16x16x32_bf16 v[78:81], v[178:181], v[212:215], v[78:81]
	v_mfma_f32_16x16x32_bf16 v[74:77], v[186:189], v[212:215], v[74:77]
	v_mfma_f32_16x16x32_bf16 v[70:73], v[178:181], v[220:223], v[70:73]
	v_mfma_f32_16x16x32_bf16 v[66:69], v[186:189], v[220:223], v[66:69]
	s_setprio 0
	s_barrier
	s_add_i32 s59, s50, s41
	v_lshl_add_u64 v[224:225], s[28:29], 0, v[134:135]
	s_mov_b32 m0, s59
	ds_read_b128 v[190:193], v157 offset:16384
	ds_read_b128 v[196:199], v157 offset:17408
	ds_read_b128 v[200:203], v157 offset:18432
	ds_read_b128 v[204:207], v157 offset:19456
	ds_read_b128 v[208:211], v157 offset:20480
	ds_read_b128 v[212:215], v157 offset:21504
	ds_read_b128 v[216:219], v157 offset:22528
	ds_read_b128 v[220:223], v157 offset:23552
	global_load_lds_dwordx4 v[224:225], off
	s_add_i32 m0, s59, 0x2000
	s_add_u32 s60, s28, 0x100000
	v_lshl_add_u64 v[226:227], s[28:29], 0, v[136:137]
	s_addc_u32 s61, s29, 0
	s_add_i32 s59, s51, s41
	global_load_lds_dwordx4 v[226:227], off
	v_lshl_add_u64 v[228:229], s[60:61], 0, v[134:135]
	s_mov_b32 m0, s59
	v_lshl_add_u64 v[230:231], s[30:31], 0, v[132:133]
	global_load_lds_dwordx4 v[228:229], off
	v_lshl_add_u64 v[228:229], s[60:61], 0, v[136:137]
	s_add_i32 m0, s59, 0x2000
	s_nop 0
	global_load_lds_dwordx4 v[228:229], off
	v_lshl_add_u64 v[228:229], s[30:31], 0, v[130:131]
	s_mov_b32 m0, s17
	s_nop 0
	global_load_lds_dwordx4 v[228:229], off
	s_mov_b32 m0, s42
	s_nop 0
	global_load_lds_dwordx4 v[230:231], off
	s_waitcnt vmcnt(8)
	s_waitcnt lgkmcnt(0)
	s_barrier
	s_setprio 1
	v_mfma_f32_16x16x32_bf16 v[62:65], v[158:161], v[190:193], v[62:65]
	v_mfma_f32_16x16x32_bf16 v[58:61], v[166:169], v[190:193], v[58:61]
	v_mfma_f32_16x16x32_bf16 v[54:57], v[158:161], v[200:203], v[54:57]
	v_mfma_f32_16x16x32_bf16 v[50:53], v[166:169], v[200:203], v[50:53]
	v_mfma_f32_16x16x32_bf16 v[38:41], v[158:161], v[208:211], v[38:41]
	v_mfma_f32_16x16x32_bf16 v[34:37], v[166:169], v[208:211], v[34:37]
	v_mfma_f32_16x16x32_bf16 v[22:25], v[158:161], v[216:219], v[22:25]
	v_mfma_f32_16x16x32_bf16 v[18:21], v[166:169], v[216:219], v[18:21]
	v_mfma_f32_16x16x32_bf16 v[62:65], v[162:165], v[196:199], v[62:65]
	v_mfma_f32_16x16x32_bf16 v[58:61], v[170:173], v[196:199], v[58:61]
	v_mfma_f32_16x16x32_bf16 v[54:57], v[162:165], v[204:207], v[54:57]
	v_mfma_f32_16x16x32_bf16 v[50:53], v[170:173], v[204:207], v[50:53]
	v_mfma_f32_16x16x32_bf16 v[38:41], v[162:165], v[212:215], v[38:41]
	v_mfma_f32_16x16x32_bf16 v[34:37], v[170:173], v[212:215], v[34:37]
	v_mfma_f32_16x16x32_bf16 v[22:25], v[162:165], v[220:223], v[22:25]
	v_mfma_f32_16x16x32_bf16 v[18:21], v[170:173], v[220:223], v[18:21]
	v_mfma_f32_16x16x32_bf16 v[46:49], v[174:177], v[190:193], v[46:49]
	v_mfma_f32_16x16x32_bf16 v[42:45], v[182:185], v[190:193], v[42:45]
	v_mfma_f32_16x16x32_bf16 v[30:33], v[174:177], v[200:203], v[30:33]
	v_mfma_f32_16x16x32_bf16 v[26:29], v[182:185], v[200:203], v[26:29]
	v_mfma_f32_16x16x32_bf16 v[14:17], v[174:177], v[208:211], v[14:17]
	v_mfma_f32_16x16x32_bf16 v[10:13], v[182:185], v[208:211], v[10:13]
	v_mfma_f32_16x16x32_bf16 v[6:9], v[174:177], v[216:219], v[6:9]
	v_mfma_f32_16x16x32_bf16 v[2:5], v[182:185], v[216:219], v[2:5]
	v_mfma_f32_16x16x32_bf16 v[46:49], v[178:181], v[196:199], v[46:49]
	v_mfma_f32_16x16x32_bf16 v[42:45], v[186:189], v[196:199], v[42:45]
	v_mfma_f32_16x16x32_bf16 v[30:33], v[178:181], v[204:207], v[30:33]
	v_mfma_f32_16x16x32_bf16 v[26:29], v[186:189], v[204:207], v[26:29]
	v_mfma_f32_16x16x32_bf16 v[14:17], v[178:181], v[212:215], v[14:17]
	v_mfma_f32_16x16x32_bf16 v[10:13], v[186:189], v[212:215], v[10:13]
	v_mfma_f32_16x16x32_bf16 v[6:9], v[178:181], v[220:223], v[6:9]
	v_mfma_f32_16x16x32_bf16 v[2:5], v[186:189], v[220:223], v[2:5]
	s_setprio 0
	s_barrier
	s_add_i32 s59, 0, 0x18000
	s_add_i32 s60, 0, 0x1c000
	v_add_u32_e32 v170, s59, v153
	v_add_u32_e32 v186, s60, v153
	ds_read_b128 v[158:161], v170
	ds_read_b128 v[162:165], v170 offset:1024
	ds_read_b128 v[166:169], v170 offset:2048
	ds_read_b128 v[170:173], v170 offset:3072
	ds_read_b128 v[174:177], v186
	ds_read_b128 v[178:181], v186 offset:1024
	ds_read_b128 v[182:185], v186 offset:2048
	ds_read_b128 v[186:189], v186 offset:3072
	s_add_u32 s30, s30, 0x100000
	s_addc_u32 s31, s31, 0
	s_mov_b32 m0, s43
	v_lshl_add_u64 v[232:233], s[30:31], 0, v[130:131]
	ds_read_b128 v[190:193], v157 offset:32768
	ds_read_b128 v[196:199], v157 offset:33792
	ds_read_b128 v[200:203], v157 offset:34816
	ds_read_b128 v[204:207], v157 offset:35840
	ds_read_b128 v[208:211], v157 offset:36864
	ds_read_b128 v[212:215], v157 offset:37888
	ds_read_b128 v[216:219], v157 offset:38912
	ds_read_b128 v[220:223], v157 offset:39936
	global_load_lds_dwordx4 v[232:233], off
	v_lshl_add_u64 v[232:233], s[30:31], 0, v[132:133]
	s_mov_b32 m0, s45
	s_nop 0
	global_load_lds_dwordx4 v[232:233], off
	s_waitcnt vmcnt(8)
	s_waitcnt lgkmcnt(0)
	s_barrier
	s_setprio 1
	v_mfma_f32_16x16x32_bf16 v[126:129], v[158:161], v[190:193], v[126:129]
	v_mfma_f32_16x16x32_bf16 v[122:125], v[166:169], v[190:193], v[122:125]
	v_mfma_f32_16x16x32_bf16 v[118:121], v[158:161], v[200:203], v[118:121]
	v_mfma_f32_16x16x32_bf16 v[114:117], v[166:169], v[200:203], v[114:117]
	v_mfma_f32_16x16x32_bf16 v[102:105], v[158:161], v[208:211], v[102:105]
	v_mfma_f32_16x16x32_bf16 v[98:101], v[166:169], v[208:211], v[98:101]
	v_mfma_f32_16x16x32_bf16 v[86:89], v[158:161], v[216:219], v[86:89]
	v_mfma_f32_16x16x32_bf16 v[82:85], v[166:169], v[216:219], v[82:85]
	v_mfma_f32_16x16x32_bf16 v[126:129], v[162:165], v[196:199], v[126:129]
	v_mfma_f32_16x16x32_bf16 v[122:125], v[170:173], v[196:199], v[122:125]
	v_mfma_f32_16x16x32_bf16 v[118:121], v[162:165], v[204:207], v[118:121]
	v_mfma_f32_16x16x32_bf16 v[114:117], v[170:173], v[204:207], v[114:117]
	v_mfma_f32_16x16x32_bf16 v[102:105], v[162:165], v[212:215], v[102:105]
	v_mfma_f32_16x16x32_bf16 v[98:101], v[170:173], v[212:215], v[98:101]
	v_mfma_f32_16x16x32_bf16 v[86:89], v[162:165], v[220:223], v[86:89]
	v_mfma_f32_16x16x32_bf16 v[82:85], v[170:173], v[220:223], v[82:85]
	v_mfma_f32_16x16x32_bf16 v[110:113], v[174:177], v[190:193], v[110:113]
	v_mfma_f32_16x16x32_bf16 v[106:109], v[182:185], v[190:193], v[106:109]
	v_mfma_f32_16x16x32_bf16 v[94:97], v[174:177], v[200:203], v[94:97]
	v_mfma_f32_16x16x32_bf16 v[90:93], v[182:185], v[200:203], v[90:93]
	v_mfma_f32_16x16x32_bf16 v[78:81], v[174:177], v[208:211], v[78:81]
	v_mfma_f32_16x16x32_bf16 v[74:77], v[182:185], v[208:211], v[74:77]
	v_mfma_f32_16x16x32_bf16 v[70:73], v[174:177], v[216:219], v[70:73]
	v_mfma_f32_16x16x32_bf16 v[66:69], v[182:185], v[216:219], v[66:69]
	v_mfma_f32_16x16x32_bf16 v[110:113], v[178:181], v[196:199], v[110:113]
	v_mfma_f32_16x16x32_bf16 v[106:109], v[186:189], v[196:199], v[106:109]
	v_mfma_f32_16x16x32_bf16 v[94:97], v[178:181], v[204:207], v[94:97]
	v_mfma_f32_16x16x32_bf16 v[90:93], v[186:189], v[204:207], v[90:93]
	v_mfma_f32_16x16x32_bf16 v[78:81], v[178:181], v[212:215], v[78:81]
	v_mfma_f32_16x16x32_bf16 v[74:77], v[186:189], v[212:215], v[74:77]
	v_mfma_f32_16x16x32_bf16 v[70:73], v[178:181], v[220:223], v[70:73]
	v_mfma_f32_16x16x32_bf16 v[66:69], v[186:189], v[220:223], v[66:69]
	s_setprio 0
	s_barrier
	s_add_i32 s30, s59, s41
	v_lshl_add_u64 v[224:225], v[224:225], 0, s[12:13]
	s_mov_b32 m0, s30
	ds_read_b128 v[190:193], v157 offset:49152
	ds_read_b128 v[196:199], v157 offset:50176
	ds_read_b128 v[200:203], v157 offset:51200
	ds_read_b128 v[204:207], v157 offset:52224
	ds_read_b128 v[208:211], v157 offset:53248
	ds_read_b128 v[212:215], v157 offset:54272
	ds_read_b128 v[216:219], v157 offset:55296
	ds_read_b128 v[220:223], v157 offset:56320
	global_load_lds_dwordx4 v[224:225], off
	s_add_i32 m0, s30, 0x2000
	s_add_u32 s28, s28, 0x100080
	v_lshl_add_u64 v[224:225], v[226:227], 0, s[12:13]
	s_addc_u32 s29, s29, 0
	s_add_i32 s30, s60, s41
	global_load_lds_dwordx4 v[224:225], off
	v_lshl_add_u64 v[224:225], s[28:29], 0, v[134:135]
	s_mov_b32 m0, s30
	s_nop 0
	global_load_lds_dwordx4 v[224:225], off
	v_lshl_add_u64 v[224:225], s[28:29], 0, v[136:137]
	s_add_i32 m0, s30, 0x2000
	s_nop 0
	global_load_lds_dwordx4 v[224:225], off
	v_lshl_add_u64 v[224:225], v[228:229], 0, s[12:13]
	s_mov_b32 m0, s47
	s_nop 0
	global_load_lds_dwordx4 v[224:225], off
	v_lshl_add_u64 v[224:225], v[230:231], 0, s[12:13]
	s_mov_b32 m0, s48
	s_nop 0
	global_load_lds_dwordx4 v[224:225], off
	s_nop 0
	s_waitcnt vmcnt(8)
	s_waitcnt lgkmcnt(0)
	s_barrier
	s_setprio 1
	v_mfma_f32_16x16x32_bf16 v[62:65], v[158:161], v[190:193], v[62:65]
	v_mfma_f32_16x16x32_bf16 v[58:61], v[166:169], v[190:193], v[58:61]
	v_mfma_f32_16x16x32_bf16 v[54:57], v[158:161], v[200:203], v[54:57]
	v_mfma_f32_16x16x32_bf16 v[50:53], v[166:169], v[200:203], v[50:53]
	v_mfma_f32_16x16x32_bf16 v[38:41], v[158:161], v[208:211], v[38:41]
	v_mfma_f32_16x16x32_bf16 v[34:37], v[166:169], v[208:211], v[34:37]
	v_mfma_f32_16x16x32_bf16 v[22:25], v[158:161], v[216:219], v[22:25]
	v_mfma_f32_16x16x32_bf16 v[18:21], v[166:169], v[216:219], v[18:21]
	v_mfma_f32_16x16x32_bf16 v[62:65], v[162:165], v[196:199], v[62:65]
	v_mfma_f32_16x16x32_bf16 v[58:61], v[170:173], v[196:199], v[58:61]
	v_mfma_f32_16x16x32_bf16 v[54:57], v[162:165], v[204:207], v[54:57]
	v_mfma_f32_16x16x32_bf16 v[50:53], v[170:173], v[204:207], v[50:53]
	v_mfma_f32_16x16x32_bf16 v[38:41], v[162:165], v[212:215], v[38:41]
	v_mfma_f32_16x16x32_bf16 v[34:37], v[170:173], v[212:215], v[34:37]
	v_mfma_f32_16x16x32_bf16 v[22:25], v[162:165], v[220:223], v[22:25]
	v_mfma_f32_16x16x32_bf16 v[18:21], v[170:173], v[220:223], v[18:21]
	v_mfma_f32_16x16x32_bf16 v[46:49], v[174:177], v[190:193], v[46:49]
	v_mfma_f32_16x16x32_bf16 v[42:45], v[182:185], v[190:193], v[42:45]
	v_mfma_f32_16x16x32_bf16 v[30:33], v[174:177], v[200:203], v[30:33]
	v_mfma_f32_16x16x32_bf16 v[26:29], v[182:185], v[200:203], v[26:29]
	v_mfma_f32_16x16x32_bf16 v[14:17], v[174:177], v[208:211], v[14:17]
	v_mfma_f32_16x16x32_bf16 v[10:13], v[182:185], v[208:211], v[10:13]
	v_mfma_f32_16x16x32_bf16 v[6:9], v[174:177], v[216:219], v[6:9]
	v_mfma_f32_16x16x32_bf16 v[2:5], v[182:185], v[216:219], v[2:5]
	v_mfma_f32_16x16x32_bf16 v[46:49], v[178:181], v[196:199], v[46:49]
	v_mfma_f32_16x16x32_bf16 v[42:45], v[186:189], v[196:199], v[42:45]
	v_mfma_f32_16x16x32_bf16 v[30:33], v[178:181], v[204:207], v[30:33]
	v_mfma_f32_16x16x32_bf16 v[26:29], v[186:189], v[204:207], v[26:29]
	v_mfma_f32_16x16x32_bf16 v[14:17], v[178:181], v[212:215], v[14:17]
	v_mfma_f32_16x16x32_bf16 v[10:13], v[186:189], v[212:215], v[10:13]
	v_mfma_f32_16x16x32_bf16 v[6:9], v[178:181], v[220:223], v[6:9]
	v_mfma_f32_16x16x32_bf16 v[2:5], v[186:189], v[220:223], v[2:5]
	s_setprio 0
	s_barrier
	s_add_i32 s58, s58, 2
	s_add_u32 s26, s26, 0x100
	s_addc_u32 s27, s27, 0
	s_add_u32 s56, s56, 0x100
	s_addc_u32 s57, s57, 0
	s_cmp_gt_u32 s58, 61
	s_cbranch_scc0 .LBB0_657
	s_and_b64 vcc, exec, s[14:15]
	s_cbranch_vccz .LBB0_660
	s_barrier

.LBB0_681:
	ds_read_b128 v[152:155], v144
	ds_read_b128 v[156:159], v144 offset:1024
	ds_read_b128 v[160:163], v144 offset:2048
	ds_read_b128 v[164:167], v144 offset:3072
	ds_read_b128 v[168:171], v145
	ds_read_b128 v[172:175], v145 offset:1024
	ds_read_b128 v[176:179], v145 offset:2048
	ds_read_b128 v[180:183], v145 offset:3072
	s_add_u32 s42, s40, 0xfff00080
	s_addc_u32 s43, s41, -1
	s_cmp_eq_u32 s70, 60
	s_cselect_b32 s47, s27, s43
	s_cselect_b32 s46, s66, s42
	s_cselect_b32 s43, s25, s69
	s_cselect_b32 s42, s67, s68
	v_lshl_add_u64 v[192:193], s[40:41], 0, v[134:135]
	s_add_i32 m0, s29, 0xc000
	ds_read_b128 v[184:187], v150
	ds_read_b128 v[188:191], v150 offset:1024
	ds_read_b128 v[196:199], v150 offset:2048
	ds_read_b128 v[200:203], v150 offset:3072
	ds_read_b128 v[204:207], v150 offset:4096
	ds_read_b128 v[208:211], v150 offset:5120
	ds_read_b128 v[212:215], v150 offset:6144
	ds_read_b128 v[216:219], v150 offset:7168
	global_load_lds_dwordx4 v[192:193], off
	v_lshl_add_u64 v[192:193], s[40:41], 0, v[136:137]
	s_add_i32 m0, s29, 0xe000
	s_nop 0
	global_load_lds_dwordx4 v[192:193], off
	s_nop 0
	s_waitcnt vmcnt(8)
	s_waitcnt lgkmcnt(0)
	s_barrier
	s_setprio 1
	v_mfma_f32_16x16x32_bf16 v[126:129], v[152:155], v[184:187], v[126:129]
	v_mfma_f32_16x16x32_bf16 v[122:125], v[160:163], v[184:187], v[122:125]
	v_mfma_f32_16x16x32_bf16 v[118:121], v[152:155], v[196:199], v[118:121]
	v_mfma_f32_16x16x32_bf16 v[110:113], v[160:163], v[196:199], v[110:113]
	v_mfma_f32_16x16x32_bf16 v[102:105], v[152:155], v[204:207], v[102:105]
	v_mfma_f32_16x16x32_bf16 v[94:97], v[160:163], v[204:207], v[94:97]
	v_mfma_f32_16x16x32_bf16 v[86:89], v[152:155], v[212:215], v[86:89]
	v_mfma_f32_16x16x32_bf16 v[78:81], v[160:163], v[212:215], v[78:81]
	v_mfma_f32_16x16x32_bf16 v[126:129], v[156:159], v[188:191], v[126:129]
	v_mfma_f32_16x16x32_bf16 v[122:125], v[164:167], v[188:191], v[122:125]
	v_mfma_f32_16x16x32_bf16 v[118:121], v[156:159], v[200:203], v[118:121]
	v_mfma_f32_16x16x32_bf16 v[110:113], v[164:167], v[200:203], v[110:113]
	v_mfma_f32_16x16x32_bf16 v[102:105], v[156:159], v[208:211], v[102:105]
	v_mfma_f32_16x16x32_bf16 v[94:97], v[164:167], v[208:211], v[94:97]
	v_mfma_f32_16x16x32_bf16 v[86:89], v[156:159], v[216:219], v[86:89]
	v_mfma_f32_16x16x32_bf16 v[78:81], v[164:167], v[216:219], v[78:81]
	v_mfma_f32_16x16x32_bf16 v[114:117], v[168:171], v[184:187], v[114:117]
	v_mfma_f32_16x16x32_bf16 v[106:109], v[176:179], v[184:187], v[106:109]
	v_mfma_f32_16x16x32_bf16 v[98:101], v[168:171], v[196:199], v[98:101]
	v_mfma_f32_16x16x32_bf16 v[90:93], v[176:179], v[196:199], v[90:93]
	v_mfma_f32_16x16x32_bf16 v[82:85], v[168:171], v[204:207], v[82:85]
	v_mfma_f32_16x16x32_bf16 v[74:77], v[176:179], v[204:207], v[74:77]
	v_mfma_f32_16x16x32_bf16 v[70:73], v[168:171], v[212:215], v[70:73]
	v_mfma_f32_16x16x32_bf16 v[66:69], v[176:179], v[212:215], v[66:69]
	v_mfma_f32_16x16x32_bf16 v[114:117], v[172:175], v[188:191], v[114:117]
	v_mfma_f32_16x16x32_bf16 v[106:109], v[180:183], v[188:191], v[106:109]
	v_mfma_f32_16x16x32_bf16 v[98:101], v[172:175], v[200:203], v[98:101]
	v_mfma_f32_16x16x32_bf16 v[90:93], v[180:183], v[200:203], v[90:93]
	v_mfma_f32_16x16x32_bf16 v[82:85], v[172:175], v[208:211], v[82:85]
	v_mfma_f32_16x16x32_bf16 v[74:77], v[180:183], v[208:211], v[74:77]
	v_mfma_f32_16x16x32_bf16 v[70:73], v[172:175], v[216:219], v[70:73]
	v_mfma_f32_16x16x32_bf16 v[66:69], v[180:183], v[216:219], v[66:69]
	s_setprio 0
	s_barrier
	s_add_i32 s71, s62, s54
	v_lshl_add_u64 v[192:193], s[42:43], 0, v[130:131]
	s_mov_b32 m0, s71
	ds_read_b128 v[184:187], v150 offset:16384
	ds_read_b128 v[188:191], v150 offset:17408
	ds_read_b128 v[196:199], v150 offset:18432
	ds_read_b128 v[200:203], v150 offset:19456
	ds_read_b128 v[204:207], v150 offset:20480
	ds_read_b128 v[208:211], v150 offset:21504
	ds_read_b128 v[212:215], v150 offset:22528
	ds_read_b128 v[216:219], v150 offset:23552
	global_load_lds_dwordx4 v[192:193], off
	s_add_i32 m0, s71, 0x2000
	s_add_u32 s72, s42, 0x100000
	v_lshl_add_u64 v[220:221], s[42:43], 0, v[132:133]
	s_addc_u32 s73, s43, 0
	s_add_i32 s71, s63, s54
	global_load_lds_dwordx4 v[220:221], off
	v_lshl_add_u64 v[222:223], s[72:73], 0, v[130:131]
	s_mov_b32 m0, s71
	v_lshl_add_u64 v[224:225], s[46:47], 0, v[132:133]
	global_load_lds_dwordx4 v[222:223], off
	v_lshl_add_u64 v[222:223], s[72:73], 0, v[132:133]
	s_add_i32 m0, s71, 0x2000
	s_nop 0
	global_load_lds_dwordx4 v[222:223], off
	v_lshl_add_u64 v[222:223], s[46:47], 0, v[130:131]
	s_mov_b32 m0, s29
	s_nop 0
	global_load_lds_dwordx4 v[222:223], off
	s_mov_b32 m0, s55
	s_nop 0
	global_load_lds_dwordx4 v[224:225], off
	s_waitcnt vmcnt(8)
	s_waitcnt lgkmcnt(0)
	s_barrier
	s_setprio 1
	v_mfma_f32_16x16x32_bf16 v[62:65], v[152:155], v[184:187], v[62:65]
	v_mfma_f32_16x16x32_bf16 v[58:61], v[160:163], v[184:187], v[58:61]
	v_mfma_f32_16x16x32_bf16 v[54:57], v[152:155], v[196:199], v[54:57]
	v_mfma_f32_16x16x32_bf16 v[46:49], v[160:163], v[196:199], v[46:49]
	v_mfma_f32_16x16x32_bf16 v[38:41], v[152:155], v[204:207], v[38:41]
	v_mfma_f32_16x16x32_bf16 v[30:33], v[160:163], v[204:207], v[30:33]
	v_mfma_f32_16x16x32_bf16 v[22:25], v[152:155], v[212:215], v[22:25]
	v_mfma_f32_16x16x32_bf16 v[14:17], v[160:163], v[212:215], v[14:17]
	v_mfma_f32_16x16x32_bf16 v[62:65], v[156:159], v[188:191], v[62:65]
	v_mfma_f32_16x16x32_bf16 v[58:61], v[164:167], v[188:191], v[58:61]
	v_mfma_f32_16x16x32_bf16 v[54:57], v[156:159], v[200:203], v[54:57]
	v_mfma_f32_16x16x32_bf16 v[46:49], v[164:167], v[200:203], v[46:49]
	v_mfma_f32_16x16x32_bf16 v[38:41], v[156:159], v[208:211], v[38:41]
	v_mfma_f32_16x16x32_bf16 v[30:33], v[164:167], v[208:211], v[30:33]
	v_mfma_f32_16x16x32_bf16 v[22:25], v[156:159], v[216:219], v[22:25]
	v_mfma_f32_16x16x32_bf16 v[14:17], v[164:167], v[216:219], v[14:17]
	v_mfma_f32_16x16x32_bf16 v[50:53], v[168:171], v[184:187], v[50:53]
	v_mfma_f32_16x16x32_bf16 v[42:45], v[176:179], v[184:187], v[42:45]
	v_mfma_f32_16x16x32_bf16 v[34:37], v[168:171], v[196:199], v[34:37]
	v_mfma_f32_16x16x32_bf16 v[26:29], v[176:179], v[196:199], v[26:29]
	v_mfma_f32_16x16x32_bf16 v[18:21], v[168:171], v[204:207], v[18:21]
	v_mfma_f32_16x16x32_bf16 v[10:13], v[176:179], v[204:207], v[10:13]
	v_mfma_f32_16x16x32_bf16 v[6:9], v[168:171], v[212:215], v[6:9]
	v_mfma_f32_16x16x32_bf16 v[2:5], v[176:179], v[212:215], v[2:5]
	v_mfma_f32_16x16x32_bf16 v[50:53], v[172:175], v[188:191], v[50:53]
	v_mfma_f32_16x16x32_bf16 v[42:45], v[180:183], v[188:191], v[42:45]
	v_mfma_f32_16x16x32_bf16 v[34:37], v[172:175], v[200:203], v[34:37]
	v_mfma_f32_16x16x32_bf16 v[26:29], v[180:183], v[200:203], v[26:29]
	v_mfma_f32_16x16x32_bf16 v[18:21], v[172:175], v[208:211], v[18:21]
	v_mfma_f32_16x16x32_bf16 v[10:13], v[180:183], v[208:211], v[10:13]
	v_mfma_f32_16x16x32_bf16 v[6:9], v[172:175], v[216:219], v[6:9]
	v_mfma_f32_16x16x32_bf16 v[2:5], v[180:183], v[216:219], v[2:5]
	s_setprio 0
	s_barrier
	s_add_i32 s71, 0, 0x18000
	v_add_u32_e32 v151, s71, v142
	s_add_i32 s72, 0, 0x1c000
	ds_read_b128 v[152:155], v151
	ds_read_b128 v[156:159], v151 offset:1024
	ds_read_b128 v[160:163], v151 offset:2048
	ds_read_b128 v[164:167], v151 offset:3072
	v_add_u32_e32 v151, s72, v142
	ds_read_b128 v[168:171], v151
	ds_read_b128 v[172:175], v151 offset:1024
	ds_read_b128 v[176:179], v151 offset:2048
	ds_read_b128 v[180:183], v151 offset:3072
	s_add_u32 s46, s46, 0x100000
	s_addc_u32 s47, s47, 0
	s_mov_b32 m0, s56
	v_lshl_add_u64 v[226:227], s[46:47], 0, v[130:131]
	ds_read_b128 v[184:187], v150 offset:32768
	ds_read_b128 v[188:191], v150 offset:33792
	ds_read_b128 v[196:199], v150 offset:34816
	ds_read_b128 v[200:203], v150 offset:35840
	ds_read_b128 v[204:207], v150 offset:36864
	ds_read_b128 v[208:211], v150 offset:37888
	ds_read_b128 v[212:215], v150 offset:38912
	ds_read_b128 v[216:219], v150 offset:39936
	global_load_lds_dwordx4 v[226:227], off
	v_lshl_add_u64 v[226:227], s[46:47], 0, v[132:133]
	s_mov_b32 m0, s57
	s_nop 0
	global_load_lds_dwordx4 v[226:227], off
	s_waitcnt vmcnt(8)
	s_waitcnt lgkmcnt(0)
	s_barrier
	s_setprio 1
	v_mfma_f32_16x16x32_bf16 v[126:129], v[152:155], v[184:187], v[126:129]
	v_mfma_f32_16x16x32_bf16 v[122:125], v[160:163], v[184:187], v[122:125]
	v_mfma_f32_16x16x32_bf16 v[118:121], v[152:155], v[196:199], v[118:121]
	v_mfma_f32_16x16x32_bf16 v[110:113], v[160:163], v[196:199], v[110:113]
	v_mfma_f32_16x16x32_bf16 v[102:105], v[152:155], v[204:207], v[102:105]
	v_mfma_f32_16x16x32_bf16 v[94:97], v[160:163], v[204:207], v[94:97]
	v_mfma_f32_16x16x32_bf16 v[86:89], v[152:155], v[212:215], v[86:89]
	v_mfma_f32_16x16x32_bf16 v[78:81], v[160:163], v[212:215], v[78:81]
	v_mfma_f32_16x16x32_bf16 v[126:129], v[156:159], v[188:191], v[126:129]
	v_mfma_f32_16x16x32_bf16 v[122:125], v[164:167], v[188:191], v[122:125]
	v_mfma_f32_16x16x32_bf16 v[118:121], v[156:159], v[200:203], v[118:121]
	v_mfma_f32_16x16x32_bf16 v[110:113], v[164:167], v[200:203], v[110:113]
	v_mfma_f32_16x16x32_bf16 v[102:105], v[156:159], v[208:211], v[102:105]
	v_mfma_f32_16x16x32_bf16 v[94:97], v[164:167], v[208:211], v[94:97]
	v_mfma_f32_16x16x32_bf16 v[86:89], v[156:159], v[216:219], v[86:89]
	v_mfma_f32_16x16x32_bf16 v[78:81], v[164:167], v[216:219], v[78:81]
	v_mfma_f32_16x16x32_bf16 v[114:117], v[168:171], v[184:187], v[114:117]
	v_mfma_f32_16x16x32_bf16 v[106:109], v[176:179], v[184:187], v[106:109]
	v_mfma_f32_16x16x32_bf16 v[98:101], v[168:171], v[196:199], v[98:101]
	v_mfma_f32_16x16x32_bf16 v[90:93], v[176:179], v[196:199], v[90:93]
	v_mfma_f32_16x16x32_bf16 v[82:85], v[168:171], v[204:207], v[82:85]
	v_mfma_f32_16x16x32_bf16 v[74:77], v[176:179], v[204:207], v[74:77]
	v_mfma_f32_16x16x32_bf16 v[70:73], v[168:171], v[212:215], v[70:73]
	v_mfma_f32_16x16x32_bf16 v[66:69], v[176:179], v[212:215], v[66:69]
	v_mfma_f32_16x16x32_bf16 v[114:117], v[172:175], v[188:191], v[114:117]
	v_mfma_f32_16x16x32_bf16 v[106:109], v[180:183], v[188:191], v[106:109]
	v_mfma_f32_16x16x32_bf16 v[98:101], v[172:175], v[200:203], v[98:101]
	v_mfma_f32_16x16x32_bf16 v[90:93], v[180:183], v[200:203], v[90:93]
	v_mfma_f32_16x16x32_bf16 v[82:85], v[172:175], v[208:211], v[82:85]
	v_mfma_f32_16x16x32_bf16 v[74:77], v[180:183], v[208:211], v[74:77]
	v_mfma_f32_16x16x32_bf16 v[70:73], v[172:175], v[216:219], v[70:73]
	v_mfma_f32_16x16x32_bf16 v[66:69], v[180:183], v[216:219], v[66:69]
	s_setprio 0
	s_barrier
	s_add_i32 s46, s71, s54
	v_lshl_add_u64 v[192:193], v[192:193], 0, s[10:11]
	s_mov_b32 m0, s46
	ds_read_b128 v[184:187], v150 offset:49152
	ds_read_b128 v[188:191], v150 offset:50176
	ds_read_b128 v[196:199], v150 offset:51200
	ds_read_b128 v[200:203], v150 offset:52224
	ds_read_b128 v[204:207], v150 offset:53248
	ds_read_b128 v[208:211], v150 offset:54272
	ds_read_b128 v[212:215], v150 offset:55296
	ds_read_b128 v[216:219], v150 offset:56320
	global_load_lds_dwordx4 v[192:193], off
	s_add_i32 m0, s46, 0x2000
	s_add_u32 s42, s42, 0x100080
	v_lshl_add_u64 v[192:193], v[220:221], 0, s[10:11]
	s_addc_u32 s43, s43, 0
	s_add_i32 s46, s72, s54
	global_load_lds_dwordx4 v[192:193], off
	v_lshl_add_u64 v[192:193], s[42:43], 0, v[130:131]
	s_mov_b32 m0, s46
	s_nop 0
	global_load_lds_dwordx4 v[192:193], off
	v_lshl_add_u64 v[192:193], s[42:43], 0, v[132:133]
	s_add_i32 m0, s46, 0x2000
	s_nop 0
	global_load_lds_dwordx4 v[192:193], off
	v_lshl_add_u64 v[192:193], v[222:223], 0, s[10:11]
	s_mov_b32 m0, s59
	s_nop 0
	global_load_lds_dwordx4 v[192:193], off
	v_lshl_add_u64 v[192:193], v[224:225], 0, s[10:11]
	s_mov_b32 m0, s60
	s_nop 0
	global_load_lds_dwordx4 v[192:193], off
	s_nop 0
	s_waitcnt vmcnt(8)
	s_waitcnt lgkmcnt(0)
	s_barrier
	s_setprio 1
	v_mfma_f32_16x16x32_bf16 v[62:65], v[152:155], v[184:187], v[62:65]
	v_mfma_f32_16x16x32_bf16 v[58:61], v[160:163], v[184:187], v[58:61]
	v_mfma_f32_16x16x32_bf16 v[54:57], v[152:155], v[196:199], v[54:57]
	v_mfma_f32_16x16x32_bf16 v[46:49], v[160:163], v[196:199], v[46:49]
	v_mfma_f32_16x16x32_bf16 v[38:41], v[152:155], v[204:207], v[38:41]
	v_mfma_f32_16x16x32_bf16 v[30:33], v[160:163], v[204:207], v[30:33]
	v_mfma_f32_16x16x32_bf16 v[22:25], v[152:155], v[212:215], v[22:25]
	v_mfma_f32_16x16x32_bf16 v[14:17], v[160:163], v[212:215], v[14:17]
	v_mfma_f32_16x16x32_bf16 v[62:65], v[156:159], v[188:191], v[62:65]
	v_mfma_f32_16x16x32_bf16 v[58:61], v[164:167], v[188:191], v[58:61]
	v_mfma_f32_16x16x32_bf16 v[54:57], v[156:159], v[200:203], v[54:57]
	v_mfma_f32_16x16x32_bf16 v[46:49], v[164:167], v[200:203], v[46:49]
	v_mfma_f32_16x16x32_bf16 v[38:41], v[156:159], v[208:211], v[38:41]
	v_mfma_f32_16x16x32_bf16 v[30:33], v[164:167], v[208:211], v[30:33]
	v_mfma_f32_16x16x32_bf16 v[22:25], v[156:159], v[216:219], v[22:25]
	v_mfma_f32_16x16x32_bf16 v[14:17], v[164:167], v[216:219], v[14:17]
	v_mfma_f32_16x16x32_bf16 v[50:53], v[168:171], v[184:187], v[50:53]
	v_mfma_f32_16x16x32_bf16 v[42:45], v[176:179], v[184:187], v[42:45]
	v_mfma_f32_16x16x32_bf16 v[34:37], v[168:171], v[196:199], v[34:37]
	v_mfma_f32_16x16x32_bf16 v[26:29], v[176:179], v[196:199], v[26:29]
	v_mfma_f32_16x16x32_bf16 v[18:21], v[168:171], v[204:207], v[18:21]
	v_mfma_f32_16x16x32_bf16 v[10:13], v[176:179], v[204:207], v[10:13]
	v_mfma_f32_16x16x32_bf16 v[6:9], v[168:171], v[212:215], v[6:9]
	v_mfma_f32_16x16x32_bf16 v[2:5], v[176:179], v[212:215], v[2:5]
	v_mfma_f32_16x16x32_bf16 v[50:53], v[172:175], v[188:191], v[50:53]
	v_mfma_f32_16x16x32_bf16 v[42:45], v[180:183], v[188:191], v[42:45]
	v_mfma_f32_16x16x32_bf16 v[34:37], v[172:175], v[200:203], v[34:37]
	v_mfma_f32_16x16x32_bf16 v[26:29], v[180:183], v[200:203], v[26:29]
	v_mfma_f32_16x16x32_bf16 v[18:21], v[172:175], v[208:211], v[18:21]
	v_mfma_f32_16x16x32_bf16 v[10:13], v[180:183], v[208:211], v[10:13]
	v_mfma_f32_16x16x32_bf16 v[6:9], v[172:175], v[216:219], v[6:9]
	v_mfma_f32_16x16x32_bf16 v[2:5], v[180:183], v[216:219], v[2:5]
	s_setprio 0
	s_barrier
	s_add_i32 s70, s70, 2
	s_add_u32 s40, s40, 0x100
	s_addc_u32 s41, s41, 0
	s_add_u32 s68, s68, 0x100
	s_addc_u32 s69, s69, 0
	s_cmp_gt_u32 s70, 61
	s_cbranch_scc0 .LBB0_681
	s_and_b64 vcc, exec, s[12:13]
	s_cbranch_vccz .LBB0_684
	s_barrier

.LBB0_705:
	ds_read_b128 v[144:147], v139
	ds_read_b128 v[148:151], v139 offset:1024
	ds_read_b128 v[152:155], v139 offset:2048
	ds_read_b128 v[156:159], v139 offset:3072
	ds_read_b128 v[160:163], v140
	ds_read_b128 v[164:167], v140 offset:1024
	ds_read_b128 v[168:171], v140 offset:2048
	ds_read_b128 v[172:175], v140 offset:3072
	s_add_u32 s42, s40, 0xfff00080
	s_addc_u32 s43, s41, -1
	s_cmp_eq_u32 s67, 60
	s_cselect_b32 s47, s27, s43
	s_cselect_b32 s46, s63, s42
	s_cselect_b32 s43, s25, s66
	s_cselect_b32 s42, s64, s65
	v_lshl_add_u64 v[192:193], s[40:41], 0, v[134:135]
	s_add_i32 m0, s29, 0xc000
	ds_read_b128 v[176:179], v142
	ds_read_b128 v[180:183], v142 offset:1024
	ds_read_b128 v[184:187], v142 offset:2048
	ds_read_b128 v[188:191], v142 offset:3072
	ds_read_b128 v[196:199], v142 offset:4096
	ds_read_b128 v[200:203], v142 offset:5120
	ds_read_b128 v[204:207], v142 offset:6144
	ds_read_b128 v[208:211], v142 offset:7168
	global_load_lds_dwordx4 v[192:193], off
	v_lshl_add_u64 v[192:193], s[40:41], 0, v[136:137]
	s_add_i32 m0, s29, 0xe000
	s_nop 0
	global_load_lds_dwordx4 v[192:193], off
	s_nop 0
	s_waitcnt vmcnt(8)
	s_waitcnt lgkmcnt(0)
	s_barrier
	s_setprio 1
	v_mfma_f32_16x16x32_bf16 v[126:129], v[144:147], v[176:179], v[126:129]
	v_mfma_f32_16x16x32_bf16 v[122:125], v[152:155], v[176:179], v[122:125]
	v_mfma_f32_16x16x32_bf16 v[118:121], v[144:147], v[184:187], v[118:121]
	v_mfma_f32_16x16x32_bf16 v[110:113], v[152:155], v[184:187], v[110:113]
	v_mfma_f32_16x16x32_bf16 v[102:105], v[144:147], v[196:199], v[102:105]
	v_mfma_f32_16x16x32_bf16 v[94:97], v[152:155], v[196:199], v[94:97]
	v_mfma_f32_16x16x32_bf16 v[86:89], v[144:147], v[204:207], v[86:89]
	v_mfma_f32_16x16x32_bf16 v[78:81], v[152:155], v[204:207], v[78:81]
	v_mfma_f32_16x16x32_bf16 v[126:129], v[148:151], v[180:183], v[126:129]
	v_mfma_f32_16x16x32_bf16 v[122:125], v[156:159], v[180:183], v[122:125]
	v_mfma_f32_16x16x32_bf16 v[118:121], v[148:151], v[188:191], v[118:121]
	v_mfma_f32_16x16x32_bf16 v[110:113], v[156:159], v[188:191], v[110:113]
	v_mfma_f32_16x16x32_bf16 v[102:105], v[148:151], v[200:203], v[102:105]
	v_mfma_f32_16x16x32_bf16 v[94:97], v[156:159], v[200:203], v[94:97]
	v_mfma_f32_16x16x32_bf16 v[86:89], v[148:151], v[208:211], v[86:89]
	v_mfma_f32_16x16x32_bf16 v[78:81], v[156:159], v[208:211], v[78:81]
	v_mfma_f32_16x16x32_bf16 v[114:117], v[160:163], v[176:179], v[114:117]
	v_mfma_f32_16x16x32_bf16 v[106:109], v[168:171], v[176:179], v[106:109]
	v_mfma_f32_16x16x32_bf16 v[98:101], v[160:163], v[184:187], v[98:101]
	v_mfma_f32_16x16x32_bf16 v[90:93], v[168:171], v[184:187], v[90:93]
	v_mfma_f32_16x16x32_bf16 v[82:85], v[160:163], v[196:199], v[82:85]
	v_mfma_f32_16x16x32_bf16 v[74:77], v[168:171], v[196:199], v[74:77]
	v_mfma_f32_16x16x32_bf16 v[70:73], v[160:163], v[204:207], v[70:73]
	v_mfma_f32_16x16x32_bf16 v[66:69], v[168:171], v[204:207], v[66:69]
	v_mfma_f32_16x16x32_bf16 v[114:117], v[164:167], v[180:183], v[114:117]
	v_mfma_f32_16x16x32_bf16 v[106:109], v[172:175], v[180:183], v[106:109]
	v_mfma_f32_16x16x32_bf16 v[98:101], v[164:167], v[188:191], v[98:101]
	v_mfma_f32_16x16x32_bf16 v[90:93], v[172:175], v[188:191], v[90:93]
	v_mfma_f32_16x16x32_bf16 v[82:85], v[164:167], v[200:203], v[82:85]
	v_mfma_f32_16x16x32_bf16 v[74:77], v[172:175], v[200:203], v[74:77]
	v_mfma_f32_16x16x32_bf16 v[70:73], v[164:167], v[208:211], v[70:73]
	v_mfma_f32_16x16x32_bf16 v[66:69], v[172:175], v[208:211], v[66:69]
	s_setprio 0
	s_barrier
	s_add_i32 s68, s59, s51
	v_lshl_add_u64 v[192:193], s[42:43], 0, v[130:131]
	s_mov_b32 m0, s68
	ds_read_b128 v[176:179], v142 offset:16384
	ds_read_b128 v[180:183], v142 offset:17408
	ds_read_b128 v[184:187], v142 offset:18432
	ds_read_b128 v[188:191], v142 offset:19456
	ds_read_b128 v[196:199], v142 offset:20480
	ds_read_b128 v[200:203], v142 offset:21504
	ds_read_b128 v[204:207], v142 offset:22528
	ds_read_b128 v[208:211], v142 offset:23552
	global_load_lds_dwordx4 v[192:193], off
	s_add_i32 m0, s68, 0x2000
	s_add_u32 s68, s42, 0x100000
	v_lshl_add_u64 v[212:213], s[42:43], 0, v[132:133]
	s_addc_u32 s69, s43, 0
	s_add_i32 s70, s60, s51
	global_load_lds_dwordx4 v[212:213], off
	v_lshl_add_u64 v[214:215], s[68:69], 0, v[130:131]
	s_mov_b32 m0, s70
	v_lshl_add_u64 v[216:217], s[46:47], 0, v[132:133]
	global_load_lds_dwordx4 v[214:215], off
	v_lshl_add_u64 v[214:215], s[68:69], 0, v[132:133]
	s_add_i32 m0, s70, 0x2000
	s_nop 0
	global_load_lds_dwordx4 v[214:215], off
	v_lshl_add_u64 v[214:215], s[46:47], 0, v[130:131]
	s_mov_b32 m0, s29
	s_nop 0
	global_load_lds_dwordx4 v[214:215], off
	s_mov_b32 m0, s52
	s_nop 0
	global_load_lds_dwordx4 v[216:217], off
	s_waitcnt vmcnt(8)
	s_waitcnt lgkmcnt(0)
	s_barrier
	s_setprio 1
	v_mfma_f32_16x16x32_bf16 v[62:65], v[144:147], v[176:179], v[62:65]
	v_mfma_f32_16x16x32_bf16 v[58:61], v[152:155], v[176:179], v[58:61]
	v_mfma_f32_16x16x32_bf16 v[54:57], v[144:147], v[184:187], v[54:57]
	v_mfma_f32_16x16x32_bf16 v[46:49], v[152:155], v[184:187], v[46:49]
	v_mfma_f32_16x16x32_bf16 v[38:41], v[144:147], v[196:199], v[38:41]
	v_mfma_f32_16x16x32_bf16 v[30:33], v[152:155], v[196:199], v[30:33]
	v_mfma_f32_16x16x32_bf16 v[22:25], v[144:147], v[204:207], v[22:25]
	v_mfma_f32_16x16x32_bf16 v[14:17], v[152:155], v[204:207], v[14:17]
	v_mfma_f32_16x16x32_bf16 v[62:65], v[148:151], v[180:183], v[62:65]
	v_mfma_f32_16x16x32_bf16 v[58:61], v[156:159], v[180:183], v[58:61]
	v_mfma_f32_16x16x32_bf16 v[54:57], v[148:151], v[188:191], v[54:57]
	v_mfma_f32_16x16x32_bf16 v[46:49], v[156:159], v[188:191], v[46:49]
	v_mfma_f32_16x16x32_bf16 v[38:41], v[148:151], v[200:203], v[38:41]
	v_mfma_f32_16x16x32_bf16 v[30:33], v[156:159], v[200:203], v[30:33]
	v_mfma_f32_16x16x32_bf16 v[22:25], v[148:151], v[208:211], v[22:25]
	v_mfma_f32_16x16x32_bf16 v[14:17], v[156:159], v[208:211], v[14:17]
	v_mfma_f32_16x16x32_bf16 v[50:53], v[160:163], v[176:179], v[50:53]
	v_mfma_f32_16x16x32_bf16 v[42:45], v[168:171], v[176:179], v[42:45]
	v_mfma_f32_16x16x32_bf16 v[34:37], v[160:163], v[184:187], v[34:37]
	v_mfma_f32_16x16x32_bf16 v[26:29], v[168:171], v[184:187], v[26:29]
	v_mfma_f32_16x16x32_bf16 v[18:21], v[160:163], v[196:199], v[18:21]
	v_mfma_f32_16x16x32_bf16 v[10:13], v[168:171], v[196:199], v[10:13]
	v_mfma_f32_16x16x32_bf16 v[6:9], v[160:163], v[204:207], v[6:9]
	v_mfma_f32_16x16x32_bf16 v[2:5], v[168:171], v[204:207], v[2:5]
	v_mfma_f32_16x16x32_bf16 v[50:53], v[164:167], v[180:183], v[50:53]
	v_mfma_f32_16x16x32_bf16 v[42:45], v[172:175], v[180:183], v[42:45]
	v_mfma_f32_16x16x32_bf16 v[34:37], v[164:167], v[188:191], v[34:37]
	v_mfma_f32_16x16x32_bf16 v[26:29], v[172:175], v[188:191], v[26:29]
	v_mfma_f32_16x16x32_bf16 v[18:21], v[164:167], v[200:203], v[18:21]
	v_mfma_f32_16x16x32_bf16 v[10:13], v[172:175], v[200:203], v[10:13]
	v_mfma_f32_16x16x32_bf16 v[6:9], v[164:167], v[208:211], v[6:9]
	v_mfma_f32_16x16x32_bf16 v[2:5], v[172:175], v[208:211], v[2:5]
	s_setprio 0
	s_barrier
	s_add_i32 s68, 0, 0x18000
	v_add_u32_e32 v143, s68, v1
	s_add_i32 s69, 0, 0x1c000
	ds_read_b128 v[144:147], v143
	ds_read_b128 v[148:151], v143 offset:1024
	ds_read_b128 v[152:155], v143 offset:2048
	ds_read_b128 v[156:159], v143 offset:3072
	v_add_u32_e32 v143, s69, v1
	ds_read_b128 v[160:163], v143
	ds_read_b128 v[164:167], v143 offset:1024
	ds_read_b128 v[168:171], v143 offset:2048
	ds_read_b128 v[172:175], v143 offset:3072
	s_add_u32 s46, s46, 0x100000
	s_addc_u32 s47, s47, 0
	s_mov_b32 m0, s53
	v_lshl_add_u64 v[218:219], s[46:47], 0, v[130:131]
	ds_read_b128 v[176:179], v142 offset:32768
	ds_read_b128 v[180:183], v142 offset:33792
	ds_read_b128 v[184:187], v142 offset:34816
	ds_read_b128 v[188:191], v142 offset:35840
	ds_read_b128 v[196:199], v142 offset:36864
	ds_read_b128 v[200:203], v142 offset:37888
	ds_read_b128 v[204:207], v142 offset:38912
	ds_read_b128 v[208:211], v142 offset:39936
	global_load_lds_dwordx4 v[218:219], off
	v_lshl_add_u64 v[218:219], s[46:47], 0, v[132:133]
	s_mov_b32 m0, s54
	s_nop 0
	global_load_lds_dwordx4 v[218:219], off
	s_waitcnt vmcnt(8)
	s_waitcnt lgkmcnt(0)
	s_barrier
	s_setprio 1
	v_mfma_f32_16x16x32_bf16 v[126:129], v[144:147], v[176:179], v[126:129]
	v_mfma_f32_16x16x32_bf16 v[122:125], v[152:155], v[176:179], v[122:125]
	v_mfma_f32_16x16x32_bf16 v[118:121], v[144:147], v[184:187], v[118:121]
	v_mfma_f32_16x16x32_bf16 v[110:113], v[152:155], v[184:187], v[110:113]
	v_mfma_f32_16x16x32_bf16 v[102:105], v[144:147], v[196:199], v[102:105]
	v_mfma_f32_16x16x32_bf16 v[94:97], v[152:155], v[196:199], v[94:97]
	v_mfma_f32_16x16x32_bf16 v[86:89], v[144:147], v[204:207], v[86:89]
	v_mfma_f32_16x16x32_bf16 v[78:81], v[152:155], v[204:207], v[78:81]
	v_mfma_f32_16x16x32_bf16 v[126:129], v[148:151], v[180:183], v[126:129]
	v_mfma_f32_16x16x32_bf16 v[122:125], v[156:159], v[180:183], v[122:125]
	v_mfma_f32_16x16x32_bf16 v[118:121], v[148:151], v[188:191], v[118:121]
	v_mfma_f32_16x16x32_bf16 v[110:113], v[156:159], v[188:191], v[110:113]
	v_mfma_f32_16x16x32_bf16 v[102:105], v[148:151], v[200:203], v[102:105]
	v_mfma_f32_16x16x32_bf16 v[94:97], v[156:159], v[200:203], v[94:97]
	v_mfma_f32_16x16x32_bf16 v[86:89], v[148:151], v[208:211], v[86:89]
	v_mfma_f32_16x16x32_bf16 v[78:81], v[156:159], v[208:211], v[78:81]
	v_mfma_f32_16x16x32_bf16 v[114:117], v[160:163], v[176:179], v[114:117]
	v_mfma_f32_16x16x32_bf16 v[106:109], v[168:171], v[176:179], v[106:109]
	v_mfma_f32_16x16x32_bf16 v[98:101], v[160:163], v[184:187], v[98:101]
	v_mfma_f32_16x16x32_bf16 v[90:93], v[168:171], v[184:187], v[90:93]
	v_mfma_f32_16x16x32_bf16 v[82:85], v[160:163], v[196:199], v[82:85]
	v_mfma_f32_16x16x32_bf16 v[74:77], v[168:171], v[196:199], v[74:77]
	v_mfma_f32_16x16x32_bf16 v[70:73], v[160:163], v[204:207], v[70:73]
	v_mfma_f32_16x16x32_bf16 v[66:69], v[168:171], v[204:207], v[66:69]
	v_mfma_f32_16x16x32_bf16 v[114:117], v[164:167], v[180:183], v[114:117]
	v_mfma_f32_16x16x32_bf16 v[106:109], v[172:175], v[180:183], v[106:109]
	v_mfma_f32_16x16x32_bf16 v[98:101], v[164:167], v[188:191], v[98:101]
	v_mfma_f32_16x16x32_bf16 v[90:93], v[172:175], v[188:191], v[90:93]
	v_mfma_f32_16x16x32_bf16 v[82:85], v[164:167], v[200:203], v[82:85]
	v_mfma_f32_16x16x32_bf16 v[74:77], v[172:175], v[200:203], v[74:77]
	v_mfma_f32_16x16x32_bf16 v[70:73], v[164:167], v[208:211], v[70:73]
	v_mfma_f32_16x16x32_bf16 v[66:69], v[172:175], v[208:211], v[66:69]
	s_setprio 0
	s_barrier
	s_add_i32 s46, s68, s51
	v_lshl_add_u64 v[192:193], v[192:193], 0, s[10:11]
	s_mov_b32 m0, s46
	ds_read_b128 v[176:179], v142 offset:49152
	ds_read_b128 v[180:183], v142 offset:50176
	ds_read_b128 v[184:187], v142 offset:51200
	ds_read_b128 v[188:191], v142 offset:52224
	ds_read_b128 v[196:199], v142 offset:53248
	ds_read_b128 v[200:203], v142 offset:54272
	ds_read_b128 v[204:207], v142 offset:55296
	ds_read_b128 v[208:211], v142 offset:56320
	global_load_lds_dwordx4 v[192:193], off
	s_add_i32 m0, s46, 0x2000
	s_add_u32 s42, s42, 0x100080
	v_lshl_add_u64 v[192:193], v[212:213], 0, s[10:11]
	s_addc_u32 s43, s43, 0
	s_add_i32 s46, s69, s51
	global_load_lds_dwordx4 v[192:193], off
	v_lshl_add_u64 v[192:193], s[42:43], 0, v[130:131]
	s_mov_b32 m0, s46
	s_nop 0
	global_load_lds_dwordx4 v[192:193], off
	v_lshl_add_u64 v[192:193], s[42:43], 0, v[132:133]
	s_add_i32 m0, s46, 0x2000
	s_nop 0
	global_load_lds_dwordx4 v[192:193], off
	v_lshl_add_u64 v[192:193], v[214:215], 0, s[10:11]
	s_mov_b32 m0, s56
	s_nop 0
	global_load_lds_dwordx4 v[192:193], off
	v_lshl_add_u64 v[192:193], v[216:217], 0, s[10:11]
	s_mov_b32 m0, s57
	s_nop 0
	global_load_lds_dwordx4 v[192:193], off
	s_nop 0
	s_waitcnt vmcnt(8)
	s_waitcnt lgkmcnt(0)
	s_barrier
	s_setprio 1
	v_mfma_f32_16x16x32_bf16 v[62:65], v[144:147], v[176:179], v[62:65]
	v_mfma_f32_16x16x32_bf16 v[58:61], v[152:155], v[176:179], v[58:61]
	v_mfma_f32_16x16x32_bf16 v[54:57], v[144:147], v[184:187], v[54:57]
	v_mfma_f32_16x16x32_bf16 v[46:49], v[152:155], v[184:187], v[46:49]
	v_mfma_f32_16x16x32_bf16 v[38:41], v[144:147], v[196:199], v[38:41]
	v_mfma_f32_16x16x32_bf16 v[30:33], v[152:155], v[196:199], v[30:33]
	v_mfma_f32_16x16x32_bf16 v[22:25], v[144:147], v[204:207], v[22:25]
	v_mfma_f32_16x16x32_bf16 v[14:17], v[152:155], v[204:207], v[14:17]
	v_mfma_f32_16x16x32_bf16 v[62:65], v[148:151], v[180:183], v[62:65]
	v_mfma_f32_16x16x32_bf16 v[58:61], v[156:159], v[180:183], v[58:61]
	v_mfma_f32_16x16x32_bf16 v[54:57], v[148:151], v[188:191], v[54:57]
	v_mfma_f32_16x16x32_bf16 v[46:49], v[156:159], v[188:191], v[46:49]
	v_mfma_f32_16x16x32_bf16 v[38:41], v[148:151], v[200:203], v[38:41]
	v_mfma_f32_16x16x32_bf16 v[30:33], v[156:159], v[200:203], v[30:33]
	v_mfma_f32_16x16x32_bf16 v[22:25], v[148:151], v[208:211], v[22:25]
	v_mfma_f32_16x16x32_bf16 v[14:17], v[156:159], v[208:211], v[14:17]
	v_mfma_f32_16x16x32_bf16 v[50:53], v[160:163], v[176:179], v[50:53]
	v_mfma_f32_16x16x32_bf16 v[42:45], v[168:171], v[176:179], v[42:45]
	v_mfma_f32_16x16x32_bf16 v[34:37], v[160:163], v[184:187], v[34:37]
	v_mfma_f32_16x16x32_bf16 v[26:29], v[168:171], v[184:187], v[26:29]
	v_mfma_f32_16x16x32_bf16 v[18:21], v[160:163], v[196:199], v[18:21]
	v_mfma_f32_16x16x32_bf16 v[10:13], v[168:171], v[196:199], v[10:13]
	v_mfma_f32_16x16x32_bf16 v[6:9], v[160:163], v[204:207], v[6:9]
	v_mfma_f32_16x16x32_bf16 v[2:5], v[168:171], v[204:207], v[2:5]
	v_mfma_f32_16x16x32_bf16 v[50:53], v[164:167], v[180:183], v[50:53]
	v_mfma_f32_16x16x32_bf16 v[42:45], v[172:175], v[180:183], v[42:45]
	v_mfma_f32_16x16x32_bf16 v[34:37], v[164:167], v[188:191], v[34:37]
	v_mfma_f32_16x16x32_bf16 v[26:29], v[172:175], v[188:191], v[26:29]
	v_mfma_f32_16x16x32_bf16 v[18:21], v[164:167], v[200:203], v[18:21]
	v_mfma_f32_16x16x32_bf16 v[10:13], v[172:175], v[200:203], v[10:13]
	v_mfma_f32_16x16x32_bf16 v[6:9], v[164:167], v[208:211], v[6:9]
	v_mfma_f32_16x16x32_bf16 v[2:5], v[172:175], v[208:211], v[2:5]
	s_setprio 0
	s_barrier
	s_add_i32 s67, s67, 2
	s_add_u32 s40, s40, 0x100
	s_addc_u32 s41, s41, 0
	s_add_u32 s65, s65, 0x100
	s_addc_u32 s66, s66, 0
	s_cmp_gt_u32 s67, 61
	s_cbranch_scc0 .LBB0_705
	s_and_b64 vcc, exec, s[12:13]
	s_cbranch_vccz .LBB0_708
	s_barrier

.LBB0_967:
	ds_read_b128 v[146:149], v152
	ds_read_b128 v[156:159], v152 offset:1024
	ds_read_b128 v[160:163], v152 offset:2048
	ds_read_b128 v[164:167], v152 offset:3072
	ds_read_b128 v[168:171], v153
	ds_read_b128 v[172:175], v153 offset:1024
	ds_read_b128 v[176:179], v153 offset:2048
	ds_read_b128 v[180:183], v153 offset:3072
	s_add_u32 s30, s28, 0xfff80080
	s_addc_u32 s31, s29, -1
	s_cmp_eq_u32 s57, 28
	s_cselect_b32 s35, s21, s31
	s_cselect_b32 s34, s53, s30
	s_cselect_b32 s31, s19, s56
	s_cselect_b32 s30, s54, s55
	v_lshl_add_u64 v[192:193], s[28:29], 0, v[138:139]
	s_add_i32 m0, s27, 0xc000
	ds_read_b128 v[184:187], v154
	ds_read_b128 v[188:191], v154 offset:1024
	ds_read_b128 v[196:199], v154 offset:2048
	ds_read_b128 v[200:203], v154 offset:3072
	ds_read_b128 v[206:209], v154 offset:4096
	ds_read_b128 v[210:213], v154 offset:5120
	ds_read_b128 v[214:217], v154 offset:6144
	ds_read_b128 v[218:221], v154 offset:7168
	global_load_lds_dwordx4 v[192:193], off
	v_lshl_add_u64 v[192:193], s[28:29], 0, v[140:141]
	s_add_i32 m0, s27, 0xe000
	s_nop 0
	global_load_lds_dwordx4 v[192:193], off
	s_nop 0
	s_waitcnt vmcnt(8)
	s_waitcnt lgkmcnt(0)
	s_barrier
	s_setprio 1
	v_mfma_f32_16x16x32_bf16 v[126:129], v[146:149], v[184:187], v[126:129]
	v_mfma_f32_16x16x32_bf16 v[122:125], v[160:163], v[184:187], v[122:125]
	v_mfma_f32_16x16x32_bf16 v[110:113], v[146:149], v[196:199], v[110:113]
	v_mfma_f32_16x16x32_bf16 v[106:109], v[160:163], v[196:199], v[106:109]
	v_mfma_f32_16x16x32_bf16 v[98:101], v[146:149], v[206:209], v[98:101]
	v_mfma_f32_16x16x32_bf16 v[90:93], v[160:163], v[206:209], v[90:93]
	v_mfma_f32_16x16x32_bf16 v[78:81], v[146:149], v[214:217], v[78:81]
	v_mfma_f32_16x16x32_bf16 v[74:77], v[160:163], v[214:217], v[74:77]
	v_mfma_f32_16x16x32_bf16 v[126:129], v[156:159], v[188:191], v[126:129]
	v_mfma_f32_16x16x32_bf16 v[122:125], v[164:167], v[188:191], v[122:125]
	v_mfma_f32_16x16x32_bf16 v[110:113], v[156:159], v[200:203], v[110:113]
	v_mfma_f32_16x16x32_bf16 v[106:109], v[164:167], v[200:203], v[106:109]
	v_mfma_f32_16x16x32_bf16 v[98:101], v[156:159], v[210:213], v[98:101]
	v_mfma_f32_16x16x32_bf16 v[90:93], v[164:167], v[210:213], v[90:93]
	v_mfma_f32_16x16x32_bf16 v[78:81], v[156:159], v[218:221], v[78:81]
	v_mfma_f32_16x16x32_bf16 v[74:77], v[164:167], v[218:221], v[74:77]
	v_mfma_f32_16x16x32_bf16 v[118:121], v[168:171], v[184:187], v[118:121]
	v_mfma_f32_16x16x32_bf16 v[114:117], v[176:179], v[184:187], v[114:117]
	v_mfma_f32_16x16x32_bf16 v[102:105], v[168:171], v[196:199], v[102:105]
	v_mfma_f32_16x16x32_bf16 v[94:97], v[176:179], v[196:199], v[94:97]
	v_mfma_f32_16x16x32_bf16 v[86:89], v[168:171], v[206:209], v[86:89]
	v_mfma_f32_16x16x32_bf16 v[82:85], v[176:179], v[206:209], v[82:85]
	v_mfma_f32_16x16x32_bf16 v[70:73], v[168:171], v[214:217], v[70:73]
	v_mfma_f32_16x16x32_bf16 v[66:69], v[176:179], v[214:217], v[66:69]
	v_mfma_f32_16x16x32_bf16 v[118:121], v[172:175], v[188:191], v[118:121]
	v_mfma_f32_16x16x32_bf16 v[114:117], v[180:183], v[188:191], v[114:117]
	v_mfma_f32_16x16x32_bf16 v[102:105], v[172:175], v[200:203], v[102:105]
	v_mfma_f32_16x16x32_bf16 v[94:97], v[180:183], v[200:203], v[94:97]
	v_mfma_f32_16x16x32_bf16 v[86:89], v[172:175], v[210:213], v[86:89]
	v_mfma_f32_16x16x32_bf16 v[82:85], v[180:183], v[210:213], v[82:85]
	v_mfma_f32_16x16x32_bf16 v[70:73], v[172:175], v[218:221], v[70:73]
	v_mfma_f32_16x16x32_bf16 v[66:69], v[180:183], v[218:221], v[66:69]
	s_setprio 0
	s_barrier
	s_add_i32 s58, s50, s40
	v_lshl_add_u64 v[192:193], s[30:31], 0, v[134:135]
	s_mov_b32 m0, s58
	ds_read_b128 v[184:187], v154 offset:16384
	ds_read_b128 v[188:191], v154 offset:17408
	ds_read_b128 v[196:199], v154 offset:18432
	ds_read_b128 v[200:203], v154 offset:19456
	ds_read_b128 v[206:209], v154 offset:20480
	ds_read_b128 v[210:213], v154 offset:21504
	ds_read_b128 v[214:217], v154 offset:22528
	ds_read_b128 v[218:221], v154 offset:23552
	global_load_lds_dwordx4 v[192:193], off
	s_add_i32 m0, s58, 0x2000
	s_add_u32 s58, s30, 0x80000
	v_lshl_add_u64 v[222:223], s[30:31], 0, v[130:131]
	s_addc_u32 s59, s31, 0
	s_add_i32 s60, s51, s40
	global_load_lds_dwordx4 v[222:223], off
	v_lshl_add_u64 v[224:225], s[58:59], 0, v[134:135]
	s_mov_b32 m0, s60
	v_lshl_add_u64 v[226:227], s[34:35], 0, v[132:133]
	global_load_lds_dwordx4 v[224:225], off
	v_lshl_add_u64 v[224:225], s[58:59], 0, v[130:131]
	s_add_i32 m0, s60, 0x2000
	s_nop 0
	global_load_lds_dwordx4 v[224:225], off
	v_lshl_add_u64 v[224:225], s[34:35], 0, v[136:137]
	s_mov_b32 m0, s27
	s_nop 0
	global_load_lds_dwordx4 v[224:225], off
	s_mov_b32 m0, s42
	s_nop 0
	global_load_lds_dwordx4 v[226:227], off
	s_waitcnt vmcnt(8)
	s_waitcnt lgkmcnt(0)
	s_barrier
	s_setprio 1
	v_mfma_f32_16x16x32_bf16 v[62:65], v[146:149], v[184:187], v[62:65]
	v_mfma_f32_16x16x32_bf16 v[58:61], v[160:163], v[184:187], v[58:61]
	v_mfma_f32_16x16x32_bf16 v[46:49], v[146:149], v[196:199], v[46:49]
	v_mfma_f32_16x16x32_bf16 v[42:45], v[160:163], v[196:199], v[42:45]
	v_mfma_f32_16x16x32_bf16 v[30:33], v[146:149], v[206:209], v[30:33]
	v_mfma_f32_16x16x32_bf16 v[26:29], v[160:163], v[206:209], v[26:29]
	v_mfma_f32_16x16x32_bf16 v[14:17], v[146:149], v[214:217], v[14:17]
	v_mfma_f32_16x16x32_bf16 v[10:13], v[160:163], v[214:217], v[10:13]
	v_mfma_f32_16x16x32_bf16 v[62:65], v[156:159], v[188:191], v[62:65]
	v_mfma_f32_16x16x32_bf16 v[58:61], v[164:167], v[188:191], v[58:61]
	v_mfma_f32_16x16x32_bf16 v[46:49], v[156:159], v[200:203], v[46:49]
	v_mfma_f32_16x16x32_bf16 v[42:45], v[164:167], v[200:203], v[42:45]
	v_mfma_f32_16x16x32_bf16 v[30:33], v[156:159], v[210:213], v[30:33]
	v_mfma_f32_16x16x32_bf16 v[26:29], v[164:167], v[210:213], v[26:29]
	v_mfma_f32_16x16x32_bf16 v[14:17], v[156:159], v[218:221], v[14:17]
	v_mfma_f32_16x16x32_bf16 v[10:13], v[164:167], v[218:221], v[10:13]
	v_mfma_f32_16x16x32_bf16 v[54:57], v[168:171], v[184:187], v[54:57]
	v_mfma_f32_16x16x32_bf16 v[50:53], v[176:179], v[184:187], v[50:53]
	v_mfma_f32_16x16x32_bf16 v[38:41], v[168:171], v[196:199], v[38:41]
	v_mfma_f32_16x16x32_bf16 v[34:37], v[176:179], v[196:199], v[34:37]
	v_mfma_f32_16x16x32_bf16 v[22:25], v[168:171], v[206:209], v[22:25]
	v_mfma_f32_16x16x32_bf16 v[18:21], v[176:179], v[206:209], v[18:21]
	v_mfma_f32_16x16x32_bf16 v[6:9], v[168:171], v[214:217], v[6:9]
	v_mfma_f32_16x16x32_bf16 v[2:5], v[176:179], v[214:217], v[2:5]
	v_mfma_f32_16x16x32_bf16 v[54:57], v[172:175], v[188:191], v[54:57]
	v_mfma_f32_16x16x32_bf16 v[50:53], v[180:183], v[188:191], v[50:53]
	v_mfma_f32_16x16x32_bf16 v[38:41], v[172:175], v[200:203], v[38:41]
	v_mfma_f32_16x16x32_bf16 v[34:37], v[180:183], v[200:203], v[34:37]
	v_mfma_f32_16x16x32_bf16 v[22:25], v[172:175], v[210:213], v[22:25]
	v_mfma_f32_16x16x32_bf16 v[18:21], v[180:183], v[210:213], v[18:21]
	v_mfma_f32_16x16x32_bf16 v[6:9], v[172:175], v[218:221], v[6:9]
	v_mfma_f32_16x16x32_bf16 v[2:5], v[180:183], v[218:221], v[2:5]
	s_setprio 0
	s_barrier
	s_add_i32 s58, 0, 0x18000
	v_add_u32_e32 v155, s58, v150
	s_add_i32 s59, 0, 0x1c000
	ds_read_b128 v[146:149], v155
	ds_read_b128 v[156:159], v155 offset:1024
	ds_read_b128 v[160:163], v155 offset:2048
	ds_read_b128 v[164:167], v155 offset:3072
	v_add_u32_e32 v155, s59, v150
	ds_read_b128 v[168:171], v155
	ds_read_b128 v[172:175], v155 offset:1024
	ds_read_b128 v[176:179], v155 offset:2048
	ds_read_b128 v[180:183], v155 offset:3072
	s_add_u32 s34, s34, 0x80000
	s_addc_u32 s35, s35, 0
	s_mov_b32 m0, s43
	v_lshl_add_u64 v[228:229], s[34:35], 0, v[136:137]
	ds_read_b128 v[184:187], v154 offset:32768
	ds_read_b128 v[188:191], v154 offset:33792
	ds_read_b128 v[196:199], v154 offset:34816
	ds_read_b128 v[200:203], v154 offset:35840
	ds_read_b128 v[206:209], v154 offset:36864
	ds_read_b128 v[210:213], v154 offset:37888
	ds_read_b128 v[214:217], v154 offset:38912
	ds_read_b128 v[218:221], v154 offset:39936
	global_load_lds_dwordx4 v[228:229], off
	v_lshl_add_u64 v[228:229], s[34:35], 0, v[132:133]
	s_mov_b32 m0, s45
	s_nop 0
	global_load_lds_dwordx4 v[228:229], off
	s_waitcnt vmcnt(8)
	s_waitcnt lgkmcnt(0)
	s_barrier
	s_setprio 1
	v_mfma_f32_16x16x32_bf16 v[126:129], v[146:149], v[184:187], v[126:129]
	v_mfma_f32_16x16x32_bf16 v[122:125], v[160:163], v[184:187], v[122:125]
	v_mfma_f32_16x16x32_bf16 v[110:113], v[146:149], v[196:199], v[110:113]
	v_mfma_f32_16x16x32_bf16 v[106:109], v[160:163], v[196:199], v[106:109]
	v_mfma_f32_16x16x32_bf16 v[98:101], v[146:149], v[206:209], v[98:101]
	v_mfma_f32_16x16x32_bf16 v[90:93], v[160:163], v[206:209], v[90:93]
	v_mfma_f32_16x16x32_bf16 v[78:81], v[146:149], v[214:217], v[78:81]
	v_mfma_f32_16x16x32_bf16 v[74:77], v[160:163], v[214:217], v[74:77]
	v_mfma_f32_16x16x32_bf16 v[126:129], v[156:159], v[188:191], v[126:129]
	v_mfma_f32_16x16x32_bf16 v[122:125], v[164:167], v[188:191], v[122:125]
	v_mfma_f32_16x16x32_bf16 v[110:113], v[156:159], v[200:203], v[110:113]
	v_mfma_f32_16x16x32_bf16 v[106:109], v[164:167], v[200:203], v[106:109]
	v_mfma_f32_16x16x32_bf16 v[98:101], v[156:159], v[210:213], v[98:101]
	v_mfma_f32_16x16x32_bf16 v[90:93], v[164:167], v[210:213], v[90:93]
	v_mfma_f32_16x16x32_bf16 v[78:81], v[156:159], v[218:221], v[78:81]
	v_mfma_f32_16x16x32_bf16 v[74:77], v[164:167], v[218:221], v[74:77]
	v_mfma_f32_16x16x32_bf16 v[118:121], v[168:171], v[184:187], v[118:121]
	v_mfma_f32_16x16x32_bf16 v[114:117], v[176:179], v[184:187], v[114:117]
	v_mfma_f32_16x16x32_bf16 v[102:105], v[168:171], v[196:199], v[102:105]
	v_mfma_f32_16x16x32_bf16 v[94:97], v[176:179], v[196:199], v[94:97]
	v_mfma_f32_16x16x32_bf16 v[86:89], v[168:171], v[206:209], v[86:89]
	v_mfma_f32_16x16x32_bf16 v[82:85], v[176:179], v[206:209], v[82:85]
	v_mfma_f32_16x16x32_bf16 v[70:73], v[168:171], v[214:217], v[70:73]
	v_mfma_f32_16x16x32_bf16 v[66:69], v[176:179], v[214:217], v[66:69]
	v_mfma_f32_16x16x32_bf16 v[118:121], v[172:175], v[188:191], v[118:121]
	v_mfma_f32_16x16x32_bf16 v[114:117], v[180:183], v[188:191], v[114:117]
	v_mfma_f32_16x16x32_bf16 v[102:105], v[172:175], v[200:203], v[102:105]
	v_mfma_f32_16x16x32_bf16 v[94:97], v[180:183], v[200:203], v[94:97]
	v_mfma_f32_16x16x32_bf16 v[86:89], v[172:175], v[210:213], v[86:89]
	v_mfma_f32_16x16x32_bf16 v[82:85], v[180:183], v[210:213], v[82:85]
	v_mfma_f32_16x16x32_bf16 v[70:73], v[172:175], v[218:221], v[70:73]
	v_mfma_f32_16x16x32_bf16 v[66:69], v[180:183], v[218:221], v[66:69]
	s_setprio 0
	s_barrier
	s_add_i32 s34, s58, s40
	v_lshl_add_u64 v[192:193], v[192:193], 0, s[14:15]
	s_mov_b32 m0, s34
	ds_read_b128 v[184:187], v154 offset:49152
	ds_read_b128 v[188:191], v154 offset:50176
	ds_read_b128 v[196:199], v154 offset:51200
	ds_read_b128 v[200:203], v154 offset:52224
	ds_read_b128 v[206:209], v154 offset:53248
	ds_read_b128 v[210:213], v154 offset:54272
	ds_read_b128 v[214:217], v154 offset:55296
	ds_read_b128 v[218:221], v154 offset:56320
	global_load_lds_dwordx4 v[192:193], off
	s_add_i32 m0, s34, 0x2000
	s_add_u32 s30, s30, 0x80080
	v_lshl_add_u64 v[192:193], v[222:223], 0, s[14:15]
	s_addc_u32 s31, s31, 0
	s_add_i32 s34, s59, s40
	global_load_lds_dwordx4 v[192:193], off
	v_lshl_add_u64 v[192:193], s[30:31], 0, v[134:135]
	s_mov_b32 m0, s34
	s_nop 0
	global_load_lds_dwordx4 v[192:193], off
	v_lshl_add_u64 v[192:193], s[30:31], 0, v[130:131]
	s_add_i32 m0, s34, 0x2000
	s_nop 0
	global_load_lds_dwordx4 v[192:193], off
	v_lshl_add_u64 v[192:193], v[224:225], 0, s[14:15]
	s_mov_b32 m0, s47
	s_nop 0
	global_load_lds_dwordx4 v[192:193], off
	v_lshl_add_u64 v[192:193], v[226:227], 0, s[14:15]
	s_mov_b32 m0, s48
	s_nop 0
	global_load_lds_dwordx4 v[192:193], off
	s_nop 0
	s_waitcnt vmcnt(8)
	s_waitcnt lgkmcnt(0)
	s_barrier
	s_setprio 1
	v_mfma_f32_16x16x32_bf16 v[62:65], v[146:149], v[184:187], v[62:65]
	v_mfma_f32_16x16x32_bf16 v[58:61], v[160:163], v[184:187], v[58:61]
	v_mfma_f32_16x16x32_bf16 v[46:49], v[146:149], v[196:199], v[46:49]
	v_mfma_f32_16x16x32_bf16 v[42:45], v[160:163], v[196:199], v[42:45]
	v_mfma_f32_16x16x32_bf16 v[30:33], v[146:149], v[206:209], v[30:33]
	v_mfma_f32_16x16x32_bf16 v[26:29], v[160:163], v[206:209], v[26:29]
	v_mfma_f32_16x16x32_bf16 v[14:17], v[146:149], v[214:217], v[14:17]
	v_mfma_f32_16x16x32_bf16 v[10:13], v[160:163], v[214:217], v[10:13]
	v_mfma_f32_16x16x32_bf16 v[62:65], v[156:159], v[188:191], v[62:65]
	v_mfma_f32_16x16x32_bf16 v[58:61], v[164:167], v[188:191], v[58:61]
	v_mfma_f32_16x16x32_bf16 v[46:49], v[156:159], v[200:203], v[46:49]
	v_mfma_f32_16x16x32_bf16 v[42:45], v[164:167], v[200:203], v[42:45]
	v_mfma_f32_16x16x32_bf16 v[30:33], v[156:159], v[210:213], v[30:33]
	v_mfma_f32_16x16x32_bf16 v[26:29], v[164:167], v[210:213], v[26:29]
	v_mfma_f32_16x16x32_bf16 v[14:17], v[156:159], v[218:221], v[14:17]
	v_mfma_f32_16x16x32_bf16 v[10:13], v[164:167], v[218:221], v[10:13]
	v_mfma_f32_16x16x32_bf16 v[54:57], v[168:171], v[184:187], v[54:57]
	v_mfma_f32_16x16x32_bf16 v[50:53], v[176:179], v[184:187], v[50:53]
	v_mfma_f32_16x16x32_bf16 v[38:41], v[168:171], v[196:199], v[38:41]
	v_mfma_f32_16x16x32_bf16 v[34:37], v[176:179], v[196:199], v[34:37]
	v_mfma_f32_16x16x32_bf16 v[22:25], v[168:171], v[206:209], v[22:25]
	v_mfma_f32_16x16x32_bf16 v[18:21], v[176:179], v[206:209], v[18:21]
	v_mfma_f32_16x16x32_bf16 v[6:9], v[168:171], v[214:217], v[6:9]
	v_mfma_f32_16x16x32_bf16 v[2:5], v[176:179], v[214:217], v[2:5]
	v_mfma_f32_16x16x32_bf16 v[54:57], v[172:175], v[188:191], v[54:57]
	v_mfma_f32_16x16x32_bf16 v[50:53], v[180:183], v[188:191], v[50:53]
	v_mfma_f32_16x16x32_bf16 v[38:41], v[172:175], v[200:203], v[38:41]
	v_mfma_f32_16x16x32_bf16 v[34:37], v[180:183], v[200:203], v[34:37]
	v_mfma_f32_16x16x32_bf16 v[22:25], v[172:175], v[210:213], v[22:25]
	v_mfma_f32_16x16x32_bf16 v[18:21], v[180:183], v[210:213], v[18:21]
	v_mfma_f32_16x16x32_bf16 v[6:9], v[172:175], v[218:221], v[6:9]
	v_mfma_f32_16x16x32_bf16 v[2:5], v[180:183], v[218:221], v[2:5]
	s_setprio 0
	s_barrier
	s_add_i32 s57, s57, 2
	s_add_u32 s28, s28, 0x100
	s_addc_u32 s29, s29, 0
	s_add_u32 s55, s55, 0x100
	s_addc_u32 s56, s56, 0
	s_cmp_gt_u32 s57, 29
	s_cbranch_scc0 .LBB0_967
	s_and_b64 vcc, exec, s[16:17]
	s_cbranch_vccz .LBB0_970
	s_barrier

.LBB0_1057:
	ds_read_b128 v[150:153], v158
	ds_read_b128 v[162:165], v158 offset:1024
	ds_read_b128 v[166:169], v158 offset:2048
	ds_read_b128 v[170:173], v158 offset:3072
	ds_read_b128 v[174:177], v159
	ds_read_b128 v[178:181], v159 offset:1024
	ds_read_b128 v[182:185], v159 offset:2048
	ds_read_b128 v[186:189], v159 offset:3072
	s_add_i32 s84, s48, 2
	s_add_u32 s49, s62, 0xfff00080
	s_addc_u32 s64, s63, -1
	s_cmp_eq_u32 s51, s48
	s_cselect_b32 s48, s56, s53
	s_cselect_b32 s65, s9, s64
	s_cselect_b32 s64, s8, s49
	s_cselect_b32 s49, s57, s55
	v_lshl_add_u64 v[154:155], s[62:63], 0, v[138:139]
	s_add_i32 m0, s59, 0xc000
	ds_read_b128 v[190:193], v160
	ds_read_b128 v[196:199], v160 offset:1024
	ds_read_b128 v[200:203], v160 offset:2048
	ds_read_b128 v[206:209], v160 offset:3072
	ds_read_b128 v[210:213], v160 offset:4096
	ds_read_b128 v[214:217], v160 offset:5120
	ds_read_b128 v[218:221], v160 offset:6144
	ds_read_b128 v[222:225], v160 offset:7168
	global_load_lds_dwordx4 v[154:155], off
	v_lshl_add_u64 v[154:155], s[62:63], 0, v[140:141]
	s_add_i32 m0, s59, 0xe000
	s_nop 0
	global_load_lds_dwordx4 v[154:155], off
	s_nop 0
	s_waitcnt vmcnt(8)
	s_waitcnt lgkmcnt(0)
	s_barrier
	s_setprio 1
	v_mfma_f32_16x16x32_bf16 v[126:129], v[150:153], v[190:193], v[126:129]
	v_mfma_f32_16x16x32_bf16 v[122:125], v[166:169], v[190:193], v[122:125]
	v_mfma_f32_16x16x32_bf16 v[110:113], v[150:153], v[200:203], v[110:113]
	v_mfma_f32_16x16x32_bf16 v[106:109], v[166:169], v[200:203], v[106:109]
	v_mfma_f32_16x16x32_bf16 v[94:97], v[150:153], v[210:213], v[94:97]
	v_mfma_f32_16x16x32_bf16 v[90:93], v[166:169], v[210:213], v[90:93]
	v_mfma_f32_16x16x32_bf16 v[78:81], v[150:153], v[218:221], v[78:81]
	v_mfma_f32_16x16x32_bf16 v[74:77], v[166:169], v[218:221], v[74:77]
	v_mfma_f32_16x16x32_bf16 v[126:129], v[162:165], v[196:199], v[126:129]
	v_mfma_f32_16x16x32_bf16 v[122:125], v[170:173], v[196:199], v[122:125]
	v_mfma_f32_16x16x32_bf16 v[110:113], v[162:165], v[206:209], v[110:113]
	v_mfma_f32_16x16x32_bf16 v[106:109], v[170:173], v[206:209], v[106:109]
	v_mfma_f32_16x16x32_bf16 v[94:97], v[162:165], v[214:217], v[94:97]
	v_mfma_f32_16x16x32_bf16 v[90:93], v[170:173], v[214:217], v[90:93]
	v_mfma_f32_16x16x32_bf16 v[78:81], v[162:165], v[222:225], v[78:81]
	v_mfma_f32_16x16x32_bf16 v[74:77], v[170:173], v[222:225], v[74:77]
	v_mfma_f32_16x16x32_bf16 v[118:121], v[174:177], v[190:193], v[118:121]
	v_mfma_f32_16x16x32_bf16 v[114:117], v[182:185], v[190:193], v[114:117]
	v_mfma_f32_16x16x32_bf16 v[102:105], v[174:177], v[200:203], v[102:105]
	v_mfma_f32_16x16x32_bf16 v[98:101], v[182:185], v[200:203], v[98:101]
	v_mfma_f32_16x16x32_bf16 v[86:89], v[174:177], v[210:213], v[86:89]
	v_mfma_f32_16x16x32_bf16 v[82:85], v[182:185], v[210:213], v[82:85]
	v_mfma_f32_16x16x32_bf16 v[70:73], v[174:177], v[218:221], v[70:73]
	v_mfma_f32_16x16x32_bf16 v[66:69], v[182:185], v[218:221], v[66:69]
	v_mfma_f32_16x16x32_bf16 v[118:121], v[178:181], v[196:199], v[118:121]
	v_mfma_f32_16x16x32_bf16 v[114:117], v[186:189], v[196:199], v[114:117]
	v_mfma_f32_16x16x32_bf16 v[102:105], v[178:181], v[206:209], v[102:105]
	v_mfma_f32_16x16x32_bf16 v[98:101], v[186:189], v[206:209], v[98:101]
	v_mfma_f32_16x16x32_bf16 v[86:89], v[178:181], v[214:217], v[86:89]
	v_mfma_f32_16x16x32_bf16 v[82:85], v[186:189], v[214:217], v[82:85]
	v_mfma_f32_16x16x32_bf16 v[70:73], v[178:181], v[222:225], v[70:73]
	v_mfma_f32_16x16x32_bf16 v[66:69], v[186:189], v[222:225], v[66:69]
	s_setprio 0
	s_barrier
	s_add_i32 s85, s75, s66
	v_lshl_add_u64 v[154:155], s[48:49], 0, v[132:133]
	s_mov_b32 m0, s85
	ds_read_b128 v[190:193], v160 offset:16384
	ds_read_b128 v[196:199], v160 offset:17408
	ds_read_b128 v[200:203], v160 offset:18432
	ds_read_b128 v[206:209], v160 offset:19456
	ds_read_b128 v[210:213], v160 offset:20480
	ds_read_b128 v[214:217], v160 offset:21504
	ds_read_b128 v[218:221], v160 offset:22528
	ds_read_b128 v[222:225], v160 offset:23552
	global_load_lds_dwordx4 v[154:155], off
	s_add_i32 m0, s85, 0x2000
	s_add_u32 s86, s48, 0x100000
	v_lshl_add_u64 v[226:227], s[48:49], 0, v[136:137]
	s_addc_u32 s87, s49, 0
	s_add_i32 s85, s76, s66
	global_load_lds_dwordx4 v[226:227], off
	v_lshl_add_u64 v[228:229], s[86:87], 0, v[132:133]
	s_mov_b32 m0, s85
	v_lshl_add_u64 v[230:231], s[64:65], 0, v[134:135]
	global_load_lds_dwordx4 v[228:229], off
	v_lshl_add_u64 v[228:229], s[86:87], 0, v[136:137]
	s_add_i32 m0, s85, 0x2000
	s_nop 0
	global_load_lds_dwordx4 v[228:229], off
	v_lshl_add_u64 v[228:229], s[64:65], 0, v[130:131]
	s_mov_b32 m0, s59
	s_nop 0
	global_load_lds_dwordx4 v[228:229], off
	s_mov_b32 m0, s61
	s_nop 0
	global_load_lds_dwordx4 v[230:231], off
	s_waitcnt vmcnt(8)
	s_waitcnt lgkmcnt(0)
	s_barrier
	s_setprio 1
	v_mfma_f32_16x16x32_bf16 v[62:65], v[150:153], v[190:193], v[62:65]
	v_mfma_f32_16x16x32_bf16 v[58:61], v[166:169], v[190:193], v[58:61]
	v_mfma_f32_16x16x32_bf16 v[46:49], v[150:153], v[200:203], v[46:49]
	v_mfma_f32_16x16x32_bf16 v[42:45], v[166:169], v[200:203], v[42:45]
	v_mfma_f32_16x16x32_bf16 v[30:33], v[150:153], v[210:213], v[30:33]
	v_mfma_f32_16x16x32_bf16 v[26:29], v[166:169], v[210:213], v[26:29]
	v_mfma_f32_16x16x32_bf16 v[14:17], v[150:153], v[218:221], v[14:17]
	v_mfma_f32_16x16x32_bf16 v[10:13], v[166:169], v[218:221], v[10:13]
	v_mfma_f32_16x16x32_bf16 v[62:65], v[162:165], v[196:199], v[62:65]
	v_mfma_f32_16x16x32_bf16 v[58:61], v[170:173], v[196:199], v[58:61]
	v_mfma_f32_16x16x32_bf16 v[46:49], v[162:165], v[206:209], v[46:49]
	v_mfma_f32_16x16x32_bf16 v[42:45], v[170:173], v[206:209], v[42:45]
	v_mfma_f32_16x16x32_bf16 v[30:33], v[162:165], v[214:217], v[30:33]
	v_mfma_f32_16x16x32_bf16 v[26:29], v[170:173], v[214:217], v[26:29]
	v_mfma_f32_16x16x32_bf16 v[14:17], v[162:165], v[222:225], v[14:17]
	v_mfma_f32_16x16x32_bf16 v[10:13], v[170:173], v[222:225], v[10:13]
	v_mfma_f32_16x16x32_bf16 v[54:57], v[174:177], v[190:193], v[54:57]
	v_mfma_f32_16x16x32_bf16 v[50:53], v[182:185], v[190:193], v[50:53]
	v_mfma_f32_16x16x32_bf16 v[38:41], v[174:177], v[200:203], v[38:41]
	v_mfma_f32_16x16x32_bf16 v[34:37], v[182:185], v[200:203], v[34:37]
	v_mfma_f32_16x16x32_bf16 v[22:25], v[174:177], v[210:213], v[22:25]
	v_mfma_f32_16x16x32_bf16 v[18:21], v[182:185], v[210:213], v[18:21]
	v_mfma_f32_16x16x32_bf16 v[6:9], v[174:177], v[218:221], v[6:9]
	v_mfma_f32_16x16x32_bf16 v[2:5], v[182:185], v[218:221], v[2:5]
	v_mfma_f32_16x16x32_bf16 v[54:57], v[178:181], v[196:199], v[54:57]
	v_mfma_f32_16x16x32_bf16 v[50:53], v[186:189], v[196:199], v[50:53]
	v_mfma_f32_16x16x32_bf16 v[38:41], v[178:181], v[206:209], v[38:41]
	v_mfma_f32_16x16x32_bf16 v[34:37], v[186:189], v[206:209], v[34:37]
	v_mfma_f32_16x16x32_bf16 v[22:25], v[178:181], v[214:217], v[22:25]
	v_mfma_f32_16x16x32_bf16 v[18:21], v[186:189], v[214:217], v[18:21]
	v_mfma_f32_16x16x32_bf16 v[6:9], v[178:181], v[222:225], v[6:9]
	v_mfma_f32_16x16x32_bf16 v[2:5], v[186:189], v[222:225], v[2:5]
	s_setprio 0
	s_barrier
	s_add_i32 s85, 0, 0x18000
	v_add_u32_e32 v161, s85, v156
	s_add_i32 s86, 0, 0x1c000
	ds_read_b128 v[150:153], v161
	ds_read_b128 v[162:165], v161 offset:1024
	ds_read_b128 v[166:169], v161 offset:2048
	ds_read_b128 v[170:173], v161 offset:3072
	v_add_u32_e32 v161, s86, v156
	ds_read_b128 v[174:177], v161
	ds_read_b128 v[178:181], v161 offset:1024
	ds_read_b128 v[182:185], v161 offset:2048
	ds_read_b128 v[186:189], v161 offset:3072
	s_add_u32 s64, s64, 0x100000
	s_addc_u32 s65, s65, 0
	s_mov_b32 m0, s67
	v_lshl_add_u64 v[232:233], s[64:65], 0, v[130:131]
	ds_read_b128 v[190:193], v160 offset:32768
	ds_read_b128 v[196:199], v160 offset:33792
	ds_read_b128 v[200:203], v160 offset:34816
	ds_read_b128 v[206:209], v160 offset:35840
	ds_read_b128 v[210:213], v160 offset:36864
	ds_read_b128 v[214:217], v160 offset:37888
	ds_read_b128 v[218:221], v160 offset:38912
	ds_read_b128 v[222:225], v160 offset:39936
	global_load_lds_dwordx4 v[232:233], off
	v_lshl_add_u64 v[232:233], s[64:65], 0, v[134:135]
	s_mov_b32 m0, s68
	s_nop 0
	global_load_lds_dwordx4 v[232:233], off
	s_waitcnt vmcnt(8)
	s_waitcnt lgkmcnt(0)
	s_barrier
	s_setprio 1
	v_mfma_f32_16x16x32_bf16 v[126:129], v[150:153], v[190:193], v[126:129]
	v_mfma_f32_16x16x32_bf16 v[122:125], v[166:169], v[190:193], v[122:125]
	v_mfma_f32_16x16x32_bf16 v[110:113], v[150:153], v[200:203], v[110:113]
	v_mfma_f32_16x16x32_bf16 v[106:109], v[166:169], v[200:203], v[106:109]
	v_mfma_f32_16x16x32_bf16 v[94:97], v[150:153], v[210:213], v[94:97]
	v_mfma_f32_16x16x32_bf16 v[90:93], v[166:169], v[210:213], v[90:93]
	v_mfma_f32_16x16x32_bf16 v[78:81], v[150:153], v[218:221], v[78:81]
	v_mfma_f32_16x16x32_bf16 v[74:77], v[166:169], v[218:221], v[74:77]
	v_mfma_f32_16x16x32_bf16 v[126:129], v[162:165], v[196:199], v[126:129]
	v_mfma_f32_16x16x32_bf16 v[122:125], v[170:173], v[196:199], v[122:125]
	v_mfma_f32_16x16x32_bf16 v[110:113], v[162:165], v[206:209], v[110:113]
	v_mfma_f32_16x16x32_bf16 v[106:109], v[170:173], v[206:209], v[106:109]
	v_mfma_f32_16x16x32_bf16 v[94:97], v[162:165], v[214:217], v[94:97]
	v_mfma_f32_16x16x32_bf16 v[90:93], v[170:173], v[214:217], v[90:93]
	v_mfma_f32_16x16x32_bf16 v[78:81], v[162:165], v[222:225], v[78:81]
	v_mfma_f32_16x16x32_bf16 v[74:77], v[170:173], v[222:225], v[74:77]
	v_mfma_f32_16x16x32_bf16 v[118:121], v[174:177], v[190:193], v[118:121]
	v_mfma_f32_16x16x32_bf16 v[114:117], v[182:185], v[190:193], v[114:117]
	v_mfma_f32_16x16x32_bf16 v[102:105], v[174:177], v[200:203], v[102:105]
	v_mfma_f32_16x16x32_bf16 v[98:101], v[182:185], v[200:203], v[98:101]
	v_mfma_f32_16x16x32_bf16 v[86:89], v[174:177], v[210:213], v[86:89]
	v_mfma_f32_16x16x32_bf16 v[82:85], v[182:185], v[210:213], v[82:85]
	v_mfma_f32_16x16x32_bf16 v[70:73], v[174:177], v[218:221], v[70:73]
	v_mfma_f32_16x16x32_bf16 v[66:69], v[182:185], v[218:221], v[66:69]
	v_mfma_f32_16x16x32_bf16 v[118:121], v[178:181], v[196:199], v[118:121]
	v_mfma_f32_16x16x32_bf16 v[114:117], v[186:189], v[196:199], v[114:117]
	v_mfma_f32_16x16x32_bf16 v[102:105], v[178:181], v[206:209], v[102:105]
	v_mfma_f32_16x16x32_bf16 v[98:101], v[186:189], v[206:209], v[98:101]
	v_mfma_f32_16x16x32_bf16 v[86:89], v[178:181], v[214:217], v[86:89]
	v_mfma_f32_16x16x32_bf16 v[82:85], v[186:189], v[214:217], v[82:85]
	v_mfma_f32_16x16x32_bf16 v[70:73], v[178:181], v[222:225], v[70:73]
	v_mfma_f32_16x16x32_bf16 v[66:69], v[186:189], v[222:225], v[66:69]
	s_setprio 0
	s_barrier
	s_add_i32 s64, s85, s66
	v_lshl_add_u64 v[154:155], v[154:155], 0, s[20:21]
	s_mov_b32 m0, s64
	ds_read_b128 v[190:193], v160 offset:49152
	ds_read_b128 v[196:199], v160 offset:50176
	ds_read_b128 v[200:203], v160 offset:51200
	ds_read_b128 v[206:209], v160 offset:52224
	ds_read_b128 v[210:213], v160 offset:53248
	ds_read_b128 v[214:217], v160 offset:54272
	ds_read_b128 v[218:221], v160 offset:55296
	ds_read_b128 v[222:225], v160 offset:56320
	global_load_lds_dwordx4 v[154:155], off
	s_add_i32 m0, s64, 0x2000
	s_add_u32 s48, s48, 0x100080
	v_lshl_add_u64 v[154:155], v[226:227], 0, s[20:21]
	s_addc_u32 s49, s49, 0
	s_add_i32 s64, s86, s66
	global_load_lds_dwordx4 v[154:155], off
	v_lshl_add_u64 v[154:155], s[48:49], 0, v[132:133]
	s_mov_b32 m0, s64
	s_nop 0
	global_load_lds_dwordx4 v[154:155], off
	v_lshl_add_u64 v[154:155], s[48:49], 0, v[136:137]
	s_add_i32 m0, s64, 0x2000
	s_nop 0
	global_load_lds_dwordx4 v[154:155], off
	v_lshl_add_u64 v[154:155], v[228:229], 0, s[20:21]
	s_mov_b32 m0, s72
	s_nop 0
	global_load_lds_dwordx4 v[154:155], off
	v_lshl_add_u64 v[154:155], v[230:231], 0, s[20:21]
	s_mov_b32 m0, s73
	s_nop 0
	global_load_lds_dwordx4 v[154:155], off
	s_nop 0
	s_waitcnt vmcnt(8)
	s_waitcnt lgkmcnt(0)
	s_barrier
	s_setprio 1
	v_mfma_f32_16x16x32_bf16 v[62:65], v[150:153], v[190:193], v[62:65]
	v_mfma_f32_16x16x32_bf16 v[58:61], v[166:169], v[190:193], v[58:61]
	v_mfma_f32_16x16x32_bf16 v[46:49], v[150:153], v[200:203], v[46:49]
	v_mfma_f32_16x16x32_bf16 v[42:45], v[166:169], v[200:203], v[42:45]
	v_mfma_f32_16x16x32_bf16 v[30:33], v[150:153], v[210:213], v[30:33]
	v_mfma_f32_16x16x32_bf16 v[26:29], v[166:169], v[210:213], v[26:29]
	v_mfma_f32_16x16x32_bf16 v[14:17], v[150:153], v[218:221], v[14:17]
	v_mfma_f32_16x16x32_bf16 v[10:13], v[166:169], v[218:221], v[10:13]
	v_mfma_f32_16x16x32_bf16 v[62:65], v[162:165], v[196:199], v[62:65]
	v_mfma_f32_16x16x32_bf16 v[58:61], v[170:173], v[196:199], v[58:61]
	v_mfma_f32_16x16x32_bf16 v[46:49], v[162:165], v[206:209], v[46:49]
	v_mfma_f32_16x16x32_bf16 v[42:45], v[170:173], v[206:209], v[42:45]
	v_mfma_f32_16x16x32_bf16 v[30:33], v[162:165], v[214:217], v[30:33]
	v_mfma_f32_16x16x32_bf16 v[26:29], v[170:173], v[214:217], v[26:29]
	v_mfma_f32_16x16x32_bf16 v[14:17], v[162:165], v[222:225], v[14:17]
	v_mfma_f32_16x16x32_bf16 v[10:13], v[170:173], v[222:225], v[10:13]
	v_mfma_f32_16x16x32_bf16 v[54:57], v[174:177], v[190:193], v[54:57]
	v_mfma_f32_16x16x32_bf16 v[50:53], v[182:185], v[190:193], v[50:53]
	v_mfma_f32_16x16x32_bf16 v[38:41], v[174:177], v[200:203], v[38:41]
	v_mfma_f32_16x16x32_bf16 v[34:37], v[182:185], v[200:203], v[34:37]
	v_mfma_f32_16x16x32_bf16 v[22:25], v[174:177], v[210:213], v[22:25]
	v_mfma_f32_16x16x32_bf16 v[18:21], v[182:185], v[210:213], v[18:21]
	v_mfma_f32_16x16x32_bf16 v[6:9], v[174:177], v[218:221], v[6:9]
	v_mfma_f32_16x16x32_bf16 v[2:5], v[182:185], v[218:221], v[2:5]
	v_mfma_f32_16x16x32_bf16 v[54:57], v[178:181], v[196:199], v[54:57]
	v_mfma_f32_16x16x32_bf16 v[50:53], v[186:189], v[196:199], v[50:53]
	v_mfma_f32_16x16x32_bf16 v[38:41], v[178:181], v[206:209], v[38:41]
	v_mfma_f32_16x16x32_bf16 v[34:37], v[186:189], v[206:209], v[34:37]
	v_mfma_f32_16x16x32_bf16 v[22:25], v[178:181], v[214:217], v[22:25]
	v_mfma_f32_16x16x32_bf16 v[18:21], v[186:189], v[214:217], v[18:21]
	v_mfma_f32_16x16x32_bf16 v[6:9], v[178:181], v[222:225], v[6:9]
	v_mfma_f32_16x16x32_bf16 v[2:5], v[186:189], v[222:225], v[2:5]
	s_setprio 0
	s_barrier
	s_add_u32 s62, s62, 0x100
	s_addc_u32 s63, s63, 0
	s_add_u32 s53, s53, 0x100
	s_addc_u32 s55, s55, 0
	s_cmp_ge_i32 s84, s83
	s_mov_b32 s48, s84
	s_cbranch_scc0 .LBB0_1057
	s_and_b64 vcc, exec, s[22:23]
	s_cbranch_vccz .LBB0_1060
	s_barrier

.LBB0_1197:
	ds_read_b128 v[162:165], v141
	ds_read_b128 v[166:169], v141 offset:1024
	ds_read_b128 v[170:173], v141 offset:2048
	ds_read_b128 v[174:177], v141 offset:3072
	ds_read_b128 v[178:181], v145
	ds_read_b128 v[182:185], v145 offset:1024
	ds_read_b128 v[186:189], v145 offset:2048
	ds_read_b128 v[190:193], v145 offset:3072
	s_add_i32 s65, s34, 2
	s_add_u32 s35, s30, 0xfff00080
	s_addc_u32 s40, s31, -1
	s_cmp_eq_u32 s62, s34
	s_cselect_b32 s34, s61, s63
	s_cselect_b32 s41, s21, s40
	s_cselect_b32 s40, s25, s35
	s_cselect_b32 s35, s23, s64
	v_lshl_add_u64 v[158:159], s[30:31], 0, v[148:149]
	s_add_i32 m0, s8, 0xc000
	ds_read_b128 v[196:199], v160
	ds_read_b128 v[200:203], v160 offset:1024
	ds_read_b128 v[206:209], v160 offset:2048
	ds_read_b128 v[210:213], v160 offset:3072
	ds_read_b128 v[214:217], v160 offset:4096
	ds_read_b128 v[218:221], v160 offset:5120
	ds_read_b128 v[222:225], v160 offset:6144
	ds_read_b128 v[226:229], v160 offset:7168
	global_load_lds_dwordx4 v[158:159], off
	v_lshl_add_u64 v[158:159], s[30:31], 0, v[150:151]
	s_add_i32 m0, s8, 0xe000
	s_nop 0
	global_load_lds_dwordx4 v[158:159], off
	s_nop 0
	s_waitcnt vmcnt(8)
	s_waitcnt lgkmcnt(0)
	s_barrier
	s_setprio 1
	v_mfma_f32_16x16x32_bf16 v[126:129], v[162:165], v[196:199], v[126:129]
	v_mfma_f32_16x16x32_bf16 v[122:125], v[170:173], v[196:199], v[122:125]
	v_mfma_f32_16x16x32_bf16 v[118:121], v[162:165], v[206:209], v[118:121]
	v_mfma_f32_16x16x32_bf16 v[114:117], v[170:173], v[206:209], v[114:117]
	v_mfma_f32_16x16x32_bf16 v[102:105], v[162:165], v[214:217], v[102:105]
	v_mfma_f32_16x16x32_bf16 v[98:101], v[170:173], v[214:217], v[98:101]
	v_mfma_f32_16x16x32_bf16 v[42:45], v[162:165], v[222:225], v[42:45]
	v_mfma_f32_16x16x32_bf16 v[34:37], v[170:173], v[222:225], v[34:37]
	v_mfma_f32_16x16x32_bf16 v[126:129], v[166:169], v[200:203], v[126:129]
	v_mfma_f32_16x16x32_bf16 v[122:125], v[174:177], v[200:203], v[122:125]
	v_mfma_f32_16x16x32_bf16 v[118:121], v[166:169], v[210:213], v[118:121]
	v_mfma_f32_16x16x32_bf16 v[114:117], v[174:177], v[210:213], v[114:117]
	v_mfma_f32_16x16x32_bf16 v[102:105], v[166:169], v[218:221], v[102:105]
	v_mfma_f32_16x16x32_bf16 v[98:101], v[174:177], v[218:221], v[98:101]
	v_mfma_f32_16x16x32_bf16 v[42:45], v[166:169], v[226:229], v[42:45]
	v_mfma_f32_16x16x32_bf16 v[34:37], v[174:177], v[226:229], v[34:37]
	v_mfma_f32_16x16x32_bf16 v[110:113], v[178:181], v[196:199], v[110:113]
	v_mfma_f32_16x16x32_bf16 v[106:109], v[186:189], v[196:199], v[106:109]
	v_mfma_f32_16x16x32_bf16 v[94:97], v[178:181], v[206:209], v[94:97]
	v_mfma_f32_16x16x32_bf16 v[90:93], v[186:189], v[206:209], v[90:93]
	v_mfma_f32_16x16x32_bf16 v[86:89], v[178:181], v[214:217], v[86:89]
	v_mfma_f32_16x16x32_bf16 v[82:85], v[186:189], v[214:217], v[82:85]
	v_mfma_f32_16x16x32_bf16 v[30:33], v[178:181], v[222:225], v[30:33]
	v_mfma_f32_16x16x32_bf16 v[26:29], v[186:189], v[222:225], v[26:29]
	v_mfma_f32_16x16x32_bf16 v[110:113], v[182:185], v[200:203], v[110:113]
	v_mfma_f32_16x16x32_bf16 v[106:109], v[190:193], v[200:203], v[106:109]
	v_mfma_f32_16x16x32_bf16 v[94:97], v[182:185], v[210:213], v[94:97]
	v_mfma_f32_16x16x32_bf16 v[90:93], v[190:193], v[210:213], v[90:93]
	v_mfma_f32_16x16x32_bf16 v[86:89], v[182:185], v[218:221], v[86:89]
	v_mfma_f32_16x16x32_bf16 v[82:85], v[190:193], v[218:221], v[82:85]
	v_mfma_f32_16x16x32_bf16 v[30:33], v[182:185], v[226:229], v[30:33]
	v_mfma_f32_16x16x32_bf16 v[26:29], v[190:193], v[226:229], v[26:29]
	s_setprio 0
	s_barrier
	s_add_i32 s66, s56, s42
	v_lshl_add_u64 v[158:159], s[34:35], 0, v[134:135]
	s_mov_b32 m0, s66
	ds_read_b128 v[196:199], v160 offset:16384
	ds_read_b128 v[200:203], v160 offset:17408
	ds_read_b128 v[206:209], v160 offset:18432
	ds_read_b128 v[210:213], v160 offset:19456
	ds_read_b128 v[214:217], v160 offset:20480
	ds_read_b128 v[218:221], v160 offset:21504
	ds_read_b128 v[222:225], v160 offset:22528
	ds_read_b128 v[226:229], v160 offset:23552
	global_load_lds_dwordx4 v[158:159], off
	s_add_i32 m0, s66, 0x2000
	s_add_u32 s66, s34, 0x100000
	v_lshl_add_u64 v[230:231], s[34:35], 0, v[132:133]
	s_addc_u32 s67, s35, 0
	s_add_i32 s68, s57, s42
	global_load_lds_dwordx4 v[230:231], off
	v_lshl_add_u64 v[232:233], s[66:67], 0, v[134:135]
	s_mov_b32 m0, s68
	v_lshl_add_u64 v[234:235], s[40:41], 0, v[132:133]
	global_load_lds_dwordx4 v[232:233], off
	v_lshl_add_u64 v[232:233], s[66:67], 0, v[132:133]
	s_add_i32 m0, s68, 0x2000
	s_nop 0
	global_load_lds_dwordx4 v[232:233], off
	v_lshl_add_u64 v[232:233], s[40:41], 0, v[134:135]
	s_mov_b32 m0, s8
	s_nop 0
	global_load_lds_dwordx4 v[232:233], off
	s_mov_b32 m0, s15
	s_nop 0
	global_load_lds_dwordx4 v[234:235], off
	s_waitcnt vmcnt(8)
	s_waitcnt lgkmcnt(0)
	s_barrier
	s_setprio 1
	v_mfma_f32_16x16x32_bf16 v[78:81], v[162:165], v[196:199], v[78:81]
	v_mfma_f32_16x16x32_bf16 v[74:77], v[170:173], v[196:199], v[74:77]
	v_mfma_f32_16x16x32_bf16 v[70:73], v[162:165], v[206:209], v[70:73]
	v_mfma_f32_16x16x32_bf16 v[66:69], v[170:173], v[206:209], v[66:69]
	v_mfma_f32_16x16x32_bf16 v[54:57], v[162:165], v[214:217], v[54:57]
	v_mfma_f32_16x16x32_bf16 v[50:53], v[170:173], v[214:217], v[50:53]
	v_mfma_f32_16x16x32_bf16 v[14:17], v[162:165], v[222:225], v[14:17]
	v_mfma_f32_16x16x32_bf16 v[10:13], v[170:173], v[222:225], v[10:13]
	v_mfma_f32_16x16x32_bf16 v[78:81], v[166:169], v[200:203], v[78:81]
	v_mfma_f32_16x16x32_bf16 v[74:77], v[174:177], v[200:203], v[74:77]
	v_mfma_f32_16x16x32_bf16 v[70:73], v[166:169], v[210:213], v[70:73]
	v_mfma_f32_16x16x32_bf16 v[66:69], v[174:177], v[210:213], v[66:69]
	v_mfma_f32_16x16x32_bf16 v[54:57], v[166:169], v[218:221], v[54:57]
	v_mfma_f32_16x16x32_bf16 v[50:53], v[174:177], v[218:221], v[50:53]
	v_mfma_f32_16x16x32_bf16 v[14:17], v[166:169], v[226:229], v[14:17]
	v_mfma_f32_16x16x32_bf16 v[10:13], v[174:177], v[226:229], v[10:13]
	v_mfma_f32_16x16x32_bf16 v[62:65], v[178:181], v[196:199], v[62:65]
	v_mfma_f32_16x16x32_bf16 v[58:61], v[186:189], v[196:199], v[58:61]
	v_mfma_f32_16x16x32_bf16 v[46:49], v[178:181], v[206:209], v[46:49]
	v_mfma_f32_16x16x32_bf16 v[38:41], v[186:189], v[206:209], v[38:41]
	v_mfma_f32_16x16x32_bf16 v[22:25], v[178:181], v[214:217], v[22:25]
	v_mfma_f32_16x16x32_bf16 v[18:21], v[186:189], v[214:217], v[18:21]
	v_mfma_f32_16x16x32_bf16 v[6:9], v[178:181], v[222:225], v[6:9]
	v_mfma_f32_16x16x32_bf16 v[2:5], v[186:189], v[222:225], v[2:5]
	v_mfma_f32_16x16x32_bf16 v[62:65], v[182:185], v[200:203], v[62:65]
	v_mfma_f32_16x16x32_bf16 v[58:61], v[190:193], v[200:203], v[58:61]
	v_mfma_f32_16x16x32_bf16 v[46:49], v[182:185], v[210:213], v[46:49]
	v_mfma_f32_16x16x32_bf16 v[38:41], v[190:193], v[210:213], v[38:41]
	v_mfma_f32_16x16x32_bf16 v[22:25], v[182:185], v[218:221], v[22:25]
	v_mfma_f32_16x16x32_bf16 v[18:21], v[190:193], v[218:221], v[18:21]
	v_mfma_f32_16x16x32_bf16 v[6:9], v[182:185], v[226:229], v[6:9]
	v_mfma_f32_16x16x32_bf16 v[2:5], v[190:193], v[226:229], v[2:5]
	s_setprio 0
	s_barrier
	s_add_i32 s66, 0, 0x18000
	v_add_u32_e32 v161, s66, v1
	s_add_i32 s67, 0, 0x1c000
	ds_read_b128 v[162:165], v161
	ds_read_b128 v[166:169], v161 offset:1024
	ds_read_b128 v[170:173], v161 offset:2048
	ds_read_b128 v[174:177], v161 offset:3072
	v_add_u32_e32 v161, s67, v1
	ds_read_b128 v[178:181], v161
	ds_read_b128 v[182:185], v161 offset:1024
	ds_read_b128 v[186:189], v161 offset:2048
	ds_read_b128 v[190:193], v161 offset:3072
	s_add_u32 s40, s40, 0x100000
	s_addc_u32 s41, s41, 0
	s_mov_b32 m0, s46
	v_lshl_add_u64 v[236:237], s[40:41], 0, v[134:135]
	ds_read_b128 v[196:199], v160 offset:32768
	ds_read_b128 v[200:203], v160 offset:33792
	ds_read_b128 v[206:209], v160 offset:34816
	ds_read_b128 v[210:213], v160 offset:35840
	ds_read_b128 v[214:217], v160 offset:36864
	ds_read_b128 v[218:221], v160 offset:37888
	ds_read_b128 v[222:225], v160 offset:38912
	ds_read_b128 v[226:229], v160 offset:39936
	global_load_lds_dwordx4 v[236:237], off
	v_lshl_add_u64 v[236:237], s[40:41], 0, v[132:133]
	s_mov_b32 m0, s47
	s_nop 0
	global_load_lds_dwordx4 v[236:237], off
	s_waitcnt vmcnt(8)
	s_waitcnt lgkmcnt(0)
	s_barrier
	s_setprio 1
	v_mfma_f32_16x16x32_bf16 v[126:129], v[162:165], v[196:199], v[126:129]
	v_mfma_f32_16x16x32_bf16 v[122:125], v[170:173], v[196:199], v[122:125]
	v_mfma_f32_16x16x32_bf16 v[118:121], v[162:165], v[206:209], v[118:121]
	v_mfma_f32_16x16x32_bf16 v[114:117], v[170:173], v[206:209], v[114:117]
	v_mfma_f32_16x16x32_bf16 v[102:105], v[162:165], v[214:217], v[102:105]
	v_mfma_f32_16x16x32_bf16 v[98:101], v[170:173], v[214:217], v[98:101]
	v_mfma_f32_16x16x32_bf16 v[42:45], v[162:165], v[222:225], v[42:45]
	v_mfma_f32_16x16x32_bf16 v[34:37], v[170:173], v[222:225], v[34:37]
	v_mfma_f32_16x16x32_bf16 v[126:129], v[166:169], v[200:203], v[126:129]
	v_mfma_f32_16x16x32_bf16 v[122:125], v[174:177], v[200:203], v[122:125]
	v_mfma_f32_16x16x32_bf16 v[118:121], v[166:169], v[210:213], v[118:121]
	v_mfma_f32_16x16x32_bf16 v[114:117], v[174:177], v[210:213], v[114:117]
	v_mfma_f32_16x16x32_bf16 v[102:105], v[166:169], v[218:221], v[102:105]
	v_mfma_f32_16x16x32_bf16 v[98:101], v[174:177], v[218:221], v[98:101]
	v_mfma_f32_16x16x32_bf16 v[42:45], v[166:169], v[226:229], v[42:45]
	v_mfma_f32_16x16x32_bf16 v[34:37], v[174:177], v[226:229], v[34:37]
	v_mfma_f32_16x16x32_bf16 v[110:113], v[178:181], v[196:199], v[110:113]
	v_mfma_f32_16x16x32_bf16 v[106:109], v[186:189], v[196:199], v[106:109]
	v_mfma_f32_16x16x32_bf16 v[94:97], v[178:181], v[206:209], v[94:97]
	v_mfma_f32_16x16x32_bf16 v[90:93], v[186:189], v[206:209], v[90:93]
	v_mfma_f32_16x16x32_bf16 v[86:89], v[178:181], v[214:217], v[86:89]
	v_mfma_f32_16x16x32_bf16 v[82:85], v[186:189], v[214:217], v[82:85]
	v_mfma_f32_16x16x32_bf16 v[30:33], v[178:181], v[222:225], v[30:33]
	v_mfma_f32_16x16x32_bf16 v[26:29], v[186:189], v[222:225], v[26:29]
	v_mfma_f32_16x16x32_bf16 v[110:113], v[182:185], v[200:203], v[110:113]
	v_mfma_f32_16x16x32_bf16 v[106:109], v[190:193], v[200:203], v[106:109]
	v_mfma_f32_16x16x32_bf16 v[94:97], v[182:185], v[210:213], v[94:97]
	v_mfma_f32_16x16x32_bf16 v[90:93], v[190:193], v[210:213], v[90:93]
	v_mfma_f32_16x16x32_bf16 v[86:89], v[182:185], v[218:221], v[86:89]
	v_mfma_f32_16x16x32_bf16 v[82:85], v[190:193], v[218:221], v[82:85]
	v_mfma_f32_16x16x32_bf16 v[30:33], v[182:185], v[226:229], v[30:33]
	v_mfma_f32_16x16x32_bf16 v[26:29], v[190:193], v[226:229], v[26:29]
	s_setprio 0
	s_barrier
	s_add_i32 s40, s66, s42
	v_lshl_add_u64 v[158:159], v[158:159], 0, s[12:13]
	s_mov_b32 m0, s40
	ds_read_b128 v[196:199], v160 offset:49152
	ds_read_b128 v[200:203], v160 offset:50176
	ds_read_b128 v[206:209], v160 offset:51200
	ds_read_b128 v[210:213], v160 offset:52224
	ds_read_b128 v[214:217], v160 offset:53248
	ds_read_b128 v[218:221], v160 offset:54272
	ds_read_b128 v[222:225], v160 offset:55296
	ds_read_b128 v[226:229], v160 offset:56320
	global_load_lds_dwordx4 v[158:159], off
	s_add_i32 m0, s40, 0x2000
	s_add_u32 s34, s34, 0x100080
	v_lshl_add_u64 v[158:159], v[230:231], 0, s[12:13]
	s_addc_u32 s35, s35, 0
	s_add_i32 s40, s67, s42
	global_load_lds_dwordx4 v[158:159], off
	v_lshl_add_u64 v[158:159], s[34:35], 0, v[134:135]
	s_mov_b32 m0, s40
	s_nop 0
	global_load_lds_dwordx4 v[158:159], off
	v_lshl_add_u64 v[158:159], s[34:35], 0, v[132:133]
	s_add_i32 m0, s40, 0x2000
	s_nop 0
	global_load_lds_dwordx4 v[158:159], off
	v_lshl_add_u64 v[158:159], v[232:233], 0, s[12:13]
	s_mov_b32 m0, s52
	s_nop 0
	global_load_lds_dwordx4 v[158:159], off
	v_lshl_add_u64 v[158:159], v[234:235], 0, s[12:13]
	s_mov_b32 m0, s53
	s_nop 0
	global_load_lds_dwordx4 v[158:159], off
	s_nop 0
	s_waitcnt vmcnt(8)
	s_waitcnt lgkmcnt(0)
	s_barrier
	s_setprio 1
	v_mfma_f32_16x16x32_bf16 v[78:81], v[162:165], v[196:199], v[78:81]
	v_mfma_f32_16x16x32_bf16 v[74:77], v[170:173], v[196:199], v[74:77]
	v_mfma_f32_16x16x32_bf16 v[70:73], v[162:165], v[206:209], v[70:73]
	v_mfma_f32_16x16x32_bf16 v[66:69], v[170:173], v[206:209], v[66:69]
	v_mfma_f32_16x16x32_bf16 v[54:57], v[162:165], v[214:217], v[54:57]
	v_mfma_f32_16x16x32_bf16 v[50:53], v[170:173], v[214:217], v[50:53]
	v_mfma_f32_16x16x32_bf16 v[14:17], v[162:165], v[222:225], v[14:17]
	v_mfma_f32_16x16x32_bf16 v[10:13], v[170:173], v[222:225], v[10:13]
	v_mfma_f32_16x16x32_bf16 v[78:81], v[166:169], v[200:203], v[78:81]
	v_mfma_f32_16x16x32_bf16 v[74:77], v[174:177], v[200:203], v[74:77]
	v_mfma_f32_16x16x32_bf16 v[70:73], v[166:169], v[210:213], v[70:73]
	v_mfma_f32_16x16x32_bf16 v[66:69], v[174:177], v[210:213], v[66:69]
	v_mfma_f32_16x16x32_bf16 v[54:57], v[166:169], v[218:221], v[54:57]
	v_mfma_f32_16x16x32_bf16 v[50:53], v[174:177], v[218:221], v[50:53]
	v_mfma_f32_16x16x32_bf16 v[14:17], v[166:169], v[226:229], v[14:17]
	v_mfma_f32_16x16x32_bf16 v[10:13], v[174:177], v[226:229], v[10:13]
	v_mfma_f32_16x16x32_bf16 v[62:65], v[178:181], v[196:199], v[62:65]
	v_mfma_f32_16x16x32_bf16 v[58:61], v[186:189], v[196:199], v[58:61]
	v_mfma_f32_16x16x32_bf16 v[46:49], v[178:181], v[206:209], v[46:49]
	v_mfma_f32_16x16x32_bf16 v[38:41], v[186:189], v[206:209], v[38:41]
	v_mfma_f32_16x16x32_bf16 v[22:25], v[178:181], v[214:217], v[22:25]
	v_mfma_f32_16x16x32_bf16 v[18:21], v[186:189], v[214:217], v[18:21]
	v_mfma_f32_16x16x32_bf16 v[6:9], v[178:181], v[222:225], v[6:9]
	v_mfma_f32_16x16x32_bf16 v[2:5], v[186:189], v[222:225], v[2:5]
	v_mfma_f32_16x16x32_bf16 v[62:65], v[182:185], v[200:203], v[62:65]
	v_mfma_f32_16x16x32_bf16 v[58:61], v[190:193], v[200:203], v[58:61]
	v_mfma_f32_16x16x32_bf16 v[46:49], v[182:185], v[210:213], v[46:49]
	v_mfma_f32_16x16x32_bf16 v[38:41], v[190:193], v[210:213], v[38:41]
	v_mfma_f32_16x16x32_bf16 v[22:25], v[182:185], v[218:221], v[22:25]
	v_mfma_f32_16x16x32_bf16 v[18:21], v[190:193], v[218:221], v[18:21]
	v_mfma_f32_16x16x32_bf16 v[6:9], v[182:185], v[226:229], v[6:9]
	v_mfma_f32_16x16x32_bf16 v[2:5], v[190:193], v[226:229], v[2:5]
	s_setprio 0
	s_barrier
	s_add_u32 s30, s30, 0x100
	s_addc_u32 s31, s31, 0
	s_add_u32 s63, s63, 0x100
	s_addc_u32 s64, s64, 0
	s_cmp_ge_i32 s65, s60
	s_mov_b32 s34, s65
	s_cbranch_scc0 .LBB0_1197
	s_and_b64 vcc, exec, s[18:19]
	s_cbranch_vccz .LBB0_1200
	s_barrier

.LBB0_1391:
	ds_read_b128 v[152:155], v159
	ds_read_b128 v[162:165], v159 offset:1024
	ds_read_b128 v[166:169], v159 offset:2048
	ds_read_b128 v[170:173], v159 offset:3072
	ds_read_b128 v[174:177], v160
	ds_read_b128 v[178:181], v160 offset:1024
	ds_read_b128 v[182:185], v160 offset:2048
	ds_read_b128 v[186:189], v160 offset:3072
	s_add_i32 s82, s48, 2
	s_add_u32 s49, s60, 0xfffe0080
	s_addc_u32 s62, s61, -1
	s_cmp_eq_u32 s47, s48
	s_cselect_b32 s48, s54, s51
	s_cselect_b32 s63, s9, s62
	s_cselect_b32 s62, s8, s49
	s_cselect_b32 s49, s55, s53
	v_lshl_add_u64 v[156:157], s[60:61], 0, v[140:141]
	s_add_i32 m0, s57, 0xc000
	ds_read_b128 v[190:193], v161
	ds_read_b128 v[196:199], v161 offset:1024
	ds_read_b128 v[200:203], v161 offset:2048
	ds_read_b128 v[206:209], v161 offset:3072
	ds_read_b128 v[210:213], v161 offset:4096
	ds_read_b128 v[214:217], v161 offset:5120
	ds_read_b128 v[218:221], v161 offset:6144
	ds_read_b128 v[222:225], v161 offset:7168
	global_load_lds_dwordx4 v[156:157], off
	v_lshl_add_u64 v[156:157], s[60:61], 0, v[142:143]
	s_add_i32 m0, s57, 0xe000
	s_nop 0
	global_load_lds_dwordx4 v[156:157], off
	s_nop 0
	s_waitcnt vmcnt(8)
	s_waitcnt lgkmcnt(0)
	s_barrier
	s_setprio 1
	v_mfma_f32_16x16x32_bf16 v[126:129], v[152:155], v[190:193], v[126:129]
	v_mfma_f32_16x16x32_bf16 v[122:125], v[166:169], v[190:193], v[122:125]
	v_mfma_f32_16x16x32_bf16 v[110:113], v[152:155], v[200:203], v[110:113]
	v_mfma_f32_16x16x32_bf16 v[106:109], v[166:169], v[200:203], v[106:109]
	v_mfma_f32_16x16x32_bf16 v[94:97], v[152:155], v[210:213], v[94:97]
	v_mfma_f32_16x16x32_bf16 v[90:93], v[166:169], v[210:213], v[90:93]
	v_mfma_f32_16x16x32_bf16 v[78:81], v[152:155], v[218:221], v[78:81]
	v_mfma_f32_16x16x32_bf16 v[74:77], v[166:169], v[218:221], v[74:77]
	v_mfma_f32_16x16x32_bf16 v[126:129], v[162:165], v[196:199], v[126:129]
	v_mfma_f32_16x16x32_bf16 v[122:125], v[170:173], v[196:199], v[122:125]
	v_mfma_f32_16x16x32_bf16 v[110:113], v[162:165], v[206:209], v[110:113]
	v_mfma_f32_16x16x32_bf16 v[106:109], v[170:173], v[206:209], v[106:109]
	v_mfma_f32_16x16x32_bf16 v[94:97], v[162:165], v[214:217], v[94:97]
	v_mfma_f32_16x16x32_bf16 v[90:93], v[170:173], v[214:217], v[90:93]
	v_mfma_f32_16x16x32_bf16 v[78:81], v[162:165], v[222:225], v[78:81]
	v_mfma_f32_16x16x32_bf16 v[74:77], v[170:173], v[222:225], v[74:77]
	v_mfma_f32_16x16x32_bf16 v[118:121], v[174:177], v[190:193], v[118:121]
	v_mfma_f32_16x16x32_bf16 v[114:117], v[182:185], v[190:193], v[114:117]
	v_mfma_f32_16x16x32_bf16 v[102:105], v[174:177], v[200:203], v[102:105]
	v_mfma_f32_16x16x32_bf16 v[98:101], v[182:185], v[200:203], v[98:101]
	v_mfma_f32_16x16x32_bf16 v[86:89], v[174:177], v[210:213], v[86:89]
	v_mfma_f32_16x16x32_bf16 v[82:85], v[182:185], v[210:213], v[82:85]
	v_mfma_f32_16x16x32_bf16 v[70:73], v[174:177], v[218:221], v[70:73]
	v_mfma_f32_16x16x32_bf16 v[66:69], v[182:185], v[218:221], v[66:69]
	v_mfma_f32_16x16x32_bf16 v[118:121], v[178:181], v[196:199], v[118:121]
	v_mfma_f32_16x16x32_bf16 v[114:117], v[186:189], v[196:199], v[114:117]
	v_mfma_f32_16x16x32_bf16 v[102:105], v[178:181], v[206:209], v[102:105]
	v_mfma_f32_16x16x32_bf16 v[98:101], v[186:189], v[206:209], v[98:101]
	v_mfma_f32_16x16x32_bf16 v[86:89], v[178:181], v[214:217], v[86:89]
	v_mfma_f32_16x16x32_bf16 v[82:85], v[186:189], v[214:217], v[82:85]
	v_mfma_f32_16x16x32_bf16 v[70:73], v[178:181], v[222:225], v[70:73]
	v_mfma_f32_16x16x32_bf16 v[66:69], v[186:189], v[222:225], v[66:69]
	s_setprio 0
	s_barrier
	s_add_i32 s83, s73, s64
	v_lshl_add_u64 v[156:157], s[48:49], 0, v[134:135]
	s_mov_b32 m0, s83
	ds_read_b128 v[190:193], v161 offset:16384
	ds_read_b128 v[196:199], v161 offset:17408
	ds_read_b128 v[200:203], v161 offset:18432
	ds_read_b128 v[206:209], v161 offset:19456
	ds_read_b128 v[210:213], v161 offset:20480
	ds_read_b128 v[214:217], v161 offset:21504
	ds_read_b128 v[218:221], v161 offset:22528
	ds_read_b128 v[222:225], v161 offset:23552
	global_load_lds_dwordx4 v[156:157], off
	s_add_i32 m0, s83, 0x2000
	s_add_u32 s84, s48, 0x20000
	v_lshl_add_u64 v[226:227], s[48:49], 0, v[138:139]
	s_addc_u32 s85, s49, 0
	s_add_i32 s83, s74, s64
	global_load_lds_dwordx4 v[226:227], off
	v_lshl_add_u64 v[228:229], s[84:85], 0, v[134:135]
	s_mov_b32 m0, s83
	v_lshl_add_u64 v[230:231], s[62:63], 0, v[136:137]
	global_load_lds_dwordx4 v[228:229], off
	v_lshl_add_u64 v[228:229], s[84:85], 0, v[138:139]
	s_add_i32 m0, s83, 0x2000
	s_nop 0
	global_load_lds_dwordx4 v[228:229], off
	v_lshl_add_u64 v[228:229], s[62:63], 0, v[132:133]
	s_mov_b32 m0, s57
	s_nop 0
	global_load_lds_dwordx4 v[228:229], off
	s_mov_b32 m0, s59
	s_nop 0
	global_load_lds_dwordx4 v[230:231], off
	s_waitcnt vmcnt(8)
	s_waitcnt lgkmcnt(0)
	s_barrier
	s_setprio 1
	v_mfma_f32_16x16x32_bf16 v[62:65], v[152:155], v[190:193], v[62:65]
	v_mfma_f32_16x16x32_bf16 v[58:61], v[166:169], v[190:193], v[58:61]
	v_mfma_f32_16x16x32_bf16 v[46:49], v[152:155], v[200:203], v[46:49]
	v_mfma_f32_16x16x32_bf16 v[42:45], v[166:169], v[200:203], v[42:45]
	v_mfma_f32_16x16x32_bf16 v[30:33], v[152:155], v[210:213], v[30:33]
	v_mfma_f32_16x16x32_bf16 v[26:29], v[166:169], v[210:213], v[26:29]
	v_mfma_f32_16x16x32_bf16 v[14:17], v[152:155], v[218:221], v[14:17]
	v_mfma_f32_16x16x32_bf16 v[10:13], v[166:169], v[218:221], v[10:13]
	v_mfma_f32_16x16x32_bf16 v[62:65], v[162:165], v[196:199], v[62:65]
	v_mfma_f32_16x16x32_bf16 v[58:61], v[170:173], v[196:199], v[58:61]
	v_mfma_f32_16x16x32_bf16 v[46:49], v[162:165], v[206:209], v[46:49]
	v_mfma_f32_16x16x32_bf16 v[42:45], v[170:173], v[206:209], v[42:45]
	v_mfma_f32_16x16x32_bf16 v[30:33], v[162:165], v[214:217], v[30:33]
	v_mfma_f32_16x16x32_bf16 v[26:29], v[170:173], v[214:217], v[26:29]
	v_mfma_f32_16x16x32_bf16 v[14:17], v[162:165], v[222:225], v[14:17]
	v_mfma_f32_16x16x32_bf16 v[10:13], v[170:173], v[222:225], v[10:13]
	v_mfma_f32_16x16x32_bf16 v[54:57], v[174:177], v[190:193], v[54:57]
	v_mfma_f32_16x16x32_bf16 v[50:53], v[182:185], v[190:193], v[50:53]
	v_mfma_f32_16x16x32_bf16 v[38:41], v[174:177], v[200:203], v[38:41]
	v_mfma_f32_16x16x32_bf16 v[34:37], v[182:185], v[200:203], v[34:37]
	v_mfma_f32_16x16x32_bf16 v[22:25], v[174:177], v[210:213], v[22:25]
	v_mfma_f32_16x16x32_bf16 v[18:21], v[182:185], v[210:213], v[18:21]
	v_mfma_f32_16x16x32_bf16 v[6:9], v[174:177], v[218:221], v[6:9]
	v_mfma_f32_16x16x32_bf16 v[2:5], v[182:185], v[218:221], v[2:5]
	v_mfma_f32_16x16x32_bf16 v[54:57], v[178:181], v[196:199], v[54:57]
	v_mfma_f32_16x16x32_bf16 v[50:53], v[186:189], v[196:199], v[50:53]
	v_mfma_f32_16x16x32_bf16 v[38:41], v[178:181], v[206:209], v[38:41]
	v_mfma_f32_16x16x32_bf16 v[34:37], v[186:189], v[206:209], v[34:37]
	v_mfma_f32_16x16x32_bf16 v[22:25], v[178:181], v[214:217], v[22:25]
	v_mfma_f32_16x16x32_bf16 v[18:21], v[186:189], v[214:217], v[18:21]
	v_mfma_f32_16x16x32_bf16 v[6:9], v[178:181], v[222:225], v[6:9]
	v_mfma_f32_16x16x32_bf16 v[2:5], v[186:189], v[222:225], v[2:5]
	s_setprio 0
	s_barrier
	s_add_i32 s83, 0, 0x18000
	s_add_i32 s84, 0, 0x1c000
	v_add_u32_e32 v170, s83, v131
	v_add_u32_e32 v186, s84, v131
	ds_read_b128 v[152:155], v170
	ds_read_b128 v[162:165], v170 offset:1024
	ds_read_b128 v[166:169], v170 offset:2048
	ds_read_b128 v[170:173], v170 offset:3072
	ds_read_b128 v[174:177], v186
	ds_read_b128 v[178:181], v186 offset:1024
	ds_read_b128 v[182:185], v186 offset:2048
	ds_read_b128 v[186:189], v186 offset:3072
	s_add_u32 s62, s62, 0x20000
	s_addc_u32 s63, s63, 0
	s_mov_b32 m0, s65
	v_lshl_add_u64 v[232:233], s[62:63], 0, v[132:133]
	ds_read_b128 v[190:193], v161 offset:32768
	ds_read_b128 v[196:199], v161 offset:33792
	ds_read_b128 v[200:203], v161 offset:34816
	ds_read_b128 v[206:209], v161 offset:35840
	ds_read_b128 v[210:213], v161 offset:36864
	ds_read_b128 v[214:217], v161 offset:37888
	ds_read_b128 v[218:221], v161 offset:38912
	ds_read_b128 v[222:225], v161 offset:39936
	global_load_lds_dwordx4 v[232:233], off
	v_lshl_add_u64 v[232:233], s[62:63], 0, v[136:137]
	s_mov_b32 m0, s66
	s_nop 0
	global_load_lds_dwordx4 v[232:233], off
	s_waitcnt vmcnt(8)
	s_waitcnt lgkmcnt(0)
	s_barrier
	s_setprio 1
	v_mfma_f32_16x16x32_bf16 v[126:129], v[152:155], v[190:193], v[126:129]
	v_mfma_f32_16x16x32_bf16 v[122:125], v[166:169], v[190:193], v[122:125]
	v_mfma_f32_16x16x32_bf16 v[110:113], v[152:155], v[200:203], v[110:113]
	v_mfma_f32_16x16x32_bf16 v[106:109], v[166:169], v[200:203], v[106:109]
	v_mfma_f32_16x16x32_bf16 v[94:97], v[152:155], v[210:213], v[94:97]
	v_mfma_f32_16x16x32_bf16 v[90:93], v[166:169], v[210:213], v[90:93]
	v_mfma_f32_16x16x32_bf16 v[78:81], v[152:155], v[218:221], v[78:81]
	v_mfma_f32_16x16x32_bf16 v[74:77], v[166:169], v[218:221], v[74:77]
	v_mfma_f32_16x16x32_bf16 v[126:129], v[162:165], v[196:199], v[126:129]
	v_mfma_f32_16x16x32_bf16 v[122:125], v[170:173], v[196:199], v[122:125]
	v_mfma_f32_16x16x32_bf16 v[110:113], v[162:165], v[206:209], v[110:113]
	v_mfma_f32_16x16x32_bf16 v[106:109], v[170:173], v[206:209], v[106:109]
	v_mfma_f32_16x16x32_bf16 v[94:97], v[162:165], v[214:217], v[94:97]
	v_mfma_f32_16x16x32_bf16 v[90:93], v[170:173], v[214:217], v[90:93]
	v_mfma_f32_16x16x32_bf16 v[78:81], v[162:165], v[222:225], v[78:81]
	v_mfma_f32_16x16x32_bf16 v[74:77], v[170:173], v[222:225], v[74:77]
	v_mfma_f32_16x16x32_bf16 v[118:121], v[174:177], v[190:193], v[118:121]
	v_mfma_f32_16x16x32_bf16 v[114:117], v[182:185], v[190:193], v[114:117]
	v_mfma_f32_16x16x32_bf16 v[102:105], v[174:177], v[200:203], v[102:105]
	v_mfma_f32_16x16x32_bf16 v[98:101], v[182:185], v[200:203], v[98:101]
	v_mfma_f32_16x16x32_bf16 v[86:89], v[174:177], v[210:213], v[86:89]
	v_mfma_f32_16x16x32_bf16 v[82:85], v[182:185], v[210:213], v[82:85]
	v_mfma_f32_16x16x32_bf16 v[70:73], v[174:177], v[218:221], v[70:73]
	v_mfma_f32_16x16x32_bf16 v[66:69], v[182:185], v[218:221], v[66:69]
	v_mfma_f32_16x16x32_bf16 v[118:121], v[178:181], v[196:199], v[118:121]
	v_mfma_f32_16x16x32_bf16 v[114:117], v[186:189], v[196:199], v[114:117]
	v_mfma_f32_16x16x32_bf16 v[102:105], v[178:181], v[206:209], v[102:105]
	v_mfma_f32_16x16x32_bf16 v[98:101], v[186:189], v[206:209], v[98:101]
	v_mfma_f32_16x16x32_bf16 v[86:89], v[178:181], v[214:217], v[86:89]
	v_mfma_f32_16x16x32_bf16 v[82:85], v[186:189], v[214:217], v[82:85]
	v_mfma_f32_16x16x32_bf16 v[70:73], v[178:181], v[222:225], v[70:73]
	v_mfma_f32_16x16x32_bf16 v[66:69], v[186:189], v[222:225], v[66:69]
	s_setprio 0
	s_barrier
	s_add_i32 s62, s83, s64
	v_lshl_add_u64 v[156:157], v[156:157], 0, s[18:19]
	s_mov_b32 m0, s62
	ds_read_b128 v[190:193], v161 offset:49152
	ds_read_b128 v[196:199], v161 offset:50176
	ds_read_b128 v[200:203], v161 offset:51200
	ds_read_b128 v[206:209], v161 offset:52224
	ds_read_b128 v[210:213], v161 offset:53248
	ds_read_b128 v[214:217], v161 offset:54272
	ds_read_b128 v[218:221], v161 offset:55296
	ds_read_b128 v[222:225], v161 offset:56320
	global_load_lds_dwordx4 v[156:157], off
	s_add_i32 m0, s62, 0x2000
	s_add_u32 s48, s48, 0x20080
	v_lshl_add_u64 v[156:157], v[226:227], 0, s[18:19]
	s_addc_u32 s49, s49, 0
	s_add_i32 s62, s84, s64
	global_load_lds_dwordx4 v[156:157], off
	v_lshl_add_u64 v[156:157], s[48:49], 0, v[134:135]
	s_mov_b32 m0, s62
	s_nop 0
	global_load_lds_dwordx4 v[156:157], off
	v_lshl_add_u64 v[156:157], s[48:49], 0, v[138:139]
	s_add_i32 m0, s62, 0x2000
	s_nop 0
	global_load_lds_dwordx4 v[156:157], off
	v_lshl_add_u64 v[156:157], v[228:229], 0, s[18:19]
	s_mov_b32 m0, s70
	s_nop 0
	global_load_lds_dwordx4 v[156:157], off
	v_lshl_add_u64 v[156:157], v[230:231], 0, s[18:19]
	s_mov_b32 m0, s71
	s_nop 0
	global_load_lds_dwordx4 v[156:157], off
	s_nop 0
	s_waitcnt vmcnt(8)
	s_waitcnt lgkmcnt(0)
	s_barrier
	s_setprio 1
	v_mfma_f32_16x16x32_bf16 v[62:65], v[152:155], v[190:193], v[62:65]
	v_mfma_f32_16x16x32_bf16 v[58:61], v[166:169], v[190:193], v[58:61]
	v_mfma_f32_16x16x32_bf16 v[46:49], v[152:155], v[200:203], v[46:49]
	v_mfma_f32_16x16x32_bf16 v[42:45], v[166:169], v[200:203], v[42:45]
	v_mfma_f32_16x16x32_bf16 v[30:33], v[152:155], v[210:213], v[30:33]
	v_mfma_f32_16x16x32_bf16 v[26:29], v[166:169], v[210:213], v[26:29]
	v_mfma_f32_16x16x32_bf16 v[14:17], v[152:155], v[218:221], v[14:17]
	v_mfma_f32_16x16x32_bf16 v[10:13], v[166:169], v[218:221], v[10:13]
	v_mfma_f32_16x16x32_bf16 v[62:65], v[162:165], v[196:199], v[62:65]
	v_mfma_f32_16x16x32_bf16 v[58:61], v[170:173], v[196:199], v[58:61]
	v_mfma_f32_16x16x32_bf16 v[46:49], v[162:165], v[206:209], v[46:49]
	v_mfma_f32_16x16x32_bf16 v[42:45], v[170:173], v[206:209], v[42:45]
	v_mfma_f32_16x16x32_bf16 v[30:33], v[162:165], v[214:217], v[30:33]
	v_mfma_f32_16x16x32_bf16 v[26:29], v[170:173], v[214:217], v[26:29]
	v_mfma_f32_16x16x32_bf16 v[14:17], v[162:165], v[222:225], v[14:17]
	v_mfma_f32_16x16x32_bf16 v[10:13], v[170:173], v[222:225], v[10:13]
	v_mfma_f32_16x16x32_bf16 v[54:57], v[174:177], v[190:193], v[54:57]
	v_mfma_f32_16x16x32_bf16 v[50:53], v[182:185], v[190:193], v[50:53]
	v_mfma_f32_16x16x32_bf16 v[38:41], v[174:177], v[200:203], v[38:41]
	v_mfma_f32_16x16x32_bf16 v[34:37], v[182:185], v[200:203], v[34:37]
	v_mfma_f32_16x16x32_bf16 v[22:25], v[174:177], v[210:213], v[22:25]
	v_mfma_f32_16x16x32_bf16 v[18:21], v[182:185], v[210:213], v[18:21]
	v_mfma_f32_16x16x32_bf16 v[6:9], v[174:177], v[218:221], v[6:9]
	v_mfma_f32_16x16x32_bf16 v[2:5], v[182:185], v[218:221], v[2:5]
	v_mfma_f32_16x16x32_bf16 v[54:57], v[178:181], v[196:199], v[54:57]
	v_mfma_f32_16x16x32_bf16 v[50:53], v[186:189], v[196:199], v[50:53]
	v_mfma_f32_16x16x32_bf16 v[38:41], v[178:181], v[206:209], v[38:41]
	v_mfma_f32_16x16x32_bf16 v[34:37], v[186:189], v[206:209], v[34:37]
	v_mfma_f32_16x16x32_bf16 v[22:25], v[178:181], v[214:217], v[22:25]
	v_mfma_f32_16x16x32_bf16 v[18:21], v[186:189], v[214:217], v[18:21]
	v_mfma_f32_16x16x32_bf16 v[6:9], v[178:181], v[222:225], v[6:9]
	v_mfma_f32_16x16x32_bf16 v[2:5], v[186:189], v[222:225], v[2:5]
	s_setprio 0
	s_barrier
	s_add_u32 s60, s60, 0x100
	s_addc_u32 s61, s61, 0
	s_add_u32 s51, s51, 0x100
	s_addc_u32 s53, s53, 0
	s_cmp_ge_i32 s82, s81
	s_mov_b32 s48, s82
	s_cbranch_scc0 .LBB0_1391
	s_and_b64 vcc, exec, s[20:21]
	s_cbranch_vccz .LBB0_1394
	s_barrier

.LBB0_1553:
	ds_read_b128 v[156:159], v161
	ds_read_b128 v[164:167], v161 offset:1024
	ds_read_b128 v[168:171], v161 offset:2048
	ds_read_b128 v[172:175], v161 offset:3072
	ds_read_b128 v[176:179], v162
	ds_read_b128 v[180:183], v162 offset:1024
	ds_read_b128 v[184:187], v162 offset:2048
	ds_read_b128 v[188:191], v162 offset:3072
	s_add_i32 s76, s48, 2
	s_add_u32 s49, s46, 0xfff00080
	s_addc_u32 s50, s47, -1
	s_cmp_eq_u32 s73, s48
	s_cselect_b32 s48, s29, s74
	s_cselect_b32 s51, s9, s50
	s_cselect_b32 s50, s27, s49
	s_cselect_b32 s49, s25, s75
	v_lshl_add_u64 v[192:193], s[46:47], 0, v[148:149]
	s_add_i32 m0, s43, 0xc000
	ds_read_b128 v[196:199], v163
	ds_read_b128 v[200:203], v163 offset:1024
	ds_read_b128 v[206:209], v163 offset:2048
	ds_read_b128 v[210:213], v163 offset:3072
	ds_read_b128 v[214:217], v163 offset:4096
	ds_read_b128 v[218:221], v163 offset:5120
	ds_read_b128 v[222:225], v163 offset:6144
	ds_read_b128 v[226:229], v163 offset:7168
	global_load_lds_dwordx4 v[192:193], off
	v_lshl_add_u64 v[192:193], s[46:47], 0, v[150:151]
	s_add_i32 m0, s43, 0xe000
	s_nop 0
	global_load_lds_dwordx4 v[192:193], off
	s_nop 0
	s_waitcnt vmcnt(8)
	s_waitcnt lgkmcnt(0)
	s_barrier
	s_setprio 1
	v_mfma_f32_16x16x32_bf16 v[78:81], v[156:159], v[196:199], v[78:81]
	v_mfma_f32_16x16x32_bf16 v[74:77], v[168:171], v[196:199], v[74:77]
	v_mfma_f32_16x16x32_bf16 v[70:73], v[156:159], v[206:209], v[70:73]
	v_mfma_f32_16x16x32_bf16 v[62:65], v[168:171], v[206:209], v[62:65]
	v_mfma_f32_16x16x32_bf16 v[58:61], v[156:159], v[214:217], v[58:61]
	v_mfma_f32_16x16x32_bf16 v[54:57], v[168:171], v[214:217], v[54:57]
	v_mfma_f32_16x16x32_bf16 v[46:49], v[156:159], v[222:225], v[46:49]
	v_mfma_f32_16x16x32_bf16 v[38:41], v[168:171], v[222:225], v[38:41]
	v_mfma_f32_16x16x32_bf16 v[78:81], v[164:167], v[200:203], v[78:81]
	v_mfma_f32_16x16x32_bf16 v[74:77], v[172:175], v[200:203], v[74:77]
	v_mfma_f32_16x16x32_bf16 v[70:73], v[164:167], v[210:213], v[70:73]
	v_mfma_f32_16x16x32_bf16 v[62:65], v[172:175], v[210:213], v[62:65]
	v_mfma_f32_16x16x32_bf16 v[58:61], v[164:167], v[218:221], v[58:61]
	v_mfma_f32_16x16x32_bf16 v[54:57], v[172:175], v[218:221], v[54:57]
	v_mfma_f32_16x16x32_bf16 v[46:49], v[164:167], v[226:229], v[46:49]
	v_mfma_f32_16x16x32_bf16 v[38:41], v[172:175], v[226:229], v[38:41]
	v_mfma_f32_16x16x32_bf16 v[50:53], v[176:179], v[196:199], v[50:53]
	v_mfma_f32_16x16x32_bf16 v[42:45], v[184:187], v[196:199], v[42:45]
	v_mfma_f32_16x16x32_bf16 v[34:37], v[176:179], v[206:209], v[34:37]
	v_mfma_f32_16x16x32_bf16 v[26:29], v[184:187], v[206:209], v[26:29]
	v_mfma_f32_16x16x32_bf16 v[18:21], v[176:179], v[214:217], v[18:21]
	v_mfma_f32_16x16x32_bf16 v[14:17], v[184:187], v[214:217], v[14:17]
	v_mfma_f32_16x16x32_bf16 v[10:13], v[176:179], v[222:225], v[10:13]
	v_mfma_f32_16x16x32_bf16 v[6:9], v[184:187], v[222:225], v[6:9]
	v_mfma_f32_16x16x32_bf16 v[50:53], v[180:183], v[200:203], v[50:53]
	v_mfma_f32_16x16x32_bf16 v[42:45], v[188:191], v[200:203], v[42:45]
	v_mfma_f32_16x16x32_bf16 v[34:37], v[180:183], v[210:213], v[34:37]
	v_mfma_f32_16x16x32_bf16 v[26:29], v[188:191], v[210:213], v[26:29]
	v_mfma_f32_16x16x32_bf16 v[18:21], v[180:183], v[218:221], v[18:21]
	v_mfma_f32_16x16x32_bf16 v[14:17], v[188:191], v[218:221], v[14:17]
	v_mfma_f32_16x16x32_bf16 v[10:13], v[180:183], v[226:229], v[10:13]
	v_mfma_f32_16x16x32_bf16 v[6:9], v[188:191], v[226:229], v[6:9]
	s_setprio 0
	s_barrier
	s_add_i32 s77, s66, s53
	v_lshl_add_u64 v[192:193], s[48:49], 0, v[134:135]
	s_mov_b32 m0, s77
	ds_read_b128 v[196:199], v163 offset:16384
	ds_read_b128 v[200:203], v163 offset:17408
	ds_read_b128 v[206:209], v163 offset:18432
	ds_read_b128 v[210:213], v163 offset:19456
	ds_read_b128 v[214:217], v163 offset:20480
	ds_read_b128 v[218:221], v163 offset:21504
	ds_read_b128 v[222:225], v163 offset:22528
	ds_read_b128 v[226:229], v163 offset:23552
	global_load_lds_dwordx4 v[192:193], off
	s_add_i32 m0, s77, 0x2000
	s_add_u32 s78, s48, 0x100000
	v_lshl_add_u64 v[230:231], s[48:49], 0, v[138:139]
	s_addc_u32 s79, s49, 0
	s_add_i32 s77, s67, s53
	global_load_lds_dwordx4 v[230:231], off
	v_lshl_add_u64 v[232:233], s[78:79], 0, v[134:135]
	s_mov_b32 m0, s77
	v_lshl_add_u64 v[234:235], s[50:51], 0, v[136:137]
	global_load_lds_dwordx4 v[232:233], off
	v_lshl_add_u64 v[232:233], s[78:79], 0, v[138:139]
	s_add_i32 m0, s77, 0x2000
	s_nop 0
	global_load_lds_dwordx4 v[232:233], off
	v_lshl_add_u64 v[232:233], s[50:51], 0, v[132:133]
	s_mov_b32 m0, s43
	s_nop 0
	global_load_lds_dwordx4 v[232:233], off
	s_mov_b32 m0, s54
	s_nop 0
	global_load_lds_dwordx4 v[234:235], off
	s_waitcnt vmcnt(8)
	s_waitcnt lgkmcnt(0)
	s_barrier
	s_setprio 1
	v_mfma_f32_16x16x32_bf16 v[126:129], v[156:159], v[196:199], v[126:129]
	v_mfma_f32_16x16x32_bf16 v[118:121], v[168:171], v[196:199], v[118:121]
	v_mfma_f32_16x16x32_bf16 v[110:113], v[156:159], v[206:209], v[110:113]
	v_mfma_f32_16x16x32_bf16 v[102:105], v[168:171], v[206:209], v[102:105]
	v_mfma_f32_16x16x32_bf16 v[94:97], v[156:159], v[214:217], v[94:97]
	v_mfma_f32_16x16x32_bf16 v[86:89], v[168:171], v[214:217], v[86:89]
	v_mfma_f32_16x16x32_bf16 v[66:69], v[156:159], v[222:225], v[66:69]
	v_mfma_f32_16x16x32_bf16 v[22:25], v[168:171], v[222:225], v[22:25]
	v_mfma_f32_16x16x32_bf16 v[126:129], v[164:167], v[200:203], v[126:129]
	v_mfma_f32_16x16x32_bf16 v[118:121], v[172:175], v[200:203], v[118:121]
	v_mfma_f32_16x16x32_bf16 v[110:113], v[164:167], v[210:213], v[110:113]
	v_mfma_f32_16x16x32_bf16 v[102:105], v[172:175], v[210:213], v[102:105]
	v_mfma_f32_16x16x32_bf16 v[94:97], v[164:167], v[218:221], v[94:97]
	v_mfma_f32_16x16x32_bf16 v[86:89], v[172:175], v[218:221], v[86:89]
	v_mfma_f32_16x16x32_bf16 v[66:69], v[164:167], v[226:229], v[66:69]
	v_mfma_f32_16x16x32_bf16 v[22:25], v[172:175], v[226:229], v[22:25]
	v_mfma_f32_16x16x32_bf16 v[122:125], v[176:179], v[196:199], v[122:125]
	v_mfma_f32_16x16x32_bf16 v[114:117], v[184:187], v[196:199], v[114:117]
	v_mfma_f32_16x16x32_bf16 v[106:109], v[176:179], v[206:209], v[106:109]
	v_mfma_f32_16x16x32_bf16 v[98:101], v[184:187], v[206:209], v[98:101]
	v_mfma_f32_16x16x32_bf16 v[90:93], v[176:179], v[214:217], v[90:93]
	v_mfma_f32_16x16x32_bf16 v[82:85], v[184:187], v[214:217], v[82:85]
	v_mfma_f32_16x16x32_bf16 v[30:33], v[176:179], v[222:225], v[30:33]
	v_mfma_f32_16x16x32_bf16 v[2:5], v[184:187], v[222:225], v[2:5]
	v_mfma_f32_16x16x32_bf16 v[122:125], v[180:183], v[200:203], v[122:125]
	v_mfma_f32_16x16x32_bf16 v[114:117], v[188:191], v[200:203], v[114:117]
	v_mfma_f32_16x16x32_bf16 v[106:109], v[180:183], v[210:213], v[106:109]
	v_mfma_f32_16x16x32_bf16 v[98:101], v[188:191], v[210:213], v[98:101]
	v_mfma_f32_16x16x32_bf16 v[90:93], v[180:183], v[218:221], v[90:93]
	v_mfma_f32_16x16x32_bf16 v[82:85], v[188:191], v[218:221], v[82:85]
	v_mfma_f32_16x16x32_bf16 v[30:33], v[180:183], v[226:229], v[30:33]
	v_mfma_f32_16x16x32_bf16 v[2:5], v[188:191], v[226:229], v[2:5]
	s_setprio 0
	s_barrier
	s_add_i32 s77, 0, 0x18000
	s_add_i32 s78, 0, 0x1c000
	v_add_u32_e32 v172, s77, v131
	v_add_u32_e32 v188, s78, v131
	ds_read_b128 v[156:159], v172
	ds_read_b128 v[164:167], v172 offset:1024
	ds_read_b128 v[168:171], v172 offset:2048
	ds_read_b128 v[172:175], v172 offset:3072
	ds_read_b128 v[176:179], v188
	ds_read_b128 v[180:183], v188 offset:1024
	ds_read_b128 v[184:187], v188 offset:2048
	ds_read_b128 v[188:191], v188 offset:3072
	s_add_u32 s50, s50, 0x100000
	s_addc_u32 s51, s51, 0
	s_mov_b32 m0, s55
	v_lshl_add_u64 v[236:237], s[50:51], 0, v[132:133]
	ds_read_b128 v[196:199], v163 offset:32768
	ds_read_b128 v[200:203], v163 offset:33792
	ds_read_b128 v[206:209], v163 offset:34816
	ds_read_b128 v[210:213], v163 offset:35840
	ds_read_b128 v[214:217], v163 offset:36864
	ds_read_b128 v[218:221], v163 offset:37888
	ds_read_b128 v[222:225], v163 offset:38912
	ds_read_b128 v[226:229], v163 offset:39936
	global_load_lds_dwordx4 v[236:237], off
	v_lshl_add_u64 v[236:237], s[50:51], 0, v[136:137]
	s_mov_b32 m0, s56
	s_nop 0
	global_load_lds_dwordx4 v[236:237], off
	s_waitcnt vmcnt(8)
	s_waitcnt lgkmcnt(0)
	s_barrier
	s_setprio 1
	v_mfma_f32_16x16x32_bf16 v[78:81], v[156:159], v[196:199], v[78:81]
	v_mfma_f32_16x16x32_bf16 v[74:77], v[168:171], v[196:199], v[74:77]
	v_mfma_f32_16x16x32_bf16 v[70:73], v[156:159], v[206:209], v[70:73]
	v_mfma_f32_16x16x32_bf16 v[62:65], v[168:171], v[206:209], v[62:65]
	v_mfma_f32_16x16x32_bf16 v[58:61], v[156:159], v[214:217], v[58:61]
	v_mfma_f32_16x16x32_bf16 v[54:57], v[168:171], v[214:217], v[54:57]
	v_mfma_f32_16x16x32_bf16 v[46:49], v[156:159], v[222:225], v[46:49]
	v_mfma_f32_16x16x32_bf16 v[38:41], v[168:171], v[222:225], v[38:41]
	v_mfma_f32_16x16x32_bf16 v[78:81], v[164:167], v[200:203], v[78:81]
	v_mfma_f32_16x16x32_bf16 v[74:77], v[172:175], v[200:203], v[74:77]
	v_mfma_f32_16x16x32_bf16 v[70:73], v[164:167], v[210:213], v[70:73]
	v_mfma_f32_16x16x32_bf16 v[62:65], v[172:175], v[210:213], v[62:65]
	v_mfma_f32_16x16x32_bf16 v[58:61], v[164:167], v[218:221], v[58:61]
	v_mfma_f32_16x16x32_bf16 v[54:57], v[172:175], v[218:221], v[54:57]
	v_mfma_f32_16x16x32_bf16 v[46:49], v[164:167], v[226:229], v[46:49]
	v_mfma_f32_16x16x32_bf16 v[38:41], v[172:175], v[226:229], v[38:41]
	v_mfma_f32_16x16x32_bf16 v[50:53], v[176:179], v[196:199], v[50:53]
	v_mfma_f32_16x16x32_bf16 v[42:45], v[184:187], v[196:199], v[42:45]
	v_mfma_f32_16x16x32_bf16 v[34:37], v[176:179], v[206:209], v[34:37]
	v_mfma_f32_16x16x32_bf16 v[26:29], v[184:187], v[206:209], v[26:29]
	v_mfma_f32_16x16x32_bf16 v[18:21], v[176:179], v[214:217], v[18:21]
	v_mfma_f32_16x16x32_bf16 v[14:17], v[184:187], v[214:217], v[14:17]
	v_mfma_f32_16x16x32_bf16 v[10:13], v[176:179], v[222:225], v[10:13]
	v_mfma_f32_16x16x32_bf16 v[6:9], v[184:187], v[222:225], v[6:9]
	v_mfma_f32_16x16x32_bf16 v[50:53], v[180:183], v[200:203], v[50:53]
	v_mfma_f32_16x16x32_bf16 v[42:45], v[188:191], v[200:203], v[42:45]
	v_mfma_f32_16x16x32_bf16 v[34:37], v[180:183], v[210:213], v[34:37]
	v_mfma_f32_16x16x32_bf16 v[26:29], v[188:191], v[210:213], v[26:29]
	v_mfma_f32_16x16x32_bf16 v[18:21], v[180:183], v[218:221], v[18:21]
	v_mfma_f32_16x16x32_bf16 v[14:17], v[188:191], v[218:221], v[14:17]
	v_mfma_f32_16x16x32_bf16 v[10:13], v[180:183], v[226:229], v[10:13]
	v_mfma_f32_16x16x32_bf16 v[6:9], v[188:191], v[226:229], v[6:9]
	s_setprio 0
	s_barrier
	s_add_i32 s50, s77, s53
	v_lshl_add_u64 v[192:193], v[192:193], 0, s[14:15]
	s_mov_b32 m0, s50
	ds_read_b128 v[196:199], v163 offset:49152
	ds_read_b128 v[200:203], v163 offset:50176
	ds_read_b128 v[206:209], v163 offset:51200
	ds_read_b128 v[210:213], v163 offset:52224
	ds_read_b128 v[214:217], v163 offset:53248
	ds_read_b128 v[218:221], v163 offset:54272
	ds_read_b128 v[222:225], v163 offset:55296
	ds_read_b128 v[226:229], v163 offset:56320
	global_load_lds_dwordx4 v[192:193], off
	s_add_i32 m0, s50, 0x2000
	s_add_u32 s48, s48, 0x100080
	v_lshl_add_u64 v[192:193], v[230:231], 0, s[14:15]
	s_addc_u32 s49, s49, 0
	s_add_i32 s50, s78, s53
	global_load_lds_dwordx4 v[192:193], off
	v_lshl_add_u64 v[192:193], s[48:49], 0, v[134:135]
	s_mov_b32 m0, s50
	s_nop 0
	global_load_lds_dwordx4 v[192:193], off
	v_lshl_add_u64 v[192:193], s[48:49], 0, v[138:139]
	s_add_i32 m0, s50, 0x2000
	s_nop 0
	global_load_lds_dwordx4 v[192:193], off
	v_lshl_add_u64 v[192:193], v[232:233], 0, s[14:15]
	s_mov_b32 m0, s59
	s_nop 0
	global_load_lds_dwordx4 v[192:193], off
	v_lshl_add_u64 v[192:193], v[234:235], 0, s[14:15]
	s_mov_b32 m0, s60
	s_nop 0
	global_load_lds_dwordx4 v[192:193], off
	s_nop 0
	s_waitcnt vmcnt(8)
	s_waitcnt lgkmcnt(0)
	s_barrier
	s_setprio 1
	v_mfma_f32_16x16x32_bf16 v[126:129], v[156:159], v[196:199], v[126:129]
	v_mfma_f32_16x16x32_bf16 v[118:121], v[168:171], v[196:199], v[118:121]
	v_mfma_f32_16x16x32_bf16 v[110:113], v[156:159], v[206:209], v[110:113]
	v_mfma_f32_16x16x32_bf16 v[102:105], v[168:171], v[206:209], v[102:105]
	v_mfma_f32_16x16x32_bf16 v[94:97], v[156:159], v[214:217], v[94:97]
	v_mfma_f32_16x16x32_bf16 v[86:89], v[168:171], v[214:217], v[86:89]
	v_mfma_f32_16x16x32_bf16 v[66:69], v[156:159], v[222:225], v[66:69]
	v_mfma_f32_16x16x32_bf16 v[22:25], v[168:171], v[222:225], v[22:25]
	v_mfma_f32_16x16x32_bf16 v[126:129], v[164:167], v[200:203], v[126:129]
	v_mfma_f32_16x16x32_bf16 v[118:121], v[172:175], v[200:203], v[118:121]
	v_mfma_f32_16x16x32_bf16 v[110:113], v[164:167], v[210:213], v[110:113]
	v_mfma_f32_16x16x32_bf16 v[102:105], v[172:175], v[210:213], v[102:105]
	v_mfma_f32_16x16x32_bf16 v[94:97], v[164:167], v[218:221], v[94:97]
	v_mfma_f32_16x16x32_bf16 v[86:89], v[172:175], v[218:221], v[86:89]
	v_mfma_f32_16x16x32_bf16 v[66:69], v[164:167], v[226:229], v[66:69]
	v_mfma_f32_16x16x32_bf16 v[22:25], v[172:175], v[226:229], v[22:25]
	v_mfma_f32_16x16x32_bf16 v[122:125], v[176:179], v[196:199], v[122:125]
	v_mfma_f32_16x16x32_bf16 v[114:117], v[184:187], v[196:199], v[114:117]
	v_mfma_f32_16x16x32_bf16 v[106:109], v[176:179], v[206:209], v[106:109]
	v_mfma_f32_16x16x32_bf16 v[98:101], v[184:187], v[206:209], v[98:101]
	v_mfma_f32_16x16x32_bf16 v[90:93], v[176:179], v[214:217], v[90:93]
	v_mfma_f32_16x16x32_bf16 v[82:85], v[184:187], v[214:217], v[82:85]
	v_mfma_f32_16x16x32_bf16 v[30:33], v[176:179], v[222:225], v[30:33]
	v_mfma_f32_16x16x32_bf16 v[2:5], v[184:187], v[222:225], v[2:5]
	v_mfma_f32_16x16x32_bf16 v[122:125], v[180:183], v[200:203], v[122:125]
	v_mfma_f32_16x16x32_bf16 v[114:117], v[188:191], v[200:203], v[114:117]
	v_mfma_f32_16x16x32_bf16 v[106:109], v[180:183], v[210:213], v[106:109]
	v_mfma_f32_16x16x32_bf16 v[98:101], v[188:191], v[210:213], v[98:101]
	v_mfma_f32_16x16x32_bf16 v[90:93], v[180:183], v[218:221], v[90:93]
	v_mfma_f32_16x16x32_bf16 v[82:85], v[188:191], v[218:221], v[82:85]
	v_mfma_f32_16x16x32_bf16 v[30:33], v[180:183], v[226:229], v[30:33]
	v_mfma_f32_16x16x32_bf16 v[2:5], v[188:191], v[226:229], v[2:5]
	s_setprio 0
	s_barrier
	s_add_u32 s46, s46, 0x100
	s_addc_u32 s47, s47, 0
	s_add_u32 s74, s74, 0x100
	s_addc_u32 s75, s75, 0
	s_cmp_ge_i32 s76, s72
	s_mov_b32 s48, s76
	s_cbranch_scc0 .LBB0_1553
	s_and_b64 vcc, exec, s[16:17]
	s_cbranch_vccz .LBB0_1558
	s_barrier
	s_cmp_lt_i32 s52, 0
	s_mov_b64 s[46:47], -1
	s_cbranch_scc1 .LBB0_1559

.LBB0_1712:
	ds_read_b128 v[152:155], v160
	ds_read_b128 v[164:167], v160 offset:1024
	ds_read_b128 v[168:171], v160 offset:2048
	ds_read_b128 v[172:175], v160 offset:3072
	ds_read_b128 v[176:179], v161
	ds_read_b128 v[180:183], v161 offset:1024
	ds_read_b128 v[184:187], v161 offset:2048
	ds_read_b128 v[188:191], v161 offset:3072
	s_add_i32 s82, s48, 2
	s_add_u32 s49, s52, 0xffd50080
	s_addc_u32 s54, s53, -1
	s_cmp_eq_u32 s47, s48
	s_cselect_b32 s48, s50, s80
	s_cselect_b32 s55, s9, s54
	s_cselect_b32 s54, s8, s49
	s_cselect_b32 s49, s51, s81
	v_lshl_add_u64 v[156:157], s[52:53], 0, v[140:141]
	s_add_i32 m0, s57, 0xc000
	ds_read_b128 v[196:199], v162
	ds_read_b128 v[200:203], v162 offset:1024
	ds_read_b128 v[206:209], v162 offset:2048
	ds_read_b128 v[210:213], v162 offset:3072
	ds_read_b128 v[214:217], v162 offset:4096
	ds_read_b128 v[218:221], v162 offset:5120
	ds_read_b128 v[222:225], v162 offset:6144
	ds_read_b128 v[226:229], v162 offset:7168
	global_load_lds_dwordx4 v[156:157], off
	v_lshl_add_u64 v[156:157], s[52:53], 0, v[142:143]
	s_add_i32 m0, s57, 0xe000
	s_nop 0
	global_load_lds_dwordx4 v[156:157], off
	s_waitcnt vmcnt(8)
	s_waitcnt lgkmcnt(0)
	s_barrier
	s_setprio 1
	v_mfma_f32_16x16x32_bf16 v[126:129], v[152:155], v[196:199], v[126:129]
	v_mfma_f32_16x16x32_bf16 v[122:125], v[168:171], v[196:199], v[122:125]
	v_mfma_f32_16x16x32_bf16 v[110:113], v[152:155], v[206:209], v[110:113]
	v_mfma_f32_16x16x32_bf16 v[106:109], v[168:171], v[206:209], v[106:109]
	v_mfma_f32_16x16x32_bf16 v[94:97], v[152:155], v[214:217], v[94:97]
	v_mfma_f32_16x16x32_bf16 v[90:93], v[168:171], v[214:217], v[90:93]
	v_mfma_f32_16x16x32_bf16 v[78:81], v[152:155], v[222:225], v[78:81]
	v_mfma_f32_16x16x32_bf16 v[74:77], v[168:171], v[222:225], v[74:77]
	v_mfma_f32_16x16x32_bf16 v[126:129], v[164:167], v[200:203], v[126:129]
	v_mfma_f32_16x16x32_bf16 v[122:125], v[172:175], v[200:203], v[122:125]
	v_mfma_f32_16x16x32_bf16 v[110:113], v[164:167], v[210:213], v[110:113]
	v_mfma_f32_16x16x32_bf16 v[106:109], v[172:175], v[210:213], v[106:109]
	v_mfma_f32_16x16x32_bf16 v[94:97], v[164:167], v[218:221], v[94:97]
	v_mfma_f32_16x16x32_bf16 v[90:93], v[172:175], v[218:221], v[90:93]
	v_mfma_f32_16x16x32_bf16 v[78:81], v[164:167], v[226:229], v[78:81]
	v_mfma_f32_16x16x32_bf16 v[74:77], v[172:175], v[226:229], v[74:77]
	v_mfma_f32_16x16x32_bf16 v[118:121], v[176:179], v[196:199], v[118:121]
	v_mfma_f32_16x16x32_bf16 v[114:117], v[184:187], v[196:199], v[114:117]
	v_mfma_f32_16x16x32_bf16 v[102:105], v[176:179], v[206:209], v[102:105]
	v_mfma_f32_16x16x32_bf16 v[98:101], v[184:187], v[206:209], v[98:101]
	v_mfma_f32_16x16x32_bf16 v[86:89], v[176:179], v[214:217], v[86:89]
	v_mfma_f32_16x16x32_bf16 v[82:85], v[184:187], v[214:217], v[82:85]
	v_mfma_f32_16x16x32_bf16 v[70:73], v[176:179], v[222:225], v[70:73]
	v_mfma_f32_16x16x32_bf16 v[66:69], v[184:187], v[222:225], v[66:69]
	v_mfma_f32_16x16x32_bf16 v[118:121], v[180:183], v[200:203], v[118:121]
	v_mfma_f32_16x16x32_bf16 v[114:117], v[188:191], v[200:203], v[114:117]
	v_mfma_f32_16x16x32_bf16 v[102:105], v[180:183], v[210:213], v[102:105]
	v_mfma_f32_16x16x32_bf16 v[98:101], v[188:191], v[210:213], v[98:101]
	v_mfma_f32_16x16x32_bf16 v[86:89], v[180:183], v[218:221], v[86:89]
	v_mfma_f32_16x16x32_bf16 v[82:85], v[188:191], v[218:221], v[82:85]
	v_mfma_f32_16x16x32_bf16 v[70:73], v[180:183], v[226:229], v[70:73]
	v_mfma_f32_16x16x32_bf16 v[66:69], v[188:191], v[226:229], v[66:69]
	s_setprio 0
	s_barrier
	s_add_i32 s83, s67, s56
	v_lshl_add_u64 v[156:157], s[48:49], 0, v[134:135]
	s_mov_b32 m0, s83
	ds_read_b128 v[196:199], v162 offset:16384
	ds_read_b128 v[200:203], v162 offset:17408
	ds_read_b128 v[206:209], v162 offset:18432
	ds_read_b128 v[210:213], v162 offset:19456
	ds_read_b128 v[214:217], v162 offset:20480
	ds_read_b128 v[218:221], v162 offset:21504
	ds_read_b128 v[222:225], v162 offset:22528
	ds_read_b128 v[226:229], v162 offset:23552
	global_load_lds_dwordx4 v[156:157], off
	s_add_i32 m0, s83, 0x2000
	s_add_u32 s84, s48, 0x2b0000
	v_lshl_add_u64 v[192:193], s[48:49], 0, v[138:139]
	s_addc_u32 s85, s49, 0
	s_add_i32 s83, s68, s56
	global_load_lds_dwordx4 v[192:193], off
	v_lshl_add_u64 v[230:231], s[84:85], 0, v[134:135]
	s_mov_b32 m0, s83
	v_lshl_add_u64 v[232:233], s[54:55], 0, v[136:137]
	global_load_lds_dwordx4 v[230:231], off
	v_lshl_add_u64 v[230:231], s[84:85], 0, v[138:139]
	s_add_i32 m0, s83, 0x2000
	s_nop 0
	global_load_lds_dwordx4 v[230:231], off
	v_lshl_add_u64 v[230:231], s[54:55], 0, v[132:133]
	s_mov_b32 m0, s57
	s_nop 0
	global_load_lds_dwordx4 v[230:231], off
	s_mov_b32 m0, s58
	s_nop 0
	global_load_lds_dwordx4 v[232:233], off
	s_waitcnt vmcnt(8)
	s_waitcnt lgkmcnt(0)
	s_barrier
	s_setprio 1
	v_mfma_f32_16x16x32_bf16 v[62:65], v[152:155], v[196:199], v[62:65]
	v_mfma_f32_16x16x32_bf16 v[58:61], v[168:171], v[196:199], v[58:61]
	v_mfma_f32_16x16x32_bf16 v[46:49], v[152:155], v[206:209], v[46:49]
	v_mfma_f32_16x16x32_bf16 v[42:45], v[168:171], v[206:209], v[42:45]
	v_mfma_f32_16x16x32_bf16 v[30:33], v[152:155], v[214:217], v[30:33]
	v_mfma_f32_16x16x32_bf16 v[26:29], v[168:171], v[214:217], v[26:29]
	v_mfma_f32_16x16x32_bf16 v[14:17], v[152:155], v[222:225], v[14:17]
	v_mfma_f32_16x16x32_bf16 v[10:13], v[168:171], v[222:225], v[10:13]
	v_mfma_f32_16x16x32_bf16 v[62:65], v[164:167], v[200:203], v[62:65]
	v_mfma_f32_16x16x32_bf16 v[58:61], v[172:175], v[200:203], v[58:61]
	v_mfma_f32_16x16x32_bf16 v[46:49], v[164:167], v[210:213], v[46:49]
	v_mfma_f32_16x16x32_bf16 v[42:45], v[172:175], v[210:213], v[42:45]
	v_mfma_f32_16x16x32_bf16 v[30:33], v[164:167], v[218:221], v[30:33]
	v_mfma_f32_16x16x32_bf16 v[26:29], v[172:175], v[218:221], v[26:29]
	v_mfma_f32_16x16x32_bf16 v[14:17], v[164:167], v[226:229], v[14:17]
	v_mfma_f32_16x16x32_bf16 v[10:13], v[172:175], v[226:229], v[10:13]
	v_mfma_f32_16x16x32_bf16 v[54:57], v[176:179], v[196:199], v[54:57]
	v_mfma_f32_16x16x32_bf16 v[50:53], v[184:187], v[196:199], v[50:53]
	v_mfma_f32_16x16x32_bf16 v[38:41], v[176:179], v[206:209], v[38:41]
	v_mfma_f32_16x16x32_bf16 v[34:37], v[184:187], v[206:209], v[34:37]
	v_mfma_f32_16x16x32_bf16 v[22:25], v[176:179], v[214:217], v[22:25]
	v_mfma_f32_16x16x32_bf16 v[18:21], v[184:187], v[214:217], v[18:21]
	v_mfma_f32_16x16x32_bf16 v[6:9], v[176:179], v[222:225], v[6:9]
	v_mfma_f32_16x16x32_bf16 v[2:5], v[184:187], v[222:225], v[2:5]
	v_mfma_f32_16x16x32_bf16 v[54:57], v[180:183], v[200:203], v[54:57]
	v_mfma_f32_16x16x32_bf16 v[50:53], v[188:191], v[200:203], v[50:53]
	v_mfma_f32_16x16x32_bf16 v[38:41], v[180:183], v[210:213], v[38:41]
	v_mfma_f32_16x16x32_bf16 v[34:37], v[188:191], v[210:213], v[34:37]
	v_mfma_f32_16x16x32_bf16 v[22:25], v[180:183], v[218:221], v[22:25]
	v_mfma_f32_16x16x32_bf16 v[18:21], v[188:191], v[218:221], v[18:21]
	v_mfma_f32_16x16x32_bf16 v[6:9], v[180:183], v[226:229], v[6:9]
	v_mfma_f32_16x16x32_bf16 v[2:5], v[188:191], v[226:229], v[2:5]
	s_setprio 0
	s_barrier
	s_add_i32 s83, 0, 0x18000
	v_add_u32_e32 v163, s83, v158
	s_add_i32 s84, 0, 0x1c000
	ds_read_b128 v[152:155], v163
	ds_read_b128 v[164:167], v163 offset:1024
	ds_read_b128 v[168:171], v163 offset:2048
	ds_read_b128 v[172:175], v163 offset:3072
	v_add_u32_e32 v163, s84, v158
	ds_read_b128 v[176:179], v163
	ds_read_b128 v[180:183], v163 offset:1024
	ds_read_b128 v[184:187], v163 offset:2048
	ds_read_b128 v[188:191], v163 offset:3072
	s_add_u32 s54, s54, 0x2b0000
	s_addc_u32 s55, s55, 0
	s_mov_b32 m0, s59
	v_lshl_add_u64 v[234:235], s[54:55], 0, v[132:133]
	ds_read_b128 v[196:199], v162 offset:32768
	ds_read_b128 v[200:203], v162 offset:33792
	ds_read_b128 v[206:209], v162 offset:34816
	ds_read_b128 v[210:213], v162 offset:35840
	ds_read_b128 v[214:217], v162 offset:36864
	ds_read_b128 v[218:221], v162 offset:37888
	ds_read_b128 v[222:225], v162 offset:38912
	ds_read_b128 v[226:229], v162 offset:39936
	global_load_lds_dwordx4 v[234:235], off
	v_lshl_add_u64 v[234:235], s[54:55], 0, v[136:137]
	s_mov_b32 m0, s60
	s_nop 0
	global_load_lds_dwordx4 v[234:235], off
	s_waitcnt vmcnt(8)
	s_waitcnt lgkmcnt(0)
	s_barrier
	s_setprio 1
	v_mfma_f32_16x16x32_bf16 v[126:129], v[152:155], v[196:199], v[126:129]
	v_mfma_f32_16x16x32_bf16 v[122:125], v[168:171], v[196:199], v[122:125]
	v_mfma_f32_16x16x32_bf16 v[110:113], v[152:155], v[206:209], v[110:113]
	v_mfma_f32_16x16x32_bf16 v[106:109], v[168:171], v[206:209], v[106:109]
	v_mfma_f32_16x16x32_bf16 v[94:97], v[152:155], v[214:217], v[94:97]
	v_mfma_f32_16x16x32_bf16 v[90:93], v[168:171], v[214:217], v[90:93]
	v_mfma_f32_16x16x32_bf16 v[78:81], v[152:155], v[222:225], v[78:81]
	v_mfma_f32_16x16x32_bf16 v[74:77], v[168:171], v[222:225], v[74:77]
	v_mfma_f32_16x16x32_bf16 v[126:129], v[164:167], v[200:203], v[126:129]
	v_mfma_f32_16x16x32_bf16 v[122:125], v[172:175], v[200:203], v[122:125]
	v_mfma_f32_16x16x32_bf16 v[110:113], v[164:167], v[210:213], v[110:113]
	v_mfma_f32_16x16x32_bf16 v[106:109], v[172:175], v[210:213], v[106:109]
	v_mfma_f32_16x16x32_bf16 v[94:97], v[164:167], v[218:221], v[94:97]
	v_mfma_f32_16x16x32_bf16 v[90:93], v[172:175], v[218:221], v[90:93]
	v_mfma_f32_16x16x32_bf16 v[78:81], v[164:167], v[226:229], v[78:81]
	v_mfma_f32_16x16x32_bf16 v[74:77], v[172:175], v[226:229], v[74:77]
	v_mfma_f32_16x16x32_bf16 v[118:121], v[176:179], v[196:199], v[118:121]
	v_mfma_f32_16x16x32_bf16 v[114:117], v[184:187], v[196:199], v[114:117]
	v_mfma_f32_16x16x32_bf16 v[102:105], v[176:179], v[206:209], v[102:105]
	v_mfma_f32_16x16x32_bf16 v[98:101], v[184:187], v[206:209], v[98:101]
	v_mfma_f32_16x16x32_bf16 v[86:89], v[176:179], v[214:217], v[86:89]
	v_mfma_f32_16x16x32_bf16 v[82:85], v[184:187], v[214:217], v[82:85]
	v_mfma_f32_16x16x32_bf16 v[70:73], v[176:179], v[222:225], v[70:73]
	v_mfma_f32_16x16x32_bf16 v[66:69], v[184:187], v[222:225], v[66:69]
	v_mfma_f32_16x16x32_bf16 v[118:121], v[180:183], v[200:203], v[118:121]
	v_mfma_f32_16x16x32_bf16 v[114:117], v[188:191], v[200:203], v[114:117]
	v_mfma_f32_16x16x32_bf16 v[102:105], v[180:183], v[210:213], v[102:105]
	v_mfma_f32_16x16x32_bf16 v[98:101], v[188:191], v[210:213], v[98:101]
	v_mfma_f32_16x16x32_bf16 v[86:89], v[180:183], v[218:221], v[86:89]
	v_mfma_f32_16x16x32_bf16 v[82:85], v[188:191], v[218:221], v[82:85]
	v_mfma_f32_16x16x32_bf16 v[70:73], v[180:183], v[226:229], v[70:73]
	v_mfma_f32_16x16x32_bf16 v[66:69], v[188:191], v[226:229], v[66:69]
	s_setprio 0
	s_barrier
	s_add_i32 s54, s83, s56
	v_lshl_add_u64 v[156:157], v[156:157], 0, s[18:19]
	s_mov_b32 m0, s54
	ds_read_b128 v[196:199], v162 offset:49152
	ds_read_b128 v[200:203], v162 offset:50176
	ds_read_b128 v[206:209], v162 offset:51200
	ds_read_b128 v[210:213], v162 offset:52224
	ds_read_b128 v[214:217], v162 offset:53248
	ds_read_b128 v[218:221], v162 offset:54272
	ds_read_b128 v[222:225], v162 offset:55296
	ds_read_b128 v[226:229], v162 offset:56320
	global_load_lds_dwordx4 v[156:157], off
	s_add_i32 m0, s54, 0x2000
	s_add_u32 s48, s48, 0x2b0080
	v_lshl_add_u64 v[156:157], v[192:193], 0, s[18:19]
	s_addc_u32 s49, s49, 0
	s_add_i32 s54, s84, s56
	global_load_lds_dwordx4 v[156:157], off
	v_lshl_add_u64 v[156:157], s[48:49], 0, v[134:135]
	s_mov_b32 m0, s54
	s_nop 0
	global_load_lds_dwordx4 v[156:157], off
	v_lshl_add_u64 v[156:157], s[48:49], 0, v[138:139]
	s_add_i32 m0, s54, 0x2000
	s_nop 0
	global_load_lds_dwordx4 v[156:157], off
	v_lshl_add_u64 v[156:157], v[230:231], 0, s[18:19]
	s_mov_b32 m0, s64
	s_nop 0
	global_load_lds_dwordx4 v[156:157], off
	v_lshl_add_u64 v[156:157], v[232:233], 0, s[18:19]
	s_mov_b32 m0, s65
	s_nop 0
	global_load_lds_dwordx4 v[156:157], off
	s_nop 0
	s_waitcnt vmcnt(8)
	s_waitcnt lgkmcnt(0)
	s_barrier
	s_setprio 1
	v_mfma_f32_16x16x32_bf16 v[62:65], v[152:155], v[196:199], v[62:65]
	v_mfma_f32_16x16x32_bf16 v[58:61], v[168:171], v[196:199], v[58:61]
	v_mfma_f32_16x16x32_bf16 v[46:49], v[152:155], v[206:209], v[46:49]
	v_mfma_f32_16x16x32_bf16 v[42:45], v[168:171], v[206:209], v[42:45]
	v_mfma_f32_16x16x32_bf16 v[30:33], v[152:155], v[214:217], v[30:33]
	v_mfma_f32_16x16x32_bf16 v[26:29], v[168:171], v[214:217], v[26:29]
	v_mfma_f32_16x16x32_bf16 v[14:17], v[152:155], v[222:225], v[14:17]
	v_mfma_f32_16x16x32_bf16 v[10:13], v[168:171], v[222:225], v[10:13]
	v_mfma_f32_16x16x32_bf16 v[62:65], v[164:167], v[200:203], v[62:65]
	v_mfma_f32_16x16x32_bf16 v[58:61], v[172:175], v[200:203], v[58:61]
	v_mfma_f32_16x16x32_bf16 v[46:49], v[164:167], v[210:213], v[46:49]
	v_mfma_f32_16x16x32_bf16 v[42:45], v[172:175], v[210:213], v[42:45]
	v_mfma_f32_16x16x32_bf16 v[30:33], v[164:167], v[218:221], v[30:33]
	v_mfma_f32_16x16x32_bf16 v[26:29], v[172:175], v[218:221], v[26:29]
	v_mfma_f32_16x16x32_bf16 v[14:17], v[164:167], v[226:229], v[14:17]
	v_mfma_f32_16x16x32_bf16 v[10:13], v[172:175], v[226:229], v[10:13]
	v_mfma_f32_16x16x32_bf16 v[54:57], v[176:179], v[196:199], v[54:57]
	v_mfma_f32_16x16x32_bf16 v[50:53], v[184:187], v[196:199], v[50:53]
	v_mfma_f32_16x16x32_bf16 v[38:41], v[176:179], v[206:209], v[38:41]
	v_mfma_f32_16x16x32_bf16 v[34:37], v[184:187], v[206:209], v[34:37]
	v_mfma_f32_16x16x32_bf16 v[22:25], v[176:179], v[214:217], v[22:25]
	v_mfma_f32_16x16x32_bf16 v[18:21], v[184:187], v[214:217], v[18:21]
	v_mfma_f32_16x16x32_bf16 v[6:9], v[176:179], v[222:225], v[6:9]
	v_mfma_f32_16x16x32_bf16 v[2:5], v[184:187], v[222:225], v[2:5]
	v_mfma_f32_16x16x32_bf16 v[54:57], v[180:183], v[200:203], v[54:57]
	v_mfma_f32_16x16x32_bf16 v[50:53], v[188:191], v[200:203], v[50:53]
	v_mfma_f32_16x16x32_bf16 v[38:41], v[180:183], v[210:213], v[38:41]
	v_mfma_f32_16x16x32_bf16 v[34:37], v[188:191], v[210:213], v[34:37]
	v_mfma_f32_16x16x32_bf16 v[22:25], v[180:183], v[218:221], v[22:25]
	v_mfma_f32_16x16x32_bf16 v[18:21], v[188:191], v[218:221], v[18:21]
	v_mfma_f32_16x16x32_bf16 v[6:9], v[180:183], v[226:229], v[6:9]
	v_mfma_f32_16x16x32_bf16 v[2:5], v[188:191], v[226:229], v[2:5]
	s_setprio 0
	s_barrier
	s_add_u32 s52, s52, 0x100
	s_addc_u32 s53, s53, 0
	s_add_u32 s80, s80, 0x100
	s_addc_u32 s81, s81, 0
	s_cmp_ge_i32 s82, s78
	s_mov_b32 s48, s82
	s_cbranch_scc0 .LBB0_1712
	s_and_b64 vcc, exec, s[20:21]
	s_cbranch_vccz .LBB0_1715
	s_barrier

.LBB0_1869:
	ds_read_b128 v[162:165], v168
	s_waitcnt vmcnt(0)
	ds_read_b128 v[172:175], v168 offset:1024
	ds_read_b128 v[176:179], v168 offset:2048
	ds_read_b128 v[180:183], v168 offset:3072
	ds_read_b128 v[184:187], v169
	ds_read_b128 v[188:191], v169 offset:1024
	ds_read_b128 v[196:199], v169 offset:2048
	ds_read_b128 v[200:203], v169 offset:3072
	s_add_i32 s55, s42, 2
	s_add_u32 s43, s8, 0xfff00080
	s_addc_u32 s46, s9, -1
	s_cmp_eq_u32 s48, s42
	s_cselect_b32 s42, s41, s49
	s_cselect_b32 s47, s31, s46
	s_cselect_b32 s46, s33, s43
	s_cselect_b32 s43, s35, s53
	v_lshl_add_u64 v[166:167], s[8:9], 0, v[150:151]
	s_add_i32 m0, s62, 0xc000
	ds_read_b128 v[206:209], v170
	ds_read_b128 v[210:213], v170 offset:1024
	ds_read_b128 v[214:217], v170 offset:2048
	ds_read_b128 v[218:221], v170 offset:3072
	ds_read_b128 v[222:225], v170 offset:4096
	ds_read_b128 v[226:229], v170 offset:5120
	ds_read_b128 v[230:233], v170 offset:6144
	ds_read_b128 v[234:237], v170 offset:7168
	global_load_lds_dwordx4 v[166:167], off
	v_lshl_add_u64 v[166:167], s[8:9], 0, v[152:153]
	s_add_i32 m0, s62, 0xe000
	s_nop 0
	global_load_lds_dwordx4 v[166:167], off
	s_waitcnt vmcnt(8)
	s_waitcnt lgkmcnt(0)
	s_barrier
	s_setprio 1
	v_mfma_f32_16x16x32_bf16 v[66:69], v[162:165], v[206:209], v[66:69]
	v_mfma_f32_16x16x32_bf16 v[62:65], v[176:179], v[206:209], v[62:65]
	v_mfma_f32_16x16x32_bf16 v[58:61], v[162:165], v[214:217], v[58:61]
	v_mfma_f32_16x16x32_bf16 v[54:57], v[176:179], v[214:217], v[54:57]
	v_mfma_f32_16x16x32_bf16 v[50:53], v[162:165], v[222:225], v[50:53]
	v_mfma_f32_16x16x32_bf16 v[46:49], v[176:179], v[222:225], v[46:49]
	v_mfma_f32_16x16x32_bf16 v[38:41], v[162:165], v[230:233], v[38:41]
	v_mfma_f32_16x16x32_bf16 v[30:33], v[176:179], v[230:233], v[30:33]
	v_mfma_f32_16x16x32_bf16 v[66:69], v[172:175], v[210:213], v[66:69]
	v_mfma_f32_16x16x32_bf16 v[62:65], v[180:183], v[210:213], v[62:65]
	v_mfma_f32_16x16x32_bf16 v[58:61], v[172:175], v[218:221], v[58:61]
	v_mfma_f32_16x16x32_bf16 v[54:57], v[180:183], v[218:221], v[54:57]
	v_mfma_f32_16x16x32_bf16 v[50:53], v[172:175], v[226:229], v[50:53]
	v_mfma_f32_16x16x32_bf16 v[46:49], v[180:183], v[226:229], v[46:49]
	v_mfma_f32_16x16x32_bf16 v[38:41], v[172:175], v[234:237], v[38:41]
	v_mfma_f32_16x16x32_bf16 v[30:33], v[180:183], v[234:237], v[30:33]
	v_mfma_f32_16x16x32_bf16 v[42:45], v[184:187], v[206:209], v[42:45]
	v_mfma_f32_16x16x32_bf16 v[34:37], v[196:199], v[206:209], v[34:37]
	v_mfma_f32_16x16x32_bf16 v[26:29], v[184:187], v[214:217], v[26:29]
	v_mfma_f32_16x16x32_bf16 v[22:25], v[196:199], v[214:217], v[22:25]
	v_mfma_f32_16x16x32_bf16 v[18:21], v[184:187], v[222:225], v[18:21]
	v_mfma_f32_16x16x32_bf16 v[14:17], v[196:199], v[222:225], v[14:17]
	v_mfma_f32_16x16x32_bf16 v[10:13], v[184:187], v[230:233], v[10:13]
	v_mfma_f32_16x16x32_bf16 v[6:9], v[196:199], v[230:233], v[6:9]
	v_mfma_f32_16x16x32_bf16 v[42:45], v[188:191], v[210:213], v[42:45]
	v_mfma_f32_16x16x32_bf16 v[34:37], v[200:203], v[210:213], v[34:37]
	v_mfma_f32_16x16x32_bf16 v[26:29], v[188:191], v[218:221], v[26:29]
	v_mfma_f32_16x16x32_bf16 v[22:25], v[200:203], v[218:221], v[22:25]
	v_mfma_f32_16x16x32_bf16 v[18:21], v[188:191], v[226:229], v[18:21]
	v_mfma_f32_16x16x32_bf16 v[14:17], v[200:203], v[226:229], v[14:17]
	v_mfma_f32_16x16x32_bf16 v[10:13], v[188:191], v[234:237], v[10:13]
	v_mfma_f32_16x16x32_bf16 v[6:9], v[200:203], v[234:237], v[6:9]
	s_setprio 0
	s_barrier
	s_add_i32 s80, s72, s61
	v_lshl_add_u64 v[166:167], s[42:43], 0, v[134:135]
	s_mov_b32 m0, s80
	ds_read_b128 v[206:209], v170 offset:16384
	ds_read_b128 v[210:213], v170 offset:17408
	ds_read_b128 v[214:217], v170 offset:18432
	ds_read_b128 v[218:221], v170 offset:19456
	ds_read_b128 v[222:225], v170 offset:20480
	ds_read_b128 v[226:229], v170 offset:21504
	ds_read_b128 v[230:233], v170 offset:22528
	ds_read_b128 v[234:237], v170 offset:23552
	global_load_lds_dwordx4 v[166:167], off
	s_add_i32 m0, s80, 0x2000
	s_add_u32 s80, s42, 0x100000
	v_lshl_add_u64 v[192:193], s[42:43], 0, v[138:139]
	s_addc_u32 s81, s43, 0
	s_add_i32 s82, s73, s61
	global_load_lds_dwordx4 v[192:193], off
	v_lshl_add_u64 v[238:239], s[80:81], 0, v[134:135]
	s_mov_b32 m0, s82
	v_lshl_add_u64 v[240:241], s[46:47], 0, v[136:137]
	global_load_lds_dwordx4 v[238:239], off
	v_lshl_add_u64 v[238:239], s[80:81], 0, v[138:139]
	s_add_i32 m0, s82, 0x2000
	s_nop 0
	global_load_lds_dwordx4 v[238:239], off
	v_lshl_add_u64 v[238:239], s[46:47], 0, v[132:133]
	s_mov_b32 m0, s62
	s_nop 0
	global_load_lds_dwordx4 v[238:239], off
	s_mov_b32 m0, s63
	s_nop 0
	global_load_lds_dwordx4 v[240:241], off
	s_waitcnt vmcnt(8)
	s_waitcnt lgkmcnt(0)
	s_barrier
	s_setprio 1
	v_mfma_f32_16x16x32_bf16 v[126:129], v[162:165], v[206:209], v[126:129]
	v_mfma_f32_16x16x32_bf16 v[122:125], v[176:179], v[206:209], v[122:125]
	v_mfma_f32_16x16x32_bf16 v[110:113], v[162:165], v[214:217], v[110:113]
	v_mfma_f32_16x16x32_bf16 v[106:109], v[176:179], v[214:217], v[106:109]
	v_mfma_f32_16x16x32_bf16 v[94:97], v[162:165], v[222:225], v[94:97]
	v_mfma_f32_16x16x32_bf16 v[90:93], v[176:179], v[222:225], v[90:93]
	v_mfma_f32_16x16x32_bf16 v[78:81], v[162:165], v[230:233], v[78:81]
	v_mfma_f32_16x16x32_bf16 v[74:77], v[176:179], v[230:233], v[74:77]
	v_mfma_f32_16x16x32_bf16 v[126:129], v[172:175], v[210:213], v[126:129]
	v_mfma_f32_16x16x32_bf16 v[122:125], v[180:183], v[210:213], v[122:125]
	v_mfma_f32_16x16x32_bf16 v[110:113], v[172:175], v[218:221], v[110:113]
	v_mfma_f32_16x16x32_bf16 v[106:109], v[180:183], v[218:221], v[106:109]
	v_mfma_f32_16x16x32_bf16 v[94:97], v[172:175], v[226:229], v[94:97]
	v_mfma_f32_16x16x32_bf16 v[90:93], v[180:183], v[226:229], v[90:93]
	v_mfma_f32_16x16x32_bf16 v[78:81], v[172:175], v[234:237], v[78:81]
	v_mfma_f32_16x16x32_bf16 v[74:77], v[180:183], v[234:237], v[74:77]
	v_mfma_f32_16x16x32_bf16 v[118:121], v[184:187], v[206:209], v[118:121]
	v_mfma_f32_16x16x32_bf16 v[114:117], v[196:199], v[206:209], v[114:117]
	v_mfma_f32_16x16x32_bf16 v[102:105], v[184:187], v[214:217], v[102:105]
	v_mfma_f32_16x16x32_bf16 v[98:101], v[196:199], v[214:217], v[98:101]
	v_mfma_f32_16x16x32_bf16 v[86:89], v[184:187], v[222:225], v[86:89]
	v_mfma_f32_16x16x32_bf16 v[82:85], v[196:199], v[222:225], v[82:85]
	v_mfma_f32_16x16x32_bf16 v[70:73], v[184:187], v[230:233], v[70:73]
	v_mfma_f32_16x16x32_bf16 v[2:5], v[196:199], v[230:233], v[2:5]
	v_mfma_f32_16x16x32_bf16 v[118:121], v[188:191], v[210:213], v[118:121]
	v_mfma_f32_16x16x32_bf16 v[114:117], v[200:203], v[210:213], v[114:117]
	v_mfma_f32_16x16x32_bf16 v[102:105], v[188:191], v[218:221], v[102:105]
	v_mfma_f32_16x16x32_bf16 v[98:101], v[200:203], v[218:221], v[98:101]
	v_mfma_f32_16x16x32_bf16 v[86:89], v[188:191], v[226:229], v[86:89]
	v_mfma_f32_16x16x32_bf16 v[82:85], v[200:203], v[226:229], v[82:85]
	v_mfma_f32_16x16x32_bf16 v[70:73], v[188:191], v[234:237], v[70:73]
	v_mfma_f32_16x16x32_bf16 v[2:5], v[200:203], v[234:237], v[2:5]
	s_setprio 0
	s_barrier
	s_add_i32 s80, 0, 0x18000
	s_add_i32 s81, 0, 0x1c000
	v_add_u32_e32 v180, s80, v131
	v_add_u32_e32 v200, s81, v131
	ds_read_b128 v[162:165], v180
	ds_read_b128 v[172:175], v180 offset:1024
	ds_read_b128 v[176:179], v180 offset:2048
	ds_read_b128 v[180:183], v180 offset:3072
	ds_read_b128 v[184:187], v200
	ds_read_b128 v[188:191], v200 offset:1024
	ds_read_b128 v[196:199], v200 offset:2048
	ds_read_b128 v[200:203], v200 offset:3072
	s_add_u32 s46, s46, 0x100000
	s_addc_u32 s47, s47, 0
	s_mov_b32 m0, s64
	v_lshl_add_u64 v[242:243], s[46:47], 0, v[132:133]
	ds_read_b128 v[206:209], v170 offset:32768
	ds_read_b128 v[210:213], v170 offset:33792
	ds_read_b128 v[214:217], v170 offset:34816
	ds_read_b128 v[218:221], v170 offset:35840
	ds_read_b128 v[222:225], v170 offset:36864
	ds_read_b128 v[226:229], v170 offset:37888
	ds_read_b128 v[230:233], v170 offset:38912
	ds_read_b128 v[234:237], v170 offset:39936
	global_load_lds_dwordx4 v[242:243], off
	v_lshl_add_u64 v[242:243], s[46:47], 0, v[136:137]
	s_mov_b32 m0, s65
	s_nop 0
	global_load_lds_dwordx4 v[242:243], off
	s_waitcnt vmcnt(8)
	s_waitcnt lgkmcnt(0)
	s_barrier
	s_setprio 1
	v_mfma_f32_16x16x32_bf16 v[66:69], v[162:165], v[206:209], v[66:69]
	v_mfma_f32_16x16x32_bf16 v[62:65], v[176:179], v[206:209], v[62:65]
	v_mfma_f32_16x16x32_bf16 v[58:61], v[162:165], v[214:217], v[58:61]
	v_mfma_f32_16x16x32_bf16 v[54:57], v[176:179], v[214:217], v[54:57]
	v_mfma_f32_16x16x32_bf16 v[50:53], v[162:165], v[222:225], v[50:53]
	v_mfma_f32_16x16x32_bf16 v[46:49], v[176:179], v[222:225], v[46:49]
	v_mfma_f32_16x16x32_bf16 v[38:41], v[162:165], v[230:233], v[38:41]
	v_mfma_f32_16x16x32_bf16 v[30:33], v[176:179], v[230:233], v[30:33]
	v_mfma_f32_16x16x32_bf16 v[66:69], v[172:175], v[210:213], v[66:69]
	v_mfma_f32_16x16x32_bf16 v[62:65], v[180:183], v[210:213], v[62:65]
	v_mfma_f32_16x16x32_bf16 v[58:61], v[172:175], v[218:221], v[58:61]
	v_mfma_f32_16x16x32_bf16 v[54:57], v[180:183], v[218:221], v[54:57]
	v_mfma_f32_16x16x32_bf16 v[50:53], v[172:175], v[226:229], v[50:53]
	v_mfma_f32_16x16x32_bf16 v[46:49], v[180:183], v[226:229], v[46:49]
	v_mfma_f32_16x16x32_bf16 v[38:41], v[172:175], v[234:237], v[38:41]
	v_mfma_f32_16x16x32_bf16 v[30:33], v[180:183], v[234:237], v[30:33]
	v_mfma_f32_16x16x32_bf16 v[42:45], v[184:187], v[206:209], v[42:45]
	v_mfma_f32_16x16x32_bf16 v[34:37], v[196:199], v[206:209], v[34:37]
	v_mfma_f32_16x16x32_bf16 v[26:29], v[184:187], v[214:217], v[26:29]
	v_mfma_f32_16x16x32_bf16 v[22:25], v[196:199], v[214:217], v[22:25]
	v_mfma_f32_16x16x32_bf16 v[18:21], v[184:187], v[222:225], v[18:21]
	v_mfma_f32_16x16x32_bf16 v[14:17], v[196:199], v[222:225], v[14:17]
	v_mfma_f32_16x16x32_bf16 v[10:13], v[184:187], v[230:233], v[10:13]
	v_mfma_f32_16x16x32_bf16 v[6:9], v[196:199], v[230:233], v[6:9]
	v_mfma_f32_16x16x32_bf16 v[42:45], v[188:191], v[210:213], v[42:45]
	v_mfma_f32_16x16x32_bf16 v[34:37], v[200:203], v[210:213], v[34:37]
	v_mfma_f32_16x16x32_bf16 v[26:29], v[188:191], v[218:221], v[26:29]
	v_mfma_f32_16x16x32_bf16 v[22:25], v[200:203], v[218:221], v[22:25]
	v_mfma_f32_16x16x32_bf16 v[18:21], v[188:191], v[226:229], v[18:21]
	v_mfma_f32_16x16x32_bf16 v[14:17], v[200:203], v[226:229], v[14:17]
	v_mfma_f32_16x16x32_bf16 v[10:13], v[188:191], v[234:237], v[10:13]
	v_mfma_f32_16x16x32_bf16 v[6:9], v[200:203], v[234:237], v[6:9]
	s_setprio 0
	s_barrier
	s_add_i32 s46, s80, s61
	v_lshl_add_u64 v[166:167], v[166:167], 0, s[18:19]
	s_mov_b32 m0, s46
	ds_read_b128 v[206:209], v170 offset:49152
	ds_read_b128 v[210:213], v170 offset:50176
	ds_read_b128 v[214:217], v170 offset:51200
	ds_read_b128 v[218:221], v170 offset:52224
	ds_read_b128 v[222:225], v170 offset:53248
	ds_read_b128 v[226:229], v170 offset:54272
	ds_read_b128 v[230:233], v170 offset:55296
	ds_read_b128 v[234:237], v170 offset:56320
	global_load_lds_dwordx4 v[166:167], off
	s_add_i32 m0, s46, 0x2000
	s_add_u32 s42, s42, 0x100080
	v_lshl_add_u64 v[166:167], v[192:193], 0, s[18:19]
	s_addc_u32 s43, s43, 0
	s_add_i32 s46, s81, s61
	global_load_lds_dwordx4 v[166:167], off
	v_lshl_add_u64 v[166:167], s[42:43], 0, v[134:135]
	s_mov_b32 m0, s46
	s_nop 0
	global_load_lds_dwordx4 v[166:167], off
	v_lshl_add_u64 v[166:167], s[42:43], 0, v[138:139]
	s_add_i32 m0, s46, 0x2000
	s_nop 0
	global_load_lds_dwordx4 v[166:167], off
	v_lshl_add_u64 v[166:167], v[238:239], 0, s[18:19]
	s_mov_b32 m0, s69
	s_nop 0
	global_load_lds_dwordx4 v[166:167], off
	v_lshl_add_u64 v[166:167], v[240:241], 0, s[18:19]
	s_mov_b32 m0, s70
	s_nop 0
	global_load_lds_dwordx4 v[166:167], off
	s_nop 0
	s_waitcnt vmcnt(8)
	s_waitcnt lgkmcnt(0)
	s_barrier
	s_setprio 1
	v_mfma_f32_16x16x32_bf16 v[126:129], v[162:165], v[206:209], v[126:129]
	v_mfma_f32_16x16x32_bf16 v[122:125], v[176:179], v[206:209], v[122:125]
	v_mfma_f32_16x16x32_bf16 v[110:113], v[162:165], v[214:217], v[110:113]
	v_mfma_f32_16x16x32_bf16 v[106:109], v[176:179], v[214:217], v[106:109]
	v_mfma_f32_16x16x32_bf16 v[94:97], v[162:165], v[222:225], v[94:97]
	v_mfma_f32_16x16x32_bf16 v[90:93], v[176:179], v[222:225], v[90:93]
	v_mfma_f32_16x16x32_bf16 v[78:81], v[162:165], v[230:233], v[78:81]
	v_mfma_f32_16x16x32_bf16 v[74:77], v[176:179], v[230:233], v[74:77]
	v_mfma_f32_16x16x32_bf16 v[126:129], v[172:175], v[210:213], v[126:129]
	v_mfma_f32_16x16x32_bf16 v[122:125], v[180:183], v[210:213], v[122:125]
	v_mfma_f32_16x16x32_bf16 v[110:113], v[172:175], v[218:221], v[110:113]
	v_mfma_f32_16x16x32_bf16 v[106:109], v[180:183], v[218:221], v[106:109]
	v_mfma_f32_16x16x32_bf16 v[94:97], v[172:175], v[226:229], v[94:97]
	v_mfma_f32_16x16x32_bf16 v[90:93], v[180:183], v[226:229], v[90:93]
	v_mfma_f32_16x16x32_bf16 v[78:81], v[172:175], v[234:237], v[78:81]
	v_mfma_f32_16x16x32_bf16 v[74:77], v[180:183], v[234:237], v[74:77]
	v_mfma_f32_16x16x32_bf16 v[118:121], v[184:187], v[206:209], v[118:121]
	v_mfma_f32_16x16x32_bf16 v[114:117], v[196:199], v[206:209], v[114:117]
	v_mfma_f32_16x16x32_bf16 v[102:105], v[184:187], v[214:217], v[102:105]
	v_mfma_f32_16x16x32_bf16 v[98:101], v[196:199], v[214:217], v[98:101]
	v_mfma_f32_16x16x32_bf16 v[86:89], v[184:187], v[222:225], v[86:89]
	v_mfma_f32_16x16x32_bf16 v[82:85], v[196:199], v[222:225], v[82:85]
	v_mfma_f32_16x16x32_bf16 v[70:73], v[184:187], v[230:233], v[70:73]
	v_mfma_f32_16x16x32_bf16 v[2:5], v[196:199], v[230:233], v[2:5]
	v_mfma_f32_16x16x32_bf16 v[118:121], v[188:191], v[210:213], v[118:121]
	v_mfma_f32_16x16x32_bf16 v[114:117], v[200:203], v[210:213], v[114:117]
	v_mfma_f32_16x16x32_bf16 v[102:105], v[188:191], v[218:221], v[102:105]
	v_mfma_f32_16x16x32_bf16 v[98:101], v[200:203], v[218:221], v[98:101]
	v_mfma_f32_16x16x32_bf16 v[86:89], v[188:191], v[226:229], v[86:89]
	v_mfma_f32_16x16x32_bf16 v[82:85], v[200:203], v[226:229], v[82:85]
	v_mfma_f32_16x16x32_bf16 v[70:73], v[188:191], v[234:237], v[70:73]
	v_mfma_f32_16x16x32_bf16 v[2:5], v[200:203], v[234:237], v[2:5]
	s_setprio 0
	s_barrier
	s_add_u32 s8, s8, 0x100
	s_addc_u32 s9, s9, 0
	s_add_u32 s49, s49, 0x100
	s_addc_u32 s53, s53, 0
	s_cmp_ge_i32 s55, s3
	s_mov_b32 s42, s55
	s_cbranch_scc0 .LBB0_1869
	s_and_b64 vcc, exec, s[20:21]
	s_cbranch_vccz .LBB0_1874
	s_barrier
	v_lshl_or_b32 v162, s40, 8, v141
	s_cmp_lt_i32 s10, 0
	s_mov_b64 s[8:9], -1
	s_cbranch_scc1 .LBB0_1875

.LBB0_3649:
	ds_read_b128 v[152:155], v162
	ds_read_b128 v[156:159], v162 offset:1024
	ds_read_b128 v[168:171], v162 offset:2048
	ds_read_b128 v[172:175], v162 offset:3072
	ds_read_b128 v[176:179], v163
	ds_read_b128 v[180:183], v163 offset:1024
	ds_read_b128 v[184:187], v163 offset:2048
	ds_read_b128 v[188:191], v163 offset:3072
	s_add_i32 s86, s48, 2
	s_add_u32 s49, s6, 0xfff00080
	s_addc_u32 s64, s7, -1
	s_cmp_eq_u32 s51, s48
	s_cselect_b32 s48, s58, s53
	s_cselect_b32 s65, s57, s64
	s_cselect_b32 s64, s56, s49
	s_cselect_b32 s49, s59, s55
	v_lshl_add_u64 v[192:193], s[6:7], 0, v[140:141]
	s_add_i32 m0, s61, 0xc000
	ds_read_b128 v[196:199], v164
	ds_read_b128 v[200:203], v164 offset:1024
	ds_read_b128 v[206:209], v164 offset:2048
	ds_read_b128 v[210:213], v164 offset:3072
	ds_read_b128 v[214:217], v164 offset:4096
	ds_read_b128 v[218:221], v164 offset:5120
	ds_read_b128 v[222:225], v164 offset:6144
	ds_read_b128 v[226:229], v164 offset:7168
	global_load_lds_dwordx4 v[192:193], off
	v_lshl_add_u64 v[192:193], s[6:7], 0, v[142:143]
	s_add_i32 m0, s61, 0xe000
	s_nop 0
	global_load_lds_dwordx4 v[192:193], off
	s_nop 0
	s_waitcnt vmcnt(8)
	s_waitcnt lgkmcnt(0)
	s_barrier
	s_setprio 1
	v_mfma_f32_16x16x32_bf16 v[126:129], v[152:155], v[196:199], v[126:129]
	v_mfma_f32_16x16x32_bf16 v[122:125], v[168:171], v[196:199], v[122:125]
	v_mfma_f32_16x16x32_bf16 v[110:113], v[152:155], v[206:209], v[110:113]
	v_mfma_f32_16x16x32_bf16 v[106:109], v[168:171], v[206:209], v[106:109]
	v_mfma_f32_16x16x32_bf16 v[94:97], v[152:155], v[214:217], v[94:97]
	v_mfma_f32_16x16x32_bf16 v[90:93], v[168:171], v[214:217], v[90:93]
	v_mfma_f32_16x16x32_bf16 v[78:81], v[152:155], v[222:225], v[78:81]
	v_mfma_f32_16x16x32_bf16 v[74:77], v[168:171], v[222:225], v[74:77]
	v_mfma_f32_16x16x32_bf16 v[126:129], v[156:159], v[200:203], v[126:129]
	v_mfma_f32_16x16x32_bf16 v[122:125], v[172:175], v[200:203], v[122:125]
	v_mfma_f32_16x16x32_bf16 v[110:113], v[156:159], v[210:213], v[110:113]
	v_mfma_f32_16x16x32_bf16 v[106:109], v[172:175], v[210:213], v[106:109]
	v_mfma_f32_16x16x32_bf16 v[94:97], v[156:159], v[218:221], v[94:97]
	v_mfma_f32_16x16x32_bf16 v[90:93], v[172:175], v[218:221], v[90:93]
	v_mfma_f32_16x16x32_bf16 v[78:81], v[156:159], v[226:229], v[78:81]
	v_mfma_f32_16x16x32_bf16 v[74:77], v[172:175], v[226:229], v[74:77]
	v_mfma_f32_16x16x32_bf16 v[118:121], v[176:179], v[196:199], v[118:121]
	v_mfma_f32_16x16x32_bf16 v[114:117], v[184:187], v[196:199], v[114:117]
	v_mfma_f32_16x16x32_bf16 v[102:105], v[176:179], v[206:209], v[102:105]
	v_mfma_f32_16x16x32_bf16 v[98:101], v[184:187], v[206:209], v[98:101]
	v_mfma_f32_16x16x32_bf16 v[86:89], v[176:179], v[214:217], v[86:89]
	v_mfma_f32_16x16x32_bf16 v[82:85], v[184:187], v[214:217], v[82:85]
	v_mfma_f32_16x16x32_bf16 v[70:73], v[176:179], v[222:225], v[70:73]
	v_mfma_f32_16x16x32_bf16 v[66:69], v[184:187], v[222:225], v[66:69]
	v_mfma_f32_16x16x32_bf16 v[118:121], v[180:183], v[200:203], v[118:121]
	v_mfma_f32_16x16x32_bf16 v[114:117], v[188:191], v[200:203], v[114:117]
	v_mfma_f32_16x16x32_bf16 v[102:105], v[180:183], v[210:213], v[102:105]
	v_mfma_f32_16x16x32_bf16 v[98:101], v[188:191], v[210:213], v[98:101]
	v_mfma_f32_16x16x32_bf16 v[86:89], v[180:183], v[218:221], v[86:89]
	v_mfma_f32_16x16x32_bf16 v[82:85], v[188:191], v[218:221], v[82:85]
	v_mfma_f32_16x16x32_bf16 v[70:73], v[180:183], v[226:229], v[70:73]
	v_mfma_f32_16x16x32_bf16 v[66:69], v[188:191], v[226:229], v[66:69]
	s_setprio 0
	s_barrier
	s_add_i32 s87, s75, s66
	v_lshl_add_u64 v[192:193], s[48:49], 0, v[134:135]
	s_mov_b32 m0, s87
	ds_read_b128 v[196:199], v164 offset:16384
	ds_read_b128 v[200:203], v164 offset:17408
	ds_read_b128 v[206:209], v164 offset:18432
	ds_read_b128 v[210:213], v164 offset:19456
	ds_read_b128 v[214:217], v164 offset:20480
	ds_read_b128 v[218:221], v164 offset:21504
	ds_read_b128 v[222:225], v164 offset:22528
	ds_read_b128 v[226:229], v164 offset:23552
	global_load_lds_dwordx4 v[192:193], off
	s_add_i32 m0, s87, 0x2000
	s_add_u32 s88, s48, 0x100000
	v_lshl_add_u64 v[230:231], s[48:49], 0, v[138:139]
	s_addc_u32 s89, s49, 0
	s_add_i32 s87, s76, s66
	global_load_lds_dwordx4 v[230:231], off
	v_lshl_add_u64 v[232:233], s[88:89], 0, v[134:135]
	s_mov_b32 m0, s87
	v_lshl_add_u64 v[234:235], s[64:65], 0, v[136:137]
	global_load_lds_dwordx4 v[232:233], off
	v_lshl_add_u64 v[232:233], s[88:89], 0, v[138:139]
	s_add_i32 m0, s87, 0x2000
	s_nop 0
	global_load_lds_dwordx4 v[232:233], off
	v_lshl_add_u64 v[232:233], s[64:65], 0, v[132:133]
	s_mov_b32 m0, s61
	s_nop 0
	global_load_lds_dwordx4 v[232:233], off
	s_mov_b32 m0, s63
	s_nop 0
	global_load_lds_dwordx4 v[234:235], off
	s_waitcnt vmcnt(8)
	s_waitcnt lgkmcnt(0)
	s_barrier
	s_setprio 1
	v_mfma_f32_16x16x32_bf16 v[62:65], v[152:155], v[196:199], v[62:65]
	v_mfma_f32_16x16x32_bf16 v[58:61], v[168:171], v[196:199], v[58:61]
	v_mfma_f32_16x16x32_bf16 v[46:49], v[152:155], v[206:209], v[46:49]
	v_mfma_f32_16x16x32_bf16 v[42:45], v[168:171], v[206:209], v[42:45]
	v_mfma_f32_16x16x32_bf16 v[30:33], v[152:155], v[214:217], v[30:33]
	v_mfma_f32_16x16x32_bf16 v[26:29], v[168:171], v[214:217], v[26:29]
	v_mfma_f32_16x16x32_bf16 v[14:17], v[152:155], v[222:225], v[14:17]
	v_mfma_f32_16x16x32_bf16 v[10:13], v[168:171], v[222:225], v[10:13]
	v_mfma_f32_16x16x32_bf16 v[62:65], v[156:159], v[200:203], v[62:65]
	v_mfma_f32_16x16x32_bf16 v[58:61], v[172:175], v[200:203], v[58:61]
	v_mfma_f32_16x16x32_bf16 v[46:49], v[156:159], v[210:213], v[46:49]
	v_mfma_f32_16x16x32_bf16 v[42:45], v[172:175], v[210:213], v[42:45]
	v_mfma_f32_16x16x32_bf16 v[30:33], v[156:159], v[218:221], v[30:33]
	v_mfma_f32_16x16x32_bf16 v[26:29], v[172:175], v[218:221], v[26:29]
	v_mfma_f32_16x16x32_bf16 v[14:17], v[156:159], v[226:229], v[14:17]
	v_mfma_f32_16x16x32_bf16 v[10:13], v[172:175], v[226:229], v[10:13]
	v_mfma_f32_16x16x32_bf16 v[54:57], v[176:179], v[196:199], v[54:57]
	v_mfma_f32_16x16x32_bf16 v[50:53], v[184:187], v[196:199], v[50:53]
	v_mfma_f32_16x16x32_bf16 v[38:41], v[176:179], v[206:209], v[38:41]
	v_mfma_f32_16x16x32_bf16 v[34:37], v[184:187], v[206:209], v[34:37]
	v_mfma_f32_16x16x32_bf16 v[22:25], v[176:179], v[214:217], v[22:25]
	v_mfma_f32_16x16x32_bf16 v[18:21], v[184:187], v[214:217], v[18:21]
	v_mfma_f32_16x16x32_bf16 v[6:9], v[176:179], v[222:225], v[6:9]
	v_mfma_f32_16x16x32_bf16 v[2:5], v[184:187], v[222:225], v[2:5]
	v_mfma_f32_16x16x32_bf16 v[54:57], v[180:183], v[200:203], v[54:57]
	v_mfma_f32_16x16x32_bf16 v[50:53], v[188:191], v[200:203], v[50:53]
	v_mfma_f32_16x16x32_bf16 v[38:41], v[180:183], v[210:213], v[38:41]
	v_mfma_f32_16x16x32_bf16 v[34:37], v[188:191], v[210:213], v[34:37]
	v_mfma_f32_16x16x32_bf16 v[22:25], v[180:183], v[218:221], v[22:25]
	v_mfma_f32_16x16x32_bf16 v[18:21], v[188:191], v[218:221], v[18:21]
	v_mfma_f32_16x16x32_bf16 v[6:9], v[180:183], v[226:229], v[6:9]
	v_mfma_f32_16x16x32_bf16 v[2:5], v[188:191], v[226:229], v[2:5]
	s_setprio 0
	s_barrier
	s_add_i32 s87, 0, 0x18000
	v_add_u32_e32 v167, s87, v160
	s_add_i32 s88, 0, 0x1c000
	ds_read_b128 v[152:155], v167
	ds_read_b128 v[156:159], v167 offset:1024
	ds_read_b128 v[168:171], v167 offset:2048
	ds_read_b128 v[172:175], v167 offset:3072
	v_add_u32_e32 v167, s88, v160
	ds_read_b128 v[176:179], v167
	ds_read_b128 v[180:183], v167 offset:1024
	ds_read_b128 v[184:187], v167 offset:2048
	ds_read_b128 v[188:191], v167 offset:3072
	s_add_u32 s64, s64, 0x100000
	s_addc_u32 s65, s65, 0
	s_mov_b32 m0, s67
	v_lshl_add_u64 v[236:237], s[64:65], 0, v[132:133]
	ds_read_b128 v[196:199], v164 offset:32768
	ds_read_b128 v[200:203], v164 offset:33792
	ds_read_b128 v[206:209], v164 offset:34816
	ds_read_b128 v[210:213], v164 offset:35840
	ds_read_b128 v[214:217], v164 offset:36864
	ds_read_b128 v[218:221], v164 offset:37888
	ds_read_b128 v[222:225], v164 offset:38912
	ds_read_b128 v[226:229], v164 offset:39936
	global_load_lds_dwordx4 v[236:237], off
	v_lshl_add_u64 v[236:237], s[64:65], 0, v[136:137]
	s_mov_b32 m0, s68
	s_nop 0
	global_load_lds_dwordx4 v[236:237], off
	s_waitcnt vmcnt(8)
	s_waitcnt lgkmcnt(0)
	s_barrier
	s_setprio 1
	v_mfma_f32_16x16x32_bf16 v[126:129], v[152:155], v[196:199], v[126:129]
	v_mfma_f32_16x16x32_bf16 v[122:125], v[168:171], v[196:199], v[122:125]
	v_mfma_f32_16x16x32_bf16 v[110:113], v[152:155], v[206:209], v[110:113]
	v_mfma_f32_16x16x32_bf16 v[106:109], v[168:171], v[206:209], v[106:109]
	v_mfma_f32_16x16x32_bf16 v[94:97], v[152:155], v[214:217], v[94:97]
	v_mfma_f32_16x16x32_bf16 v[90:93], v[168:171], v[214:217], v[90:93]
	v_mfma_f32_16x16x32_bf16 v[78:81], v[152:155], v[222:225], v[78:81]
	v_mfma_f32_16x16x32_bf16 v[74:77], v[168:171], v[222:225], v[74:77]
	v_mfma_f32_16x16x32_bf16 v[126:129], v[156:159], v[200:203], v[126:129]
	v_mfma_f32_16x16x32_bf16 v[122:125], v[172:175], v[200:203], v[122:125]
	v_mfma_f32_16x16x32_bf16 v[110:113], v[156:159], v[210:213], v[110:113]
	v_mfma_f32_16x16x32_bf16 v[106:109], v[172:175], v[210:213], v[106:109]
	v_mfma_f32_16x16x32_bf16 v[94:97], v[156:159], v[218:221], v[94:97]
	v_mfma_f32_16x16x32_bf16 v[90:93], v[172:175], v[218:221], v[90:93]
	v_mfma_f32_16x16x32_bf16 v[78:81], v[156:159], v[226:229], v[78:81]
	v_mfma_f32_16x16x32_bf16 v[74:77], v[172:175], v[226:229], v[74:77]
	v_mfma_f32_16x16x32_bf16 v[118:121], v[176:179], v[196:199], v[118:121]
	v_mfma_f32_16x16x32_bf16 v[114:117], v[184:187], v[196:199], v[114:117]
	v_mfma_f32_16x16x32_bf16 v[102:105], v[176:179], v[206:209], v[102:105]
	v_mfma_f32_16x16x32_bf16 v[98:101], v[184:187], v[206:209], v[98:101]
	v_mfma_f32_16x16x32_bf16 v[86:89], v[176:179], v[214:217], v[86:89]
	v_mfma_f32_16x16x32_bf16 v[82:85], v[184:187], v[214:217], v[82:85]
	v_mfma_f32_16x16x32_bf16 v[70:73], v[176:179], v[222:225], v[70:73]
	v_mfma_f32_16x16x32_bf16 v[66:69], v[184:187], v[222:225], v[66:69]
	v_mfma_f32_16x16x32_bf16 v[118:121], v[180:183], v[200:203], v[118:121]
	v_mfma_f32_16x16x32_bf16 v[114:117], v[188:191], v[200:203], v[114:117]
	v_mfma_f32_16x16x32_bf16 v[102:105], v[180:183], v[210:213], v[102:105]
	v_mfma_f32_16x16x32_bf16 v[98:101], v[188:191], v[210:213], v[98:101]
	v_mfma_f32_16x16x32_bf16 v[86:89], v[180:183], v[218:221], v[86:89]
	v_mfma_f32_16x16x32_bf16 v[82:85], v[188:191], v[218:221], v[82:85]
	v_mfma_f32_16x16x32_bf16 v[70:73], v[180:183], v[226:229], v[70:73]
	v_mfma_f32_16x16x32_bf16 v[66:69], v[188:191], v[226:229], v[66:69]
	s_setprio 0
	s_barrier
	s_add_i32 s64, s87, s66
	v_lshl_add_u64 v[192:193], v[192:193], 0, s[20:21]
	s_mov_b32 m0, s64
	ds_read_b128 v[196:199], v164 offset:49152
	ds_read_b128 v[200:203], v164 offset:50176
	ds_read_b128 v[206:209], v164 offset:51200
	ds_read_b128 v[210:213], v164 offset:52224
	ds_read_b128 v[214:217], v164 offset:53248
	ds_read_b128 v[218:221], v164 offset:54272
	ds_read_b128 v[222:225], v164 offset:55296
	ds_read_b128 v[226:229], v164 offset:56320
	global_load_lds_dwordx4 v[192:193], off
	s_add_i32 m0, s64, 0x2000
	s_add_u32 s48, s48, 0x100080
	v_lshl_add_u64 v[192:193], v[230:231], 0, s[20:21]
	s_addc_u32 s49, s49, 0
	s_add_i32 s64, s88, s66
	global_load_lds_dwordx4 v[192:193], off
	v_lshl_add_u64 v[192:193], s[48:49], 0, v[134:135]
	s_mov_b32 m0, s64
	s_nop 0
	global_load_lds_dwordx4 v[192:193], off
	v_lshl_add_u64 v[192:193], s[48:49], 0, v[138:139]
	s_add_i32 m0, s64, 0x2000
	s_nop 0
	global_load_lds_dwordx4 v[192:193], off
	v_lshl_add_u64 v[192:193], v[232:233], 0, s[20:21]
	s_mov_b32 m0, s72
	s_nop 0
	global_load_lds_dwordx4 v[192:193], off
	v_lshl_add_u64 v[192:193], v[234:235], 0, s[20:21]
	s_mov_b32 m0, s73
	s_nop 0
	global_load_lds_dwordx4 v[192:193], off
	s_nop 0
	s_waitcnt vmcnt(8)
	s_waitcnt lgkmcnt(0)
	s_barrier
	s_setprio 1
	v_mfma_f32_16x16x32_bf16 v[62:65], v[152:155], v[196:199], v[62:65]
	v_mfma_f32_16x16x32_bf16 v[58:61], v[168:171], v[196:199], v[58:61]
	v_mfma_f32_16x16x32_bf16 v[46:49], v[152:155], v[206:209], v[46:49]
	v_mfma_f32_16x16x32_bf16 v[42:45], v[168:171], v[206:209], v[42:45]
	v_mfma_f32_16x16x32_bf16 v[30:33], v[152:155], v[214:217], v[30:33]
	v_mfma_f32_16x16x32_bf16 v[26:29], v[168:171], v[214:217], v[26:29]
	v_mfma_f32_16x16x32_bf16 v[14:17], v[152:155], v[222:225], v[14:17]
	v_mfma_f32_16x16x32_bf16 v[10:13], v[168:171], v[222:225], v[10:13]
	v_mfma_f32_16x16x32_bf16 v[62:65], v[156:159], v[200:203], v[62:65]
	v_mfma_f32_16x16x32_bf16 v[58:61], v[172:175], v[200:203], v[58:61]
	v_mfma_f32_16x16x32_bf16 v[46:49], v[156:159], v[210:213], v[46:49]
	v_mfma_f32_16x16x32_bf16 v[42:45], v[172:175], v[210:213], v[42:45]
	v_mfma_f32_16x16x32_bf16 v[30:33], v[156:159], v[218:221], v[30:33]
	v_mfma_f32_16x16x32_bf16 v[26:29], v[172:175], v[218:221], v[26:29]
	v_mfma_f32_16x16x32_bf16 v[14:17], v[156:159], v[226:229], v[14:17]
	v_mfma_f32_16x16x32_bf16 v[10:13], v[172:175], v[226:229], v[10:13]
	v_mfma_f32_16x16x32_bf16 v[54:57], v[176:179], v[196:199], v[54:57]
	v_mfma_f32_16x16x32_bf16 v[50:53], v[184:187], v[196:199], v[50:53]
	v_mfma_f32_16x16x32_bf16 v[38:41], v[176:179], v[206:209], v[38:41]
	v_mfma_f32_16x16x32_bf16 v[34:37], v[184:187], v[206:209], v[34:37]
	v_mfma_f32_16x16x32_bf16 v[22:25], v[176:179], v[214:217], v[22:25]
	v_mfma_f32_16x16x32_bf16 v[18:21], v[184:187], v[214:217], v[18:21]
	v_mfma_f32_16x16x32_bf16 v[6:9], v[176:179], v[222:225], v[6:9]
	v_mfma_f32_16x16x32_bf16 v[2:5], v[184:187], v[222:225], v[2:5]
	v_mfma_f32_16x16x32_bf16 v[54:57], v[180:183], v[200:203], v[54:57]
	v_mfma_f32_16x16x32_bf16 v[50:53], v[188:191], v[200:203], v[50:53]
	v_mfma_f32_16x16x32_bf16 v[38:41], v[180:183], v[210:213], v[38:41]
	v_mfma_f32_16x16x32_bf16 v[34:37], v[188:191], v[210:213], v[34:37]
	v_mfma_f32_16x16x32_bf16 v[22:25], v[180:183], v[218:221], v[22:25]
	v_mfma_f32_16x16x32_bf16 v[18:21], v[188:191], v[218:221], v[18:21]
	v_mfma_f32_16x16x32_bf16 v[6:9], v[180:183], v[226:229], v[6:9]
	v_mfma_f32_16x16x32_bf16 v[2:5], v[188:191], v[226:229], v[2:5]
	s_setprio 0
	s_barrier
	s_add_u32 s6, s6, 0x100
	s_addc_u32 s7, s7, 0
	s_add_u32 s53, s53, 0x100
	s_addc_u32 s55, s55, 0
	s_cmp_ge_i32 s86, s85
	s_mov_b32 s48, s86
	s_cbranch_scc0 .LBB0_3649
	s_and_b64 vcc, exec, s[22:23]
	s_cbranch_vccz .LBB0_3652
	s_barrier

.LBB0_3789:
	ds_read_b128 v[162:165], v145
	ds_read_b128 v[166:169], v145 offset:1024
	ds_read_b128 v[170:173], v145 offset:2048
	ds_read_b128 v[174:177], v145 offset:3072
	ds_read_b128 v[178:181], v160
	ds_read_b128 v[182:185], v160 offset:1024
	ds_read_b128 v[186:189], v160 offset:2048
	ds_read_b128 v[190:193], v160 offset:3072
	s_add_i32 s63, s30, 2
	s_add_u32 s31, s28, 0xfff00080
	s_addc_u32 s34, s29, -1
	s_cmp_eq_u32 s60, s30
	s_cselect_b32 s30, s59, s61
	s_cselect_b32 s35, s19, s34
	s_cselect_b32 s34, s23, s31
	s_cselect_b32 s31, s21, s62
	v_lshl_add_u64 v[158:159], s[28:29], 0, v[148:149]
	s_add_i32 m0, s6, 0xc000
	ds_read_b128 v[196:199], v161
	ds_read_b128 v[200:203], v161 offset:1024
	ds_read_b128 v[206:209], v161 offset:2048
	ds_read_b128 v[210:213], v161 offset:3072
	ds_read_b128 v[214:217], v161 offset:4096
	ds_read_b128 v[218:221], v161 offset:5120
	ds_read_b128 v[222:225], v161 offset:6144
	ds_read_b128 v[226:229], v161 offset:7168
	global_load_lds_dwordx4 v[158:159], off
	v_lshl_add_u64 v[158:159], s[28:29], 0, v[150:151]
	s_add_i32 m0, s6, 0xe000
	s_nop 0
	global_load_lds_dwordx4 v[158:159], off
	s_waitcnt vmcnt(8)
	s_waitcnt lgkmcnt(0)
	s_barrier
	s_setprio 1
	v_mfma_f32_16x16x32_bf16 v[126:129], v[162:165], v[196:199], v[126:129]
	v_mfma_f32_16x16x32_bf16 v[122:125], v[170:173], v[196:199], v[122:125]
	v_mfma_f32_16x16x32_bf16 v[118:121], v[162:165], v[206:209], v[118:121]
	v_mfma_f32_16x16x32_bf16 v[114:117], v[170:173], v[206:209], v[114:117]
	v_mfma_f32_16x16x32_bf16 v[102:105], v[162:165], v[214:217], v[102:105]
	v_mfma_f32_16x16x32_bf16 v[98:101], v[170:173], v[214:217], v[98:101]
	v_mfma_f32_16x16x32_bf16 v[42:45], v[162:165], v[222:225], v[42:45]
	v_mfma_f32_16x16x32_bf16 v[34:37], v[170:173], v[222:225], v[34:37]
	v_mfma_f32_16x16x32_bf16 v[126:129], v[166:169], v[200:203], v[126:129]
	v_mfma_f32_16x16x32_bf16 v[122:125], v[174:177], v[200:203], v[122:125]
	v_mfma_f32_16x16x32_bf16 v[118:121], v[166:169], v[210:213], v[118:121]
	v_mfma_f32_16x16x32_bf16 v[114:117], v[174:177], v[210:213], v[114:117]
	v_mfma_f32_16x16x32_bf16 v[102:105], v[166:169], v[218:221], v[102:105]
	v_mfma_f32_16x16x32_bf16 v[98:101], v[174:177], v[218:221], v[98:101]
	v_mfma_f32_16x16x32_bf16 v[42:45], v[166:169], v[226:229], v[42:45]
	v_mfma_f32_16x16x32_bf16 v[34:37], v[174:177], v[226:229], v[34:37]
	v_mfma_f32_16x16x32_bf16 v[110:113], v[178:181], v[196:199], v[110:113]
	v_mfma_f32_16x16x32_bf16 v[106:109], v[186:189], v[196:199], v[106:109]
	v_mfma_f32_16x16x32_bf16 v[94:97], v[178:181], v[206:209], v[94:97]
	v_mfma_f32_16x16x32_bf16 v[90:93], v[186:189], v[206:209], v[90:93]
	v_mfma_f32_16x16x32_bf16 v[86:89], v[178:181], v[214:217], v[86:89]
	v_mfma_f32_16x16x32_bf16 v[82:85], v[186:189], v[214:217], v[82:85]
	v_mfma_f32_16x16x32_bf16 v[30:33], v[178:181], v[222:225], v[30:33]
	v_mfma_f32_16x16x32_bf16 v[26:29], v[186:189], v[222:225], v[26:29]
	v_mfma_f32_16x16x32_bf16 v[110:113], v[182:185], v[200:203], v[110:113]
	v_mfma_f32_16x16x32_bf16 v[106:109], v[190:193], v[200:203], v[106:109]
	v_mfma_f32_16x16x32_bf16 v[94:97], v[182:185], v[210:213], v[94:97]
	v_mfma_f32_16x16x32_bf16 v[90:93], v[190:193], v[210:213], v[90:93]
	v_mfma_f32_16x16x32_bf16 v[86:89], v[182:185], v[218:221], v[86:89]
	v_mfma_f32_16x16x32_bf16 v[82:85], v[190:193], v[218:221], v[82:85]
	v_mfma_f32_16x16x32_bf16 v[30:33], v[182:185], v[226:229], v[30:33]
	v_mfma_f32_16x16x32_bf16 v[26:29], v[190:193], v[226:229], v[26:29]
	s_setprio 0
	s_barrier
	s_add_i32 s64, s54, s40
	v_lshl_add_u64 v[158:159], s[30:31], 0, v[134:135]
	s_mov_b32 m0, s64
	ds_read_b128 v[196:199], v161 offset:16384
	ds_read_b128 v[200:203], v161 offset:17408
	ds_read_b128 v[206:209], v161 offset:18432
	ds_read_b128 v[210:213], v161 offset:19456
	ds_read_b128 v[214:217], v161 offset:20480
	ds_read_b128 v[218:221], v161 offset:21504
	ds_read_b128 v[222:225], v161 offset:22528
	ds_read_b128 v[226:229], v161 offset:23552
	global_load_lds_dwordx4 v[158:159], off
	s_add_i32 m0, s64, 0x2000
	s_add_u32 s64, s30, 0x100000
	v_lshl_add_u64 v[230:231], s[30:31], 0, v[132:133]
	s_addc_u32 s65, s31, 0
	s_add_i32 s66, s55, s40
	global_load_lds_dwordx4 v[230:231], off
	v_lshl_add_u64 v[232:233], s[64:65], 0, v[134:135]
	s_mov_b32 m0, s66
	v_lshl_add_u64 v[234:235], s[34:35], 0, v[132:133]
	global_load_lds_dwordx4 v[232:233], off
	v_lshl_add_u64 v[232:233], s[64:65], 0, v[132:133]
	s_add_i32 m0, s66, 0x2000
	s_nop 0
	global_load_lds_dwordx4 v[232:233], off
	v_lshl_add_u64 v[232:233], s[34:35], 0, v[134:135]
	s_mov_b32 m0, s6
	s_nop 0
	global_load_lds_dwordx4 v[232:233], off
	s_mov_b32 m0, s13
	s_nop 0
	global_load_lds_dwordx4 v[234:235], off
	s_waitcnt vmcnt(8)
	s_waitcnt lgkmcnt(0)
	s_barrier
	s_setprio 1
	v_mfma_f32_16x16x32_bf16 v[78:81], v[162:165], v[196:199], v[78:81]
	v_mfma_f32_16x16x32_bf16 v[74:77], v[170:173], v[196:199], v[74:77]
	v_mfma_f32_16x16x32_bf16 v[70:73], v[162:165], v[206:209], v[70:73]
	v_mfma_f32_16x16x32_bf16 v[66:69], v[170:173], v[206:209], v[66:69]
	v_mfma_f32_16x16x32_bf16 v[54:57], v[162:165], v[214:217], v[54:57]
	v_mfma_f32_16x16x32_bf16 v[50:53], v[170:173], v[214:217], v[50:53]
	v_mfma_f32_16x16x32_bf16 v[14:17], v[162:165], v[222:225], v[14:17]
	v_mfma_f32_16x16x32_bf16 v[10:13], v[170:173], v[222:225], v[10:13]
	v_mfma_f32_16x16x32_bf16 v[78:81], v[166:169], v[200:203], v[78:81]
	v_mfma_f32_16x16x32_bf16 v[74:77], v[174:177], v[200:203], v[74:77]
	v_mfma_f32_16x16x32_bf16 v[70:73], v[166:169], v[210:213], v[70:73]
	v_mfma_f32_16x16x32_bf16 v[66:69], v[174:177], v[210:213], v[66:69]
	v_mfma_f32_16x16x32_bf16 v[54:57], v[166:169], v[218:221], v[54:57]
	v_mfma_f32_16x16x32_bf16 v[50:53], v[174:177], v[218:221], v[50:53]
	v_mfma_f32_16x16x32_bf16 v[14:17], v[166:169], v[226:229], v[14:17]
	v_mfma_f32_16x16x32_bf16 v[10:13], v[174:177], v[226:229], v[10:13]
	v_mfma_f32_16x16x32_bf16 v[62:65], v[178:181], v[196:199], v[62:65]
	v_mfma_f32_16x16x32_bf16 v[58:61], v[186:189], v[196:199], v[58:61]
	v_mfma_f32_16x16x32_bf16 v[46:49], v[178:181], v[206:209], v[46:49]
	v_mfma_f32_16x16x32_bf16 v[38:41], v[186:189], v[206:209], v[38:41]
	v_mfma_f32_16x16x32_bf16 v[22:25], v[178:181], v[214:217], v[22:25]
	v_mfma_f32_16x16x32_bf16 v[18:21], v[186:189], v[214:217], v[18:21]
	v_mfma_f32_16x16x32_bf16 v[6:9], v[178:181], v[222:225], v[6:9]
	v_mfma_f32_16x16x32_bf16 v[2:5], v[186:189], v[222:225], v[2:5]
	v_mfma_f32_16x16x32_bf16 v[62:65], v[182:185], v[200:203], v[62:65]
	v_mfma_f32_16x16x32_bf16 v[58:61], v[190:193], v[200:203], v[58:61]
	v_mfma_f32_16x16x32_bf16 v[46:49], v[182:185], v[210:213], v[46:49]
	v_mfma_f32_16x16x32_bf16 v[38:41], v[190:193], v[210:213], v[38:41]
	v_mfma_f32_16x16x32_bf16 v[22:25], v[182:185], v[218:221], v[22:25]
	v_mfma_f32_16x16x32_bf16 v[18:21], v[190:193], v[218:221], v[18:21]
	v_mfma_f32_16x16x32_bf16 v[6:9], v[182:185], v[226:229], v[6:9]
	v_mfma_f32_16x16x32_bf16 v[2:5], v[190:193], v[226:229], v[2:5]
	s_setprio 0
	s_barrier
	s_add_i32 s64, 0, 0x18000
	s_add_i32 s65, 0, 0x1c000
	v_add_u32_e32 v174, s64, v131
	v_add_u32_e32 v190, s65, v131
	ds_read_b128 v[162:165], v174
	ds_read_b128 v[166:169], v174 offset:1024
	ds_read_b128 v[170:173], v174 offset:2048
	ds_read_b128 v[174:177], v174 offset:3072
	ds_read_b128 v[178:181], v190
	ds_read_b128 v[182:185], v190 offset:1024
	ds_read_b128 v[186:189], v190 offset:2048
	ds_read_b128 v[190:193], v190 offset:3072
	s_add_u32 s34, s34, 0x100000
	s_addc_u32 s35, s35, 0
	s_mov_b32 m0, s43
	v_lshl_add_u64 v[236:237], s[34:35], 0, v[134:135]
	ds_read_b128 v[196:199], v161 offset:32768
	ds_read_b128 v[200:203], v161 offset:33792
	ds_read_b128 v[206:209], v161 offset:34816
	ds_read_b128 v[210:213], v161 offset:35840
	ds_read_b128 v[214:217], v161 offset:36864
	ds_read_b128 v[218:221], v161 offset:37888
	ds_read_b128 v[222:225], v161 offset:38912
	ds_read_b128 v[226:229], v161 offset:39936
	global_load_lds_dwordx4 v[236:237], off
	v_lshl_add_u64 v[236:237], s[34:35], 0, v[132:133]
	s_mov_b32 m0, s45
	s_nop 0
	global_load_lds_dwordx4 v[236:237], off
	s_waitcnt vmcnt(8)
	s_waitcnt lgkmcnt(0)
	s_barrier
	s_setprio 1
	v_mfma_f32_16x16x32_bf16 v[126:129], v[162:165], v[196:199], v[126:129]
	v_mfma_f32_16x16x32_bf16 v[122:125], v[170:173], v[196:199], v[122:125]
	v_mfma_f32_16x16x32_bf16 v[118:121], v[162:165], v[206:209], v[118:121]
	v_mfma_f32_16x16x32_bf16 v[114:117], v[170:173], v[206:209], v[114:117]
	v_mfma_f32_16x16x32_bf16 v[102:105], v[162:165], v[214:217], v[102:105]
	v_mfma_f32_16x16x32_bf16 v[98:101], v[170:173], v[214:217], v[98:101]
	v_mfma_f32_16x16x32_bf16 v[42:45], v[162:165], v[222:225], v[42:45]
	v_mfma_f32_16x16x32_bf16 v[34:37], v[170:173], v[222:225], v[34:37]
	v_mfma_f32_16x16x32_bf16 v[126:129], v[166:169], v[200:203], v[126:129]
	v_mfma_f32_16x16x32_bf16 v[122:125], v[174:177], v[200:203], v[122:125]
	v_mfma_f32_16x16x32_bf16 v[118:121], v[166:169], v[210:213], v[118:121]
	v_mfma_f32_16x16x32_bf16 v[114:117], v[174:177], v[210:213], v[114:117]
	v_mfma_f32_16x16x32_bf16 v[102:105], v[166:169], v[218:221], v[102:105]
	v_mfma_f32_16x16x32_bf16 v[98:101], v[174:177], v[218:221], v[98:101]
	v_mfma_f32_16x16x32_bf16 v[42:45], v[166:169], v[226:229], v[42:45]
	v_mfma_f32_16x16x32_bf16 v[34:37], v[174:177], v[226:229], v[34:37]
	v_mfma_f32_16x16x32_bf16 v[110:113], v[178:181], v[196:199], v[110:113]
	v_mfma_f32_16x16x32_bf16 v[106:109], v[186:189], v[196:199], v[106:109]
	v_mfma_f32_16x16x32_bf16 v[94:97], v[178:181], v[206:209], v[94:97]
	v_mfma_f32_16x16x32_bf16 v[90:93], v[186:189], v[206:209], v[90:93]
	v_mfma_f32_16x16x32_bf16 v[86:89], v[178:181], v[214:217], v[86:89]
	v_mfma_f32_16x16x32_bf16 v[82:85], v[186:189], v[214:217], v[82:85]
	v_mfma_f32_16x16x32_bf16 v[30:33], v[178:181], v[222:225], v[30:33]
	v_mfma_f32_16x16x32_bf16 v[26:29], v[186:189], v[222:225], v[26:29]
	v_mfma_f32_16x16x32_bf16 v[110:113], v[182:185], v[200:203], v[110:113]
	v_mfma_f32_16x16x32_bf16 v[106:109], v[190:193], v[200:203], v[106:109]
	v_mfma_f32_16x16x32_bf16 v[94:97], v[182:185], v[210:213], v[94:97]
	v_mfma_f32_16x16x32_bf16 v[90:93], v[190:193], v[210:213], v[90:93]
	v_mfma_f32_16x16x32_bf16 v[86:89], v[182:185], v[218:221], v[86:89]
	v_mfma_f32_16x16x32_bf16 v[82:85], v[190:193], v[218:221], v[82:85]
	v_mfma_f32_16x16x32_bf16 v[30:33], v[182:185], v[226:229], v[30:33]
	v_mfma_f32_16x16x32_bf16 v[26:29], v[190:193], v[226:229], v[26:29]
	s_setprio 0
	s_barrier
	s_add_i32 s34, s64, s40
	v_lshl_add_u64 v[158:159], v[158:159], 0, s[10:11]
	s_mov_b32 m0, s34
	ds_read_b128 v[196:199], v161 offset:49152
	ds_read_b128 v[200:203], v161 offset:50176
	ds_read_b128 v[206:209], v161 offset:51200
	ds_read_b128 v[210:213], v161 offset:52224
	ds_read_b128 v[214:217], v161 offset:53248
	ds_read_b128 v[218:221], v161 offset:54272
	ds_read_b128 v[222:225], v161 offset:55296
	ds_read_b128 v[226:229], v161 offset:56320
	global_load_lds_dwordx4 v[158:159], off
	s_add_i32 m0, s34, 0x2000
	s_add_u32 s30, s30, 0x100080
	v_lshl_add_u64 v[158:159], v[230:231], 0, s[10:11]
	s_addc_u32 s31, s31, 0
	s_add_i32 s34, s65, s40
	global_load_lds_dwordx4 v[158:159], off
	v_lshl_add_u64 v[158:159], s[30:31], 0, v[134:135]
	s_mov_b32 m0, s34
	s_nop 0
	global_load_lds_dwordx4 v[158:159], off
	v_lshl_add_u64 v[158:159], s[30:31], 0, v[132:133]
	s_add_i32 m0, s34, 0x2000
	s_nop 0
	global_load_lds_dwordx4 v[158:159], off
	v_lshl_add_u64 v[158:159], v[232:233], 0, s[10:11]
	s_mov_b32 m0, s50
	s_nop 0
	global_load_lds_dwordx4 v[158:159], off
	v_lshl_add_u64 v[158:159], v[234:235], 0, s[10:11]
	s_mov_b32 m0, s51
	s_nop 0
	global_load_lds_dwordx4 v[158:159], off
	s_nop 0
	s_waitcnt vmcnt(8)
	s_waitcnt lgkmcnt(0)
	s_barrier
	s_setprio 1
	v_mfma_f32_16x16x32_bf16 v[78:81], v[162:165], v[196:199], v[78:81]
	v_mfma_f32_16x16x32_bf16 v[74:77], v[170:173], v[196:199], v[74:77]
	v_mfma_f32_16x16x32_bf16 v[70:73], v[162:165], v[206:209], v[70:73]
	v_mfma_f32_16x16x32_bf16 v[66:69], v[170:173], v[206:209], v[66:69]
	v_mfma_f32_16x16x32_bf16 v[54:57], v[162:165], v[214:217], v[54:57]
	v_mfma_f32_16x16x32_bf16 v[50:53], v[170:173], v[214:217], v[50:53]
	v_mfma_f32_16x16x32_bf16 v[14:17], v[162:165], v[222:225], v[14:17]
	v_mfma_f32_16x16x32_bf16 v[10:13], v[170:173], v[222:225], v[10:13]
	v_mfma_f32_16x16x32_bf16 v[78:81], v[166:169], v[200:203], v[78:81]
	v_mfma_f32_16x16x32_bf16 v[74:77], v[174:177], v[200:203], v[74:77]
	v_mfma_f32_16x16x32_bf16 v[70:73], v[166:169], v[210:213], v[70:73]
	v_mfma_f32_16x16x32_bf16 v[66:69], v[174:177], v[210:213], v[66:69]
	v_mfma_f32_16x16x32_bf16 v[54:57], v[166:169], v[218:221], v[54:57]
	v_mfma_f32_16x16x32_bf16 v[50:53], v[174:177], v[218:221], v[50:53]
	v_mfma_f32_16x16x32_bf16 v[14:17], v[166:169], v[226:229], v[14:17]
	v_mfma_f32_16x16x32_bf16 v[10:13], v[174:177], v[226:229], v[10:13]
	v_mfma_f32_16x16x32_bf16 v[62:65], v[178:181], v[196:199], v[62:65]
	v_mfma_f32_16x16x32_bf16 v[58:61], v[186:189], v[196:199], v[58:61]
	v_mfma_f32_16x16x32_bf16 v[46:49], v[178:181], v[206:209], v[46:49]
	v_mfma_f32_16x16x32_bf16 v[38:41], v[186:189], v[206:209], v[38:41]
	v_mfma_f32_16x16x32_bf16 v[22:25], v[178:181], v[214:217], v[22:25]
	v_mfma_f32_16x16x32_bf16 v[18:21], v[186:189], v[214:217], v[18:21]
	v_mfma_f32_16x16x32_bf16 v[6:9], v[178:181], v[222:225], v[6:9]
	v_mfma_f32_16x16x32_bf16 v[2:5], v[186:189], v[222:225], v[2:5]
	v_mfma_f32_16x16x32_bf16 v[62:65], v[182:185], v[200:203], v[62:65]
	v_mfma_f32_16x16x32_bf16 v[58:61], v[190:193], v[200:203], v[58:61]
	v_mfma_f32_16x16x32_bf16 v[46:49], v[182:185], v[210:213], v[46:49]
	v_mfma_f32_16x16x32_bf16 v[38:41], v[190:193], v[210:213], v[38:41]
	v_mfma_f32_16x16x32_bf16 v[22:25], v[182:185], v[218:221], v[22:25]
	v_mfma_f32_16x16x32_bf16 v[18:21], v[190:193], v[218:221], v[18:21]
	v_mfma_f32_16x16x32_bf16 v[6:9], v[182:185], v[226:229], v[6:9]
	v_mfma_f32_16x16x32_bf16 v[2:5], v[190:193], v[226:229], v[2:5]
	s_setprio 0
	s_barrier
	s_add_u32 s28, s28, 0x100
	s_addc_u32 s29, s29, 0
	s_add_u32 s61, s61, 0x100
	s_addc_u32 s62, s62, 0
	s_cmp_ge_i32 s63, s58
	s_mov_b32 s30, s63
	s_cbranch_scc0 .LBB0_3789
	s_and_b64 vcc, exec, s[16:17]
	s_cbranch_vccz .LBB0_3792
	s_barrier

.LBB0_3983:
	ds_read_b128 v[152:155], v160
	ds_read_b128 v[164:167], v160 offset:1024
	ds_read_b128 v[168:171], v160 offset:2048
	ds_read_b128 v[172:175], v160 offset:3072
	ds_read_b128 v[176:179], v161
	ds_read_b128 v[180:183], v161 offset:1024
	ds_read_b128 v[184:187], v161 offset:2048
	ds_read_b128 v[188:191], v161 offset:3072
	s_add_i32 s80, s48, 2
	s_add_u32 s49, s58, 0xfffe0080
	s_addc_u32 s60, s59, -1
	s_cmp_eq_u32 s43, s48
	s_cselect_b32 s48, s52, s47
	s_cselect_b32 s61, s5, s60
	s_cselect_b32 s60, s4, s49
	s_cselect_b32 s49, s53, s51
	v_lshl_add_u64 v[156:157], s[58:59], 0, v[140:141]
	s_add_i32 m0, s55, 0xc000
	ds_read_b128 v[196:199], v162
	ds_read_b128 v[200:203], v162 offset:1024
	ds_read_b128 v[204:207], v162 offset:2048
	ds_read_b128 v[208:211], v162 offset:3072
	ds_read_b128 v[212:215], v162 offset:4096
	ds_read_b128 v[216:219], v162 offset:5120
	ds_read_b128 v[220:223], v162 offset:6144
	ds_read_b128 v[224:227], v162 offset:7168
	global_load_lds_dwordx4 v[156:157], off
	v_lshl_add_u64 v[156:157], s[58:59], 0, v[142:143]
	s_add_i32 m0, s55, 0xe000
	s_nop 0
	global_load_lds_dwordx4 v[156:157], off
	s_waitcnt vmcnt(8)
	s_waitcnt lgkmcnt(0)
	s_barrier
	s_setprio 1
	v_mfma_f32_16x16x32_bf16 v[126:129], v[152:155], v[196:199], v[126:129]
	v_mfma_f32_16x16x32_bf16 v[122:125], v[168:171], v[196:199], v[122:125]
	v_mfma_f32_16x16x32_bf16 v[110:113], v[152:155], v[204:207], v[110:113]
	v_mfma_f32_16x16x32_bf16 v[106:109], v[168:171], v[204:207], v[106:109]
	v_mfma_f32_16x16x32_bf16 v[94:97], v[152:155], v[212:215], v[94:97]
	v_mfma_f32_16x16x32_bf16 v[90:93], v[168:171], v[212:215], v[90:93]
	v_mfma_f32_16x16x32_bf16 v[78:81], v[152:155], v[220:223], v[78:81]
	v_mfma_f32_16x16x32_bf16 v[74:77], v[168:171], v[220:223], v[74:77]
	v_mfma_f32_16x16x32_bf16 v[126:129], v[164:167], v[200:203], v[126:129]
	v_mfma_f32_16x16x32_bf16 v[122:125], v[172:175], v[200:203], v[122:125]
	v_mfma_f32_16x16x32_bf16 v[110:113], v[164:167], v[208:211], v[110:113]
	v_mfma_f32_16x16x32_bf16 v[106:109], v[172:175], v[208:211], v[106:109]
	v_mfma_f32_16x16x32_bf16 v[94:97], v[164:167], v[216:219], v[94:97]
	v_mfma_f32_16x16x32_bf16 v[90:93], v[172:175], v[216:219], v[90:93]
	v_mfma_f32_16x16x32_bf16 v[78:81], v[164:167], v[224:227], v[78:81]
	v_mfma_f32_16x16x32_bf16 v[74:77], v[172:175], v[224:227], v[74:77]
	v_mfma_f32_16x16x32_bf16 v[118:121], v[176:179], v[196:199], v[118:121]
	v_mfma_f32_16x16x32_bf16 v[114:117], v[184:187], v[196:199], v[114:117]
	v_mfma_f32_16x16x32_bf16 v[102:105], v[176:179], v[204:207], v[102:105]
	v_mfma_f32_16x16x32_bf16 v[98:101], v[184:187], v[204:207], v[98:101]
	v_mfma_f32_16x16x32_bf16 v[86:89], v[176:179], v[212:215], v[86:89]
	v_mfma_f32_16x16x32_bf16 v[82:85], v[184:187], v[212:215], v[82:85]
	v_mfma_f32_16x16x32_bf16 v[70:73], v[176:179], v[220:223], v[70:73]
	v_mfma_f32_16x16x32_bf16 v[66:69], v[184:187], v[220:223], v[66:69]
	v_mfma_f32_16x16x32_bf16 v[118:121], v[180:183], v[200:203], v[118:121]
	v_mfma_f32_16x16x32_bf16 v[114:117], v[188:191], v[200:203], v[114:117]
	v_mfma_f32_16x16x32_bf16 v[102:105], v[180:183], v[208:211], v[102:105]
	v_mfma_f32_16x16x32_bf16 v[98:101], v[188:191], v[208:211], v[98:101]
	v_mfma_f32_16x16x32_bf16 v[86:89], v[180:183], v[216:219], v[86:89]
	v_mfma_f32_16x16x32_bf16 v[82:85], v[188:191], v[216:219], v[82:85]
	v_mfma_f32_16x16x32_bf16 v[70:73], v[180:183], v[224:227], v[70:73]
	v_mfma_f32_16x16x32_bf16 v[66:69], v[188:191], v[224:227], v[66:69]
	s_setprio 0
	s_barrier
	s_add_i32 s81, s71, s62
	v_lshl_add_u64 v[156:157], s[48:49], 0, v[134:135]
	s_mov_b32 m0, s81
	ds_read_b128 v[196:199], v162 offset:16384
	ds_read_b128 v[200:203], v162 offset:17408
	ds_read_b128 v[204:207], v162 offset:18432
	ds_read_b128 v[208:211], v162 offset:19456
	ds_read_b128 v[212:215], v162 offset:20480
	ds_read_b128 v[216:219], v162 offset:21504
	ds_read_b128 v[220:223], v162 offset:22528
	ds_read_b128 v[224:227], v162 offset:23552
	global_load_lds_dwordx4 v[156:157], off
	s_add_i32 m0, s81, 0x2000
	s_add_u32 s82, s48, 0x20000
	v_lshl_add_u64 v[192:193], s[48:49], 0, v[138:139]
	s_addc_u32 s83, s49, 0
	s_add_i32 s81, s72, s62
	global_load_lds_dwordx4 v[192:193], off
	v_lshl_add_u64 v[228:229], s[82:83], 0, v[134:135]
	s_mov_b32 m0, s81
	v_lshl_add_u64 v[230:231], s[60:61], 0, v[136:137]
	global_load_lds_dwordx4 v[228:229], off
	v_lshl_add_u64 v[228:229], s[82:83], 0, v[138:139]
	s_add_i32 m0, s81, 0x2000
	s_nop 0
	global_load_lds_dwordx4 v[228:229], off
	v_lshl_add_u64 v[228:229], s[60:61], 0, v[132:133]
	s_mov_b32 m0, s55
	s_nop 0
	global_load_lds_dwordx4 v[228:229], off
	s_mov_b32 m0, s57
	s_nop 0
	global_load_lds_dwordx4 v[230:231], off
	s_waitcnt vmcnt(8)
	s_waitcnt lgkmcnt(0)
	s_barrier
	s_setprio 1
	v_mfma_f32_16x16x32_bf16 v[62:65], v[152:155], v[196:199], v[62:65]
	v_mfma_f32_16x16x32_bf16 v[58:61], v[168:171], v[196:199], v[58:61]
	v_mfma_f32_16x16x32_bf16 v[46:49], v[152:155], v[204:207], v[46:49]
	v_mfma_f32_16x16x32_bf16 v[42:45], v[168:171], v[204:207], v[42:45]
	v_mfma_f32_16x16x32_bf16 v[30:33], v[152:155], v[212:215], v[30:33]
	v_mfma_f32_16x16x32_bf16 v[26:29], v[168:171], v[212:215], v[26:29]
	v_mfma_f32_16x16x32_bf16 v[14:17], v[152:155], v[220:223], v[14:17]
	v_mfma_f32_16x16x32_bf16 v[10:13], v[168:171], v[220:223], v[10:13]
	v_mfma_f32_16x16x32_bf16 v[62:65], v[164:167], v[200:203], v[62:65]
	v_mfma_f32_16x16x32_bf16 v[58:61], v[172:175], v[200:203], v[58:61]
	v_mfma_f32_16x16x32_bf16 v[46:49], v[164:167], v[208:211], v[46:49]
	v_mfma_f32_16x16x32_bf16 v[42:45], v[172:175], v[208:211], v[42:45]
	v_mfma_f32_16x16x32_bf16 v[30:33], v[164:167], v[216:219], v[30:33]
	v_mfma_f32_16x16x32_bf16 v[26:29], v[172:175], v[216:219], v[26:29]
	v_mfma_f32_16x16x32_bf16 v[14:17], v[164:167], v[224:227], v[14:17]
	v_mfma_f32_16x16x32_bf16 v[10:13], v[172:175], v[224:227], v[10:13]
	v_mfma_f32_16x16x32_bf16 v[54:57], v[176:179], v[196:199], v[54:57]
	v_mfma_f32_16x16x32_bf16 v[50:53], v[184:187], v[196:199], v[50:53]
	v_mfma_f32_16x16x32_bf16 v[38:41], v[176:179], v[204:207], v[38:41]
	v_mfma_f32_16x16x32_bf16 v[34:37], v[184:187], v[204:207], v[34:37]
	v_mfma_f32_16x16x32_bf16 v[22:25], v[176:179], v[212:215], v[22:25]
	v_mfma_f32_16x16x32_bf16 v[18:21], v[184:187], v[212:215], v[18:21]
	v_mfma_f32_16x16x32_bf16 v[6:9], v[176:179], v[220:223], v[6:9]
	v_mfma_f32_16x16x32_bf16 v[2:5], v[184:187], v[220:223], v[2:5]
	v_mfma_f32_16x16x32_bf16 v[54:57], v[180:183], v[200:203], v[54:57]
	v_mfma_f32_16x16x32_bf16 v[50:53], v[188:191], v[200:203], v[50:53]
	v_mfma_f32_16x16x32_bf16 v[38:41], v[180:183], v[208:211], v[38:41]
	v_mfma_f32_16x16x32_bf16 v[34:37], v[188:191], v[208:211], v[34:37]
	v_mfma_f32_16x16x32_bf16 v[22:25], v[180:183], v[216:219], v[22:25]
	v_mfma_f32_16x16x32_bf16 v[18:21], v[188:191], v[216:219], v[18:21]
	v_mfma_f32_16x16x32_bf16 v[6:9], v[180:183], v[224:227], v[6:9]
	v_mfma_f32_16x16x32_bf16 v[2:5], v[188:191], v[224:227], v[2:5]
	s_setprio 0
	s_barrier
	s_add_i32 s81, 0, 0x18000
	v_add_u32_e32 v163, s81, v158
	s_add_i32 s82, 0, 0x1c000
	ds_read_b128 v[152:155], v163
	ds_read_b128 v[164:167], v163 offset:1024
	ds_read_b128 v[168:171], v163 offset:2048
	ds_read_b128 v[172:175], v163 offset:3072
	v_add_u32_e32 v163, s82, v158
	ds_read_b128 v[176:179], v163
	ds_read_b128 v[180:183], v163 offset:1024
	ds_read_b128 v[184:187], v163 offset:2048
	ds_read_b128 v[188:191], v163 offset:3072
	s_add_u32 s60, s60, 0x20000
	s_addc_u32 s61, s61, 0
	s_mov_b32 m0, s63
	v_lshl_add_u64 v[232:233], s[60:61], 0, v[132:133]
	ds_read_b128 v[196:199], v162 offset:32768
	ds_read_b128 v[200:203], v162 offset:33792
	ds_read_b128 v[204:207], v162 offset:34816
	ds_read_b128 v[208:211], v162 offset:35840
	ds_read_b128 v[212:215], v162 offset:36864
	ds_read_b128 v[216:219], v162 offset:37888
	ds_read_b128 v[220:223], v162 offset:38912
	ds_read_b128 v[224:227], v162 offset:39936
	global_load_lds_dwordx4 v[232:233], off
	v_lshl_add_u64 v[232:233], s[60:61], 0, v[136:137]
	s_mov_b32 m0, s64
	s_nop 0
	global_load_lds_dwordx4 v[232:233], off
	s_waitcnt vmcnt(8)
	s_waitcnt lgkmcnt(0)
	s_barrier
	s_setprio 1
	v_mfma_f32_16x16x32_bf16 v[126:129], v[152:155], v[196:199], v[126:129]
	v_mfma_f32_16x16x32_bf16 v[122:125], v[168:171], v[196:199], v[122:125]
	v_mfma_f32_16x16x32_bf16 v[110:113], v[152:155], v[204:207], v[110:113]
	v_mfma_f32_16x16x32_bf16 v[106:109], v[168:171], v[204:207], v[106:109]
	v_mfma_f32_16x16x32_bf16 v[94:97], v[152:155], v[212:215], v[94:97]
	v_mfma_f32_16x16x32_bf16 v[90:93], v[168:171], v[212:215], v[90:93]
	v_mfma_f32_16x16x32_bf16 v[78:81], v[152:155], v[220:223], v[78:81]
	v_mfma_f32_16x16x32_bf16 v[74:77], v[168:171], v[220:223], v[74:77]
	v_mfma_f32_16x16x32_bf16 v[126:129], v[164:167], v[200:203], v[126:129]
	v_mfma_f32_16x16x32_bf16 v[122:125], v[172:175], v[200:203], v[122:125]
	v_mfma_f32_16x16x32_bf16 v[110:113], v[164:167], v[208:211], v[110:113]
	v_mfma_f32_16x16x32_bf16 v[106:109], v[172:175], v[208:211], v[106:109]
	v_mfma_f32_16x16x32_bf16 v[94:97], v[164:167], v[216:219], v[94:97]
	v_mfma_f32_16x16x32_bf16 v[90:93], v[172:175], v[216:219], v[90:93]
	v_mfma_f32_16x16x32_bf16 v[78:81], v[164:167], v[224:227], v[78:81]
	v_mfma_f32_16x16x32_bf16 v[74:77], v[172:175], v[224:227], v[74:77]
	v_mfma_f32_16x16x32_bf16 v[118:121], v[176:179], v[196:199], v[118:121]
	v_mfma_f32_16x16x32_bf16 v[114:117], v[184:187], v[196:199], v[114:117]
	v_mfma_f32_16x16x32_bf16 v[102:105], v[176:179], v[204:207], v[102:105]
	v_mfma_f32_16x16x32_bf16 v[98:101], v[184:187], v[204:207], v[98:101]
	v_mfma_f32_16x16x32_bf16 v[86:89], v[176:179], v[212:215], v[86:89]
	v_mfma_f32_16x16x32_bf16 v[82:85], v[184:187], v[212:215], v[82:85]
	v_mfma_f32_16x16x32_bf16 v[70:73], v[176:179], v[220:223], v[70:73]
	v_mfma_f32_16x16x32_bf16 v[66:69], v[184:187], v[220:223], v[66:69]
	v_mfma_f32_16x16x32_bf16 v[118:121], v[180:183], v[200:203], v[118:121]
	v_mfma_f32_16x16x32_bf16 v[114:117], v[188:191], v[200:203], v[114:117]
	v_mfma_f32_16x16x32_bf16 v[102:105], v[180:183], v[208:211], v[102:105]
	v_mfma_f32_16x16x32_bf16 v[98:101], v[188:191], v[208:211], v[98:101]
	v_mfma_f32_16x16x32_bf16 v[86:89], v[180:183], v[216:219], v[86:89]
	v_mfma_f32_16x16x32_bf16 v[82:85], v[188:191], v[216:219], v[82:85]
	v_mfma_f32_16x16x32_bf16 v[70:73], v[180:183], v[224:227], v[70:73]
	v_mfma_f32_16x16x32_bf16 v[66:69], v[188:191], v[224:227], v[66:69]
	s_setprio 0
	s_barrier
	s_add_i32 s60, s81, s62
	v_lshl_add_u64 v[156:157], v[156:157], 0, s[14:15]
	s_mov_b32 m0, s60
	ds_read_b128 v[196:199], v162 offset:49152
	ds_read_b128 v[200:203], v162 offset:50176
	ds_read_b128 v[204:207], v162 offset:51200
	ds_read_b128 v[208:211], v162 offset:52224
	ds_read_b128 v[212:215], v162 offset:53248
	ds_read_b128 v[216:219], v162 offset:54272
	ds_read_b128 v[220:223], v162 offset:55296
	ds_read_b128 v[224:227], v162 offset:56320
	global_load_lds_dwordx4 v[156:157], off
	s_add_i32 m0, s60, 0x2000
	s_add_u32 s48, s48, 0x20080
	v_lshl_add_u64 v[156:157], v[192:193], 0, s[14:15]
	s_addc_u32 s49, s49, 0
	s_add_i32 s60, s82, s62
	global_load_lds_dwordx4 v[156:157], off
	v_lshl_add_u64 v[156:157], s[48:49], 0, v[134:135]
	s_mov_b32 m0, s60
	s_nop 0
	global_load_lds_dwordx4 v[156:157], off
	v_lshl_add_u64 v[156:157], s[48:49], 0, v[138:139]
	s_add_i32 m0, s60, 0x2000
	s_nop 0
	global_load_lds_dwordx4 v[156:157], off
	v_lshl_add_u64 v[156:157], v[228:229], 0, s[14:15]
	s_mov_b32 m0, s68
	s_nop 0
	global_load_lds_dwordx4 v[156:157], off
	v_lshl_add_u64 v[156:157], v[230:231], 0, s[14:15]
	s_mov_b32 m0, s69
	s_nop 0
	global_load_lds_dwordx4 v[156:157], off
	s_nop 0
	s_waitcnt vmcnt(8)
	s_waitcnt lgkmcnt(0)
	s_barrier
	s_setprio 1
	v_mfma_f32_16x16x32_bf16 v[62:65], v[152:155], v[196:199], v[62:65]
	v_mfma_f32_16x16x32_bf16 v[58:61], v[168:171], v[196:199], v[58:61]
	v_mfma_f32_16x16x32_bf16 v[46:49], v[152:155], v[204:207], v[46:49]
	v_mfma_f32_16x16x32_bf16 v[42:45], v[168:171], v[204:207], v[42:45]
	v_mfma_f32_16x16x32_bf16 v[30:33], v[152:155], v[212:215], v[30:33]
	v_mfma_f32_16x16x32_bf16 v[26:29], v[168:171], v[212:215], v[26:29]
	v_mfma_f32_16x16x32_bf16 v[14:17], v[152:155], v[220:223], v[14:17]
	v_mfma_f32_16x16x32_bf16 v[10:13], v[168:171], v[220:223], v[10:13]
	v_mfma_f32_16x16x32_bf16 v[62:65], v[164:167], v[200:203], v[62:65]
	v_mfma_f32_16x16x32_bf16 v[58:61], v[172:175], v[200:203], v[58:61]
	v_mfma_f32_16x16x32_bf16 v[46:49], v[164:167], v[208:211], v[46:49]
	v_mfma_f32_16x16x32_bf16 v[42:45], v[172:175], v[208:211], v[42:45]
	v_mfma_f32_16x16x32_bf16 v[30:33], v[164:167], v[216:219], v[30:33]
	v_mfma_f32_16x16x32_bf16 v[26:29], v[172:175], v[216:219], v[26:29]
	v_mfma_f32_16x16x32_bf16 v[14:17], v[164:167], v[224:227], v[14:17]
	v_mfma_f32_16x16x32_bf16 v[10:13], v[172:175], v[224:227], v[10:13]
	v_mfma_f32_16x16x32_bf16 v[54:57], v[176:179], v[196:199], v[54:57]
	v_mfma_f32_16x16x32_bf16 v[50:53], v[184:187], v[196:199], v[50:53]
	v_mfma_f32_16x16x32_bf16 v[38:41], v[176:179], v[204:207], v[38:41]
	v_mfma_f32_16x16x32_bf16 v[34:37], v[184:187], v[204:207], v[34:37]
	v_mfma_f32_16x16x32_bf16 v[22:25], v[176:179], v[212:215], v[22:25]
	v_mfma_f32_16x16x32_bf16 v[18:21], v[184:187], v[212:215], v[18:21]
	v_mfma_f32_16x16x32_bf16 v[6:9], v[176:179], v[220:223], v[6:9]
	v_mfma_f32_16x16x32_bf16 v[2:5], v[184:187], v[220:223], v[2:5]
	v_mfma_f32_16x16x32_bf16 v[54:57], v[180:183], v[200:203], v[54:57]
	v_mfma_f32_16x16x32_bf16 v[50:53], v[188:191], v[200:203], v[50:53]
	v_mfma_f32_16x16x32_bf16 v[38:41], v[180:183], v[208:211], v[38:41]
	v_mfma_f32_16x16x32_bf16 v[34:37], v[188:191], v[208:211], v[34:37]
	v_mfma_f32_16x16x32_bf16 v[22:25], v[180:183], v[216:219], v[22:25]
	v_mfma_f32_16x16x32_bf16 v[18:21], v[188:191], v[216:219], v[18:21]
	v_mfma_f32_16x16x32_bf16 v[6:9], v[180:183], v[224:227], v[6:9]
	v_mfma_f32_16x16x32_bf16 v[2:5], v[188:191], v[224:227], v[2:5]
	s_setprio 0
	s_barrier
	s_add_u32 s58, s58, 0x100
	s_addc_u32 s59, s59, 0
	s_add_u32 s47, s47, 0x100
	s_addc_u32 s51, s51, 0
	s_cmp_ge_i32 s80, s79
	s_mov_b32 s48, s80
	s_cbranch_scc0 .LBB0_3983
	s_and_b64 vcc, exec, s[16:17]
	s_cbranch_vccz .LBB0_3986
	s_barrier

.LBB0_4145:
	ds_read_b128 v[156:159], v162
	ds_read_b128 v[166:169], v162 offset:1024
	ds_read_b128 v[170:173], v162 offset:2048
	ds_read_b128 v[174:177], v162 offset:3072
	ds_read_b128 v[178:181], v163
	ds_read_b128 v[182:185], v163 offset:1024
	ds_read_b128 v[186:189], v163 offset:2048
	ds_read_b128 v[190:193], v163 offset:3072
	s_add_i32 s72, s42, 2
	s_add_u32 s43, s40, 0xfff00080
	s_addc_u32 s46, s41, -1
	s_cmp_eq_u32 s69, s42
	s_cselect_b32 s42, s25, s70
	s_cselect_b32 s47, s5, s46
	s_cselect_b32 s46, s23, s43
	s_cselect_b32 s43, s21, s71
	v_lshl_add_u64 v[228:229], s[40:41], 0, v[148:149]
	s_add_i32 m0, s35, 0xc000
	ds_read_b128 v[196:199], v164
	ds_read_b128 v[200:203], v164 offset:1024
	ds_read_b128 v[204:207], v164 offset:2048
	ds_read_b128 v[208:211], v164 offset:3072
	ds_read_b128 v[212:215], v164 offset:4096
	ds_read_b128 v[216:219], v164 offset:5120
	ds_read_b128 v[220:223], v164 offset:6144
	ds_read_b128 v[224:227], v164 offset:7168
	global_load_lds_dwordx4 v[228:229], off
	v_lshl_add_u64 v[228:229], s[40:41], 0, v[150:151]
	s_add_i32 m0, s35, 0xe000
	s_nop 0
	global_load_lds_dwordx4 v[228:229], off
	s_nop 0
	s_waitcnt vmcnt(8)
	s_waitcnt lgkmcnt(0)
	s_barrier
	s_setprio 1
	v_mfma_f32_16x16x32_bf16 v[78:81], v[156:159], v[196:199], v[78:81]
	v_mfma_f32_16x16x32_bf16 v[74:77], v[170:173], v[196:199], v[74:77]
	v_mfma_f32_16x16x32_bf16 v[70:73], v[156:159], v[204:207], v[70:73]
	v_mfma_f32_16x16x32_bf16 v[62:65], v[170:173], v[204:207], v[62:65]
	v_mfma_f32_16x16x32_bf16 v[58:61], v[156:159], v[212:215], v[58:61]
	v_mfma_f32_16x16x32_bf16 v[54:57], v[170:173], v[212:215], v[54:57]
	v_mfma_f32_16x16x32_bf16 v[46:49], v[156:159], v[220:223], v[46:49]
	v_mfma_f32_16x16x32_bf16 v[38:41], v[170:173], v[220:223], v[38:41]
	v_mfma_f32_16x16x32_bf16 v[78:81], v[166:169], v[200:203], v[78:81]
	v_mfma_f32_16x16x32_bf16 v[74:77], v[174:177], v[200:203], v[74:77]
	v_mfma_f32_16x16x32_bf16 v[70:73], v[166:169], v[208:211], v[70:73]
	v_mfma_f32_16x16x32_bf16 v[62:65], v[174:177], v[208:211], v[62:65]
	v_mfma_f32_16x16x32_bf16 v[58:61], v[166:169], v[216:219], v[58:61]
	v_mfma_f32_16x16x32_bf16 v[54:57], v[174:177], v[216:219], v[54:57]
	v_mfma_f32_16x16x32_bf16 v[46:49], v[166:169], v[224:227], v[46:49]
	v_mfma_f32_16x16x32_bf16 v[38:41], v[174:177], v[224:227], v[38:41]
	v_mfma_f32_16x16x32_bf16 v[50:53], v[178:181], v[196:199], v[50:53]
	v_mfma_f32_16x16x32_bf16 v[42:45], v[186:189], v[196:199], v[42:45]
	v_mfma_f32_16x16x32_bf16 v[34:37], v[178:181], v[204:207], v[34:37]
	v_mfma_f32_16x16x32_bf16 v[26:29], v[186:189], v[204:207], v[26:29]
	v_mfma_f32_16x16x32_bf16 v[18:21], v[178:181], v[212:215], v[18:21]
	v_mfma_f32_16x16x32_bf16 v[14:17], v[186:189], v[212:215], v[14:17]
	v_mfma_f32_16x16x32_bf16 v[10:13], v[178:181], v[220:223], v[10:13]
	v_mfma_f32_16x16x32_bf16 v[6:9], v[186:189], v[220:223], v[6:9]
	v_mfma_f32_16x16x32_bf16 v[50:53], v[182:185], v[200:203], v[50:53]
	v_mfma_f32_16x16x32_bf16 v[42:45], v[190:193], v[200:203], v[42:45]
	v_mfma_f32_16x16x32_bf16 v[34:37], v[182:185], v[208:211], v[34:37]
	v_mfma_f32_16x16x32_bf16 v[26:29], v[190:193], v[208:211], v[26:29]
	v_mfma_f32_16x16x32_bf16 v[18:21], v[182:185], v[216:219], v[18:21]
	v_mfma_f32_16x16x32_bf16 v[14:17], v[190:193], v[216:219], v[14:17]
	v_mfma_f32_16x16x32_bf16 v[10:13], v[182:185], v[224:227], v[10:13]
	v_mfma_f32_16x16x32_bf16 v[6:9], v[190:193], v[224:227], v[6:9]
	s_setprio 0
	s_barrier
	s_add_i32 s73, s62, s49
	v_lshl_add_u64 v[228:229], s[42:43], 0, v[134:135]
	s_mov_b32 m0, s73
	ds_read_b128 v[196:199], v164 offset:16384
	ds_read_b128 v[200:203], v164 offset:17408
	ds_read_b128 v[204:207], v164 offset:18432
	ds_read_b128 v[208:211], v164 offset:19456
	ds_read_b128 v[212:215], v164 offset:20480
	ds_read_b128 v[216:219], v164 offset:21504
	ds_read_b128 v[220:223], v164 offset:22528
	ds_read_b128 v[224:227], v164 offset:23552
	global_load_lds_dwordx4 v[228:229], off
	s_add_i32 m0, s73, 0x2000
	s_add_u32 s74, s42, 0x100000
	v_lshl_add_u64 v[230:231], s[42:43], 0, v[138:139]
	s_addc_u32 s75, s43, 0
	s_add_i32 s73, s63, s49
	global_load_lds_dwordx4 v[230:231], off
	v_lshl_add_u64 v[232:233], s[74:75], 0, v[134:135]
	s_mov_b32 m0, s73
	v_lshl_add_u64 v[234:235], s[46:47], 0, v[136:137]
	global_load_lds_dwordx4 v[232:233], off
	v_lshl_add_u64 v[232:233], s[74:75], 0, v[138:139]
	s_add_i32 m0, s73, 0x2000
	s_nop 0
	global_load_lds_dwordx4 v[232:233], off
	v_lshl_add_u64 v[232:233], s[46:47], 0, v[132:133]
	s_mov_b32 m0, s35
	s_nop 0
	global_load_lds_dwordx4 v[232:233], off
	s_mov_b32 m0, s50
	s_nop 0
	global_load_lds_dwordx4 v[234:235], off
	s_waitcnt vmcnt(8)
	s_waitcnt lgkmcnt(0)
	s_barrier
	s_setprio 1
	v_mfma_f32_16x16x32_bf16 v[126:129], v[156:159], v[196:199], v[126:129]
	v_mfma_f32_16x16x32_bf16 v[118:121], v[170:173], v[196:199], v[118:121]
	v_mfma_f32_16x16x32_bf16 v[110:113], v[156:159], v[204:207], v[110:113]
	v_mfma_f32_16x16x32_bf16 v[102:105], v[170:173], v[204:207], v[102:105]
	v_mfma_f32_16x16x32_bf16 v[94:97], v[156:159], v[212:215], v[94:97]
	v_mfma_f32_16x16x32_bf16 v[86:89], v[170:173], v[212:215], v[86:89]
	v_mfma_f32_16x16x32_bf16 v[66:69], v[156:159], v[220:223], v[66:69]
	v_mfma_f32_16x16x32_bf16 v[22:25], v[170:173], v[220:223], v[22:25]
	v_mfma_f32_16x16x32_bf16 v[126:129], v[166:169], v[200:203], v[126:129]
	v_mfma_f32_16x16x32_bf16 v[118:121], v[174:177], v[200:203], v[118:121]
	v_mfma_f32_16x16x32_bf16 v[110:113], v[166:169], v[208:211], v[110:113]
	v_mfma_f32_16x16x32_bf16 v[102:105], v[174:177], v[208:211], v[102:105]
	v_mfma_f32_16x16x32_bf16 v[94:97], v[166:169], v[216:219], v[94:97]
	v_mfma_f32_16x16x32_bf16 v[86:89], v[174:177], v[216:219], v[86:89]
	v_mfma_f32_16x16x32_bf16 v[66:69], v[166:169], v[224:227], v[66:69]
	v_mfma_f32_16x16x32_bf16 v[22:25], v[174:177], v[224:227], v[22:25]
	v_mfma_f32_16x16x32_bf16 v[122:125], v[178:181], v[196:199], v[122:125]
	v_mfma_f32_16x16x32_bf16 v[114:117], v[186:189], v[196:199], v[114:117]
	v_mfma_f32_16x16x32_bf16 v[106:109], v[178:181], v[204:207], v[106:109]
	v_mfma_f32_16x16x32_bf16 v[98:101], v[186:189], v[204:207], v[98:101]
	v_mfma_f32_16x16x32_bf16 v[90:93], v[178:181], v[212:215], v[90:93]
	v_mfma_f32_16x16x32_bf16 v[82:85], v[186:189], v[212:215], v[82:85]
	v_mfma_f32_16x16x32_bf16 v[30:33], v[178:181], v[220:223], v[30:33]
	v_mfma_f32_16x16x32_bf16 v[2:5], v[186:189], v[220:223], v[2:5]
	v_mfma_f32_16x16x32_bf16 v[122:125], v[182:185], v[200:203], v[122:125]
	v_mfma_f32_16x16x32_bf16 v[114:117], v[190:193], v[200:203], v[114:117]
	v_mfma_f32_16x16x32_bf16 v[106:109], v[182:185], v[208:211], v[106:109]
	v_mfma_f32_16x16x32_bf16 v[98:101], v[190:193], v[208:211], v[98:101]
	v_mfma_f32_16x16x32_bf16 v[90:93], v[182:185], v[216:219], v[90:93]
	v_mfma_f32_16x16x32_bf16 v[82:85], v[190:193], v[216:219], v[82:85]
	v_mfma_f32_16x16x32_bf16 v[30:33], v[182:185], v[224:227], v[30:33]
	v_mfma_f32_16x16x32_bf16 v[2:5], v[190:193], v[224:227], v[2:5]
	s_setprio 0
	s_barrier
	s_add_i32 s73, 0, 0x18000
	v_add_u32_e32 v165, s73, v160
	s_add_i32 s74, 0, 0x1c000
	ds_read_b128 v[156:159], v165
	ds_read_b128 v[166:169], v165 offset:1024
	ds_read_b128 v[170:173], v165 offset:2048
	ds_read_b128 v[174:177], v165 offset:3072
	v_add_u32_e32 v165, s74, v160
	ds_read_b128 v[178:181], v165
	ds_read_b128 v[182:185], v165 offset:1024
	ds_read_b128 v[186:189], v165 offset:2048
	ds_read_b128 v[190:193], v165 offset:3072
	s_add_u32 s46, s46, 0x100000
	s_addc_u32 s47, s47, 0
	s_mov_b32 m0, s51
	v_lshl_add_u64 v[236:237], s[46:47], 0, v[132:133]
	ds_read_b128 v[196:199], v164 offset:32768
	ds_read_b128 v[200:203], v164 offset:33792
	ds_read_b128 v[204:207], v164 offset:34816
	ds_read_b128 v[208:211], v164 offset:35840
	ds_read_b128 v[212:215], v164 offset:36864
	ds_read_b128 v[216:219], v164 offset:37888
	ds_read_b128 v[220:223], v164 offset:38912
	ds_read_b128 v[224:227], v164 offset:39936
	global_load_lds_dwordx4 v[236:237], off
	v_lshl_add_u64 v[236:237], s[46:47], 0, v[136:137]
	s_mov_b32 m0, s52
	s_nop 0
	global_load_lds_dwordx4 v[236:237], off
	s_waitcnt vmcnt(8)
	s_waitcnt lgkmcnt(0)
	s_barrier
	s_setprio 1
	v_mfma_f32_16x16x32_bf16 v[78:81], v[156:159], v[196:199], v[78:81]
	v_mfma_f32_16x16x32_bf16 v[74:77], v[170:173], v[196:199], v[74:77]
	v_mfma_f32_16x16x32_bf16 v[70:73], v[156:159], v[204:207], v[70:73]
	v_mfma_f32_16x16x32_bf16 v[62:65], v[170:173], v[204:207], v[62:65]
	v_mfma_f32_16x16x32_bf16 v[58:61], v[156:159], v[212:215], v[58:61]
	v_mfma_f32_16x16x32_bf16 v[54:57], v[170:173], v[212:215], v[54:57]
	v_mfma_f32_16x16x32_bf16 v[46:49], v[156:159], v[220:223], v[46:49]
	v_mfma_f32_16x16x32_bf16 v[38:41], v[170:173], v[220:223], v[38:41]
	v_mfma_f32_16x16x32_bf16 v[78:81], v[166:169], v[200:203], v[78:81]
	v_mfma_f32_16x16x32_bf16 v[74:77], v[174:177], v[200:203], v[74:77]
	v_mfma_f32_16x16x32_bf16 v[70:73], v[166:169], v[208:211], v[70:73]
	v_mfma_f32_16x16x32_bf16 v[62:65], v[174:177], v[208:211], v[62:65]
	v_mfma_f32_16x16x32_bf16 v[58:61], v[166:169], v[216:219], v[58:61]
	v_mfma_f32_16x16x32_bf16 v[54:57], v[174:177], v[216:219], v[54:57]
	v_mfma_f32_16x16x32_bf16 v[46:49], v[166:169], v[224:227], v[46:49]
	v_mfma_f32_16x16x32_bf16 v[38:41], v[174:177], v[224:227], v[38:41]
	v_mfma_f32_16x16x32_bf16 v[50:53], v[178:181], v[196:199], v[50:53]
	v_mfma_f32_16x16x32_bf16 v[42:45], v[186:189], v[196:199], v[42:45]
	v_mfma_f32_16x16x32_bf16 v[34:37], v[178:181], v[204:207], v[34:37]
	v_mfma_f32_16x16x32_bf16 v[26:29], v[186:189], v[204:207], v[26:29]
	v_mfma_f32_16x16x32_bf16 v[18:21], v[178:181], v[212:215], v[18:21]
	v_mfma_f32_16x16x32_bf16 v[14:17], v[186:189], v[212:215], v[14:17]
	v_mfma_f32_16x16x32_bf16 v[10:13], v[178:181], v[220:223], v[10:13]
	v_mfma_f32_16x16x32_bf16 v[6:9], v[186:189], v[220:223], v[6:9]
	v_mfma_f32_16x16x32_bf16 v[50:53], v[182:185], v[200:203], v[50:53]
	v_mfma_f32_16x16x32_bf16 v[42:45], v[190:193], v[200:203], v[42:45]
	v_mfma_f32_16x16x32_bf16 v[34:37], v[182:185], v[208:211], v[34:37]
	v_mfma_f32_16x16x32_bf16 v[26:29], v[190:193], v[208:211], v[26:29]
	v_mfma_f32_16x16x32_bf16 v[18:21], v[182:185], v[216:219], v[18:21]
	v_mfma_f32_16x16x32_bf16 v[14:17], v[190:193], v[216:219], v[14:17]
	v_mfma_f32_16x16x32_bf16 v[10:13], v[182:185], v[224:227], v[10:13]
	v_mfma_f32_16x16x32_bf16 v[6:9], v[190:193], v[224:227], v[6:9]
	s_setprio 0
	s_barrier
	s_add_i32 s46, s73, s49
	v_lshl_add_u64 v[228:229], v[228:229], 0, s[10:11]
	s_mov_b32 m0, s46
	ds_read_b128 v[196:199], v164 offset:49152
	ds_read_b128 v[200:203], v164 offset:50176
	ds_read_b128 v[204:207], v164 offset:51200
	ds_read_b128 v[208:211], v164 offset:52224
	ds_read_b128 v[212:215], v164 offset:53248
	ds_read_b128 v[216:219], v164 offset:54272
	ds_read_b128 v[220:223], v164 offset:55296
	ds_read_b128 v[224:227], v164 offset:56320
	global_load_lds_dwordx4 v[228:229], off
	s_add_i32 m0, s46, 0x2000
	s_add_u32 s42, s42, 0x100080
	v_lshl_add_u64 v[228:229], v[230:231], 0, s[10:11]
	s_addc_u32 s43, s43, 0
	s_add_i32 s46, s74, s49
	global_load_lds_dwordx4 v[228:229], off
	v_lshl_add_u64 v[228:229], s[42:43], 0, v[134:135]
	s_mov_b32 m0, s46
	s_nop 0
	global_load_lds_dwordx4 v[228:229], off
	v_lshl_add_u64 v[228:229], s[42:43], 0, v[138:139]
	s_add_i32 m0, s46, 0x2000
	s_nop 0
	global_load_lds_dwordx4 v[228:229], off
	v_lshl_add_u64 v[228:229], v[232:233], 0, s[10:11]
	s_mov_b32 m0, s55
	s_nop 0
	global_load_lds_dwordx4 v[228:229], off
	v_lshl_add_u64 v[228:229], v[234:235], 0, s[10:11]
	s_mov_b32 m0, s56
	s_nop 0
	global_load_lds_dwordx4 v[228:229], off
	s_nop 0
	s_waitcnt vmcnt(8)
	s_waitcnt lgkmcnt(0)
	s_barrier
	s_setprio 1
	v_mfma_f32_16x16x32_bf16 v[126:129], v[156:159], v[196:199], v[126:129]
	v_mfma_f32_16x16x32_bf16 v[118:121], v[170:173], v[196:199], v[118:121]
	v_mfma_f32_16x16x32_bf16 v[110:113], v[156:159], v[204:207], v[110:113]
	v_mfma_f32_16x16x32_bf16 v[102:105], v[170:173], v[204:207], v[102:105]
	v_mfma_f32_16x16x32_bf16 v[94:97], v[156:159], v[212:215], v[94:97]
	v_mfma_f32_16x16x32_bf16 v[86:89], v[170:173], v[212:215], v[86:89]
	v_mfma_f32_16x16x32_bf16 v[66:69], v[156:159], v[220:223], v[66:69]
	v_mfma_f32_16x16x32_bf16 v[22:25], v[170:173], v[220:223], v[22:25]
	v_mfma_f32_16x16x32_bf16 v[126:129], v[166:169], v[200:203], v[126:129]
	v_mfma_f32_16x16x32_bf16 v[118:121], v[174:177], v[200:203], v[118:121]
	v_mfma_f32_16x16x32_bf16 v[110:113], v[166:169], v[208:211], v[110:113]
	v_mfma_f32_16x16x32_bf16 v[102:105], v[174:177], v[208:211], v[102:105]
	v_mfma_f32_16x16x32_bf16 v[94:97], v[166:169], v[216:219], v[94:97]
	v_mfma_f32_16x16x32_bf16 v[86:89], v[174:177], v[216:219], v[86:89]
	v_mfma_f32_16x16x32_bf16 v[66:69], v[166:169], v[224:227], v[66:69]
	v_mfma_f32_16x16x32_bf16 v[22:25], v[174:177], v[224:227], v[22:25]
	v_mfma_f32_16x16x32_bf16 v[122:125], v[178:181], v[196:199], v[122:125]
	v_mfma_f32_16x16x32_bf16 v[114:117], v[186:189], v[196:199], v[114:117]
	v_mfma_f32_16x16x32_bf16 v[106:109], v[178:181], v[204:207], v[106:109]
	v_mfma_f32_16x16x32_bf16 v[98:101], v[186:189], v[204:207], v[98:101]
	v_mfma_f32_16x16x32_bf16 v[90:93], v[178:181], v[212:215], v[90:93]
	v_mfma_f32_16x16x32_bf16 v[82:85], v[186:189], v[212:215], v[82:85]
	v_mfma_f32_16x16x32_bf16 v[30:33], v[178:181], v[220:223], v[30:33]
	v_mfma_f32_16x16x32_bf16 v[2:5], v[186:189], v[220:223], v[2:5]
	v_mfma_f32_16x16x32_bf16 v[122:125], v[182:185], v[200:203], v[122:125]
	v_mfma_f32_16x16x32_bf16 v[114:117], v[190:193], v[200:203], v[114:117]
	v_mfma_f32_16x16x32_bf16 v[106:109], v[182:185], v[208:211], v[106:109]
	v_mfma_f32_16x16x32_bf16 v[98:101], v[190:193], v[208:211], v[98:101]
	v_mfma_f32_16x16x32_bf16 v[90:93], v[182:185], v[216:219], v[90:93]
	v_mfma_f32_16x16x32_bf16 v[82:85], v[190:193], v[216:219], v[82:85]
	v_mfma_f32_16x16x32_bf16 v[30:33], v[182:185], v[224:227], v[30:33]
	v_mfma_f32_16x16x32_bf16 v[2:5], v[190:193], v[224:227], v[2:5]
	s_setprio 0
	s_barrier
	s_add_u32 s40, s40, 0x100
	s_addc_u32 s41, s41, 0
	s_add_u32 s70, s70, 0x100
	s_addc_u32 s71, s71, 0
	s_cmp_ge_i32 s72, s68
	s_mov_b32 s42, s72
	s_cbranch_scc0 .LBB0_4145
	s_and_b64 vcc, exec, s[12:13]
	s_cbranch_vccz .LBB0_4150
	s_barrier
	s_cmp_lt_i32 s48, 0
	s_mov_b64 s[40:41], -1
	s_cbranch_scc1 .LBB0_4151

.LBB0_4304:
	ds_read_b128 v[150:153], v158
	ds_read_b128 v[162:165], v158 offset:1024
	ds_read_b128 v[166:169], v158 offset:2048
	ds_read_b128 v[170:173], v158 offset:3072
	ds_read_b128 v[174:177], v159
	ds_read_b128 v[178:181], v159 offset:1024
	ds_read_b128 v[182:185], v159 offset:2048
	ds_read_b128 v[186:189], v159 offset:3072
	s_add_i32 s80, s48, 2
	s_add_u32 s49, s50, 0xffd50080
	s_addc_u32 s52, s51, -1
	s_cmp_eq_u32 s43, s48
	s_cselect_b32 s48, s46, s78
	s_cselect_b32 s53, s5, s52
	s_cselect_b32 s52, s4, s49
	s_cselect_b32 s49, s47, s79
	v_lshl_add_u64 v[154:155], s[50:51], 0, v[138:139]
	s_add_i32 m0, s55, 0xc000
	ds_read_b128 v[190:193], v160
	ds_read_b128 v[196:199], v160 offset:1024
	ds_read_b128 v[200:203], v160 offset:2048
	ds_read_b128 v[204:207], v160 offset:3072
	ds_read_b128 v[208:211], v160 offset:4096
	ds_read_b128 v[212:215], v160 offset:5120
	ds_read_b128 v[216:219], v160 offset:6144
	ds_read_b128 v[220:223], v160 offset:7168
	global_load_lds_dwordx4 v[154:155], off
	v_lshl_add_u64 v[154:155], s[50:51], 0, v[140:141]
	s_add_i32 m0, s55, 0xe000
	s_nop 0
	global_load_lds_dwordx4 v[154:155], off
	s_nop 0
	s_waitcnt vmcnt(8)
	s_waitcnt lgkmcnt(0)
	s_barrier
	s_setprio 1
	v_mfma_f32_16x16x32_bf16 v[124:127], v[150:153], v[190:193], v[124:127]
	v_mfma_f32_16x16x32_bf16 v[120:123], v[166:169], v[190:193], v[120:123]
	v_mfma_f32_16x16x32_bf16 v[108:111], v[150:153], v[200:203], v[108:111]
	v_mfma_f32_16x16x32_bf16 v[104:107], v[166:169], v[200:203], v[104:107]
	v_mfma_f32_16x16x32_bf16 v[92:95], v[150:153], v[208:211], v[92:95]
	v_mfma_f32_16x16x32_bf16 v[88:91], v[166:169], v[208:211], v[88:91]
	v_mfma_f32_16x16x32_bf16 v[76:79], v[150:153], v[216:219], v[76:79]
	v_mfma_f32_16x16x32_bf16 v[72:75], v[166:169], v[216:219], v[72:75]
	v_mfma_f32_16x16x32_bf16 v[124:127], v[162:165], v[196:199], v[124:127]
	v_mfma_f32_16x16x32_bf16 v[120:123], v[170:173], v[196:199], v[120:123]
	v_mfma_f32_16x16x32_bf16 v[108:111], v[162:165], v[204:207], v[108:111]
	v_mfma_f32_16x16x32_bf16 v[104:107], v[170:173], v[204:207], v[104:107]
	v_mfma_f32_16x16x32_bf16 v[92:95], v[162:165], v[212:215], v[92:95]
	v_mfma_f32_16x16x32_bf16 v[88:91], v[170:173], v[212:215], v[88:91]
	v_mfma_f32_16x16x32_bf16 v[76:79], v[162:165], v[220:223], v[76:79]
	v_mfma_f32_16x16x32_bf16 v[72:75], v[170:173], v[220:223], v[72:75]
	v_mfma_f32_16x16x32_bf16 v[116:119], v[174:177], v[190:193], v[116:119]
	v_mfma_f32_16x16x32_bf16 v[112:115], v[182:185], v[190:193], v[112:115]
	v_mfma_f32_16x16x32_bf16 v[100:103], v[174:177], v[200:203], v[100:103]
	v_mfma_f32_16x16x32_bf16 v[96:99], v[182:185], v[200:203], v[96:99]
	v_mfma_f32_16x16x32_bf16 v[84:87], v[174:177], v[208:211], v[84:87]
	v_mfma_f32_16x16x32_bf16 v[80:83], v[182:185], v[208:211], v[80:83]
	v_mfma_f32_16x16x32_bf16 v[68:71], v[174:177], v[216:219], v[68:71]
	v_mfma_f32_16x16x32_bf16 v[64:67], v[182:185], v[216:219], v[64:67]
	v_mfma_f32_16x16x32_bf16 v[116:119], v[178:181], v[196:199], v[116:119]
	v_mfma_f32_16x16x32_bf16 v[112:115], v[186:189], v[196:199], v[112:115]
	v_mfma_f32_16x16x32_bf16 v[100:103], v[178:181], v[204:207], v[100:103]
	v_mfma_f32_16x16x32_bf16 v[96:99], v[186:189], v[204:207], v[96:99]
	v_mfma_f32_16x16x32_bf16 v[84:87], v[178:181], v[212:215], v[84:87]
	v_mfma_f32_16x16x32_bf16 v[80:83], v[186:189], v[212:215], v[80:83]
	v_mfma_f32_16x16x32_bf16 v[68:71], v[178:181], v[220:223], v[68:71]
	v_mfma_f32_16x16x32_bf16 v[64:67], v[186:189], v[220:223], v[64:67]
	s_setprio 0
	s_barrier
	s_add_i32 s81, s65, s54
	v_lshl_add_u64 v[154:155], s[48:49], 0, v[132:133]
	s_mov_b32 m0, s81
	ds_read_b128 v[190:193], v160 offset:16384
	ds_read_b128 v[196:199], v160 offset:17408
	ds_read_b128 v[200:203], v160 offset:18432
	ds_read_b128 v[204:207], v160 offset:19456
	ds_read_b128 v[208:211], v160 offset:20480
	ds_read_b128 v[212:215], v160 offset:21504
	ds_read_b128 v[216:219], v160 offset:22528
	ds_read_b128 v[220:223], v160 offset:23552
	global_load_lds_dwordx4 v[154:155], off
	s_add_i32 m0, s81, 0x2000
	s_add_u32 s82, s48, 0x2b0000
	v_lshl_add_u64 v[224:225], s[48:49], 0, v[136:137]
	s_addc_u32 s83, s49, 0
	s_add_i32 s81, s66, s54
	global_load_lds_dwordx4 v[224:225], off
	v_lshl_add_u64 v[226:227], s[82:83], 0, v[132:133]
	s_mov_b32 m0, s81
	v_lshl_add_u64 v[228:229], s[52:53], 0, v[134:135]
	global_load_lds_dwordx4 v[226:227], off
	v_lshl_add_u64 v[226:227], s[82:83], 0, v[136:137]
	s_add_i32 m0, s81, 0x2000
	s_nop 0
	global_load_lds_dwordx4 v[226:227], off
	v_lshl_add_u64 v[226:227], s[52:53], 0, v[128:129]
	s_mov_b32 m0, s55
	s_nop 0
	global_load_lds_dwordx4 v[226:227], off
	s_mov_b32 m0, s56
	s_nop 0
	global_load_lds_dwordx4 v[228:229], off
	s_waitcnt vmcnt(8)
	s_waitcnt lgkmcnt(0)
	s_barrier
	s_setprio 1
	v_mfma_f32_16x16x32_bf16 v[60:63], v[150:153], v[190:193], v[60:63]
	v_mfma_f32_16x16x32_bf16 v[56:59], v[166:169], v[190:193], v[56:59]
	v_mfma_f32_16x16x32_bf16 v[44:47], v[150:153], v[200:203], v[44:47]
	v_mfma_f32_16x16x32_bf16 v[40:43], v[166:169], v[200:203], v[40:43]
	v_mfma_f32_16x16x32_bf16 v[28:31], v[150:153], v[208:211], v[28:31]
	v_mfma_f32_16x16x32_bf16 v[24:27], v[166:169], v[208:211], v[24:27]
	v_mfma_f32_16x16x32_bf16 v[12:15], v[150:153], v[216:219], v[12:15]
	v_mfma_f32_16x16x32_bf16 v[8:11], v[166:169], v[216:219], v[8:11]
	v_mfma_f32_16x16x32_bf16 v[60:63], v[162:165], v[196:199], v[60:63]
	v_mfma_f32_16x16x32_bf16 v[56:59], v[170:173], v[196:199], v[56:59]
	v_mfma_f32_16x16x32_bf16 v[44:47], v[162:165], v[204:207], v[44:47]
	v_mfma_f32_16x16x32_bf16 v[40:43], v[170:173], v[204:207], v[40:43]
	v_mfma_f32_16x16x32_bf16 v[28:31], v[162:165], v[212:215], v[28:31]
	v_mfma_f32_16x16x32_bf16 v[24:27], v[170:173], v[212:215], v[24:27]
	v_mfma_f32_16x16x32_bf16 v[12:15], v[162:165], v[220:223], v[12:15]
	v_mfma_f32_16x16x32_bf16 v[8:11], v[170:173], v[220:223], v[8:11]
	v_mfma_f32_16x16x32_bf16 v[52:55], v[174:177], v[190:193], v[52:55]
	v_mfma_f32_16x16x32_bf16 v[48:51], v[182:185], v[190:193], v[48:51]
	v_mfma_f32_16x16x32_bf16 v[36:39], v[174:177], v[200:203], v[36:39]
	v_mfma_f32_16x16x32_bf16 v[32:35], v[182:185], v[200:203], v[32:35]
	v_mfma_f32_16x16x32_bf16 v[20:23], v[174:177], v[208:211], v[20:23]
	v_mfma_f32_16x16x32_bf16 v[16:19], v[182:185], v[208:211], v[16:19]
	v_mfma_f32_16x16x32_bf16 v[4:7], v[174:177], v[216:219], v[4:7]
	v_mfma_f32_16x16x32_bf16 v[0:3], v[182:185], v[216:219], v[0:3]
	v_mfma_f32_16x16x32_bf16 v[52:55], v[178:181], v[196:199], v[52:55]
	v_mfma_f32_16x16x32_bf16 v[48:51], v[186:189], v[196:199], v[48:51]
	v_mfma_f32_16x16x32_bf16 v[36:39], v[178:181], v[204:207], v[36:39]
	v_mfma_f32_16x16x32_bf16 v[32:35], v[186:189], v[204:207], v[32:35]
	v_mfma_f32_16x16x32_bf16 v[20:23], v[178:181], v[212:215], v[20:23]
	v_mfma_f32_16x16x32_bf16 v[16:19], v[186:189], v[212:215], v[16:19]
	v_mfma_f32_16x16x32_bf16 v[4:7], v[178:181], v[220:223], v[4:7]
	v_mfma_f32_16x16x32_bf16 v[0:3], v[186:189], v[220:223], v[0:3]
	s_setprio 0
	s_barrier
	s_add_i32 s81, 0, 0x18000
	v_add_u32_e32 v161, s81, v156
	s_add_i32 s82, 0, 0x1c000
	ds_read_b128 v[150:153], v161
	ds_read_b128 v[162:165], v161 offset:1024
	ds_read_b128 v[166:169], v161 offset:2048
	ds_read_b128 v[170:173], v161 offset:3072
	v_add_u32_e32 v161, s82, v156
	ds_read_b128 v[174:177], v161
	ds_read_b128 v[178:181], v161 offset:1024
	ds_read_b128 v[182:185], v161 offset:2048
	ds_read_b128 v[186:189], v161 offset:3072
	s_add_u32 s52, s52, 0x2b0000
	s_addc_u32 s53, s53, 0
	s_mov_b32 m0, s57
	v_lshl_add_u64 v[230:231], s[52:53], 0, v[128:129]
	ds_read_b128 v[190:193], v160 offset:32768
	ds_read_b128 v[196:199], v160 offset:33792
	ds_read_b128 v[200:203], v160 offset:34816
	ds_read_b128 v[204:207], v160 offset:35840
	ds_read_b128 v[208:211], v160 offset:36864
	ds_read_b128 v[212:215], v160 offset:37888
	ds_read_b128 v[216:219], v160 offset:38912
	ds_read_b128 v[220:223], v160 offset:39936
	global_load_lds_dwordx4 v[230:231], off
	v_lshl_add_u64 v[230:231], s[52:53], 0, v[134:135]
	s_mov_b32 m0, s58
	s_nop 0
	global_load_lds_dwordx4 v[230:231], off
	s_waitcnt vmcnt(8)
	s_waitcnt lgkmcnt(0)
	s_barrier
	s_setprio 1
	v_mfma_f32_16x16x32_bf16 v[124:127], v[150:153], v[190:193], v[124:127]
	v_mfma_f32_16x16x32_bf16 v[120:123], v[166:169], v[190:193], v[120:123]
	v_mfma_f32_16x16x32_bf16 v[108:111], v[150:153], v[200:203], v[108:111]
	v_mfma_f32_16x16x32_bf16 v[104:107], v[166:169], v[200:203], v[104:107]
	v_mfma_f32_16x16x32_bf16 v[92:95], v[150:153], v[208:211], v[92:95]
	v_mfma_f32_16x16x32_bf16 v[88:91], v[166:169], v[208:211], v[88:91]
	v_mfma_f32_16x16x32_bf16 v[76:79], v[150:153], v[216:219], v[76:79]
	v_mfma_f32_16x16x32_bf16 v[72:75], v[166:169], v[216:219], v[72:75]
	v_mfma_f32_16x16x32_bf16 v[124:127], v[162:165], v[196:199], v[124:127]
	v_mfma_f32_16x16x32_bf16 v[120:123], v[170:173], v[196:199], v[120:123]
	v_mfma_f32_16x16x32_bf16 v[108:111], v[162:165], v[204:207], v[108:111]
	v_mfma_f32_16x16x32_bf16 v[104:107], v[170:173], v[204:207], v[104:107]
	v_mfma_f32_16x16x32_bf16 v[92:95], v[162:165], v[212:215], v[92:95]
	v_mfma_f32_16x16x32_bf16 v[88:91], v[170:173], v[212:215], v[88:91]
	v_mfma_f32_16x16x32_bf16 v[76:79], v[162:165], v[220:223], v[76:79]
	v_mfma_f32_16x16x32_bf16 v[72:75], v[170:173], v[220:223], v[72:75]
	v_mfma_f32_16x16x32_bf16 v[116:119], v[174:177], v[190:193], v[116:119]
	v_mfma_f32_16x16x32_bf16 v[112:115], v[182:185], v[190:193], v[112:115]
	v_mfma_f32_16x16x32_bf16 v[100:103], v[174:177], v[200:203], v[100:103]
	v_mfma_f32_16x16x32_bf16 v[96:99], v[182:185], v[200:203], v[96:99]
	v_mfma_f32_16x16x32_bf16 v[84:87], v[174:177], v[208:211], v[84:87]
	v_mfma_f32_16x16x32_bf16 v[80:83], v[182:185], v[208:211], v[80:83]
	v_mfma_f32_16x16x32_bf16 v[68:71], v[174:177], v[216:219], v[68:71]
	v_mfma_f32_16x16x32_bf16 v[64:67], v[182:185], v[216:219], v[64:67]
	v_mfma_f32_16x16x32_bf16 v[116:119], v[178:181], v[196:199], v[116:119]
	v_mfma_f32_16x16x32_bf16 v[112:115], v[186:189], v[196:199], v[112:115]
	v_mfma_f32_16x16x32_bf16 v[100:103], v[178:181], v[204:207], v[100:103]
	v_mfma_f32_16x16x32_bf16 v[96:99], v[186:189], v[204:207], v[96:99]
	v_mfma_f32_16x16x32_bf16 v[84:87], v[178:181], v[212:215], v[84:87]
	v_mfma_f32_16x16x32_bf16 v[80:83], v[186:189], v[212:215], v[80:83]
	v_mfma_f32_16x16x32_bf16 v[68:71], v[178:181], v[220:223], v[68:71]
	v_mfma_f32_16x16x32_bf16 v[64:67], v[186:189], v[220:223], v[64:67]
	s_setprio 0
	s_barrier
	s_add_i32 s52, s81, s54
	v_lshl_add_u64 v[154:155], v[154:155], 0, s[14:15]
	s_mov_b32 m0, s52
	ds_read_b128 v[190:193], v160 offset:49152
	ds_read_b128 v[196:199], v160 offset:50176
	ds_read_b128 v[200:203], v160 offset:51200
	ds_read_b128 v[204:207], v160 offset:52224
	ds_read_b128 v[208:211], v160 offset:53248
	ds_read_b128 v[212:215], v160 offset:54272
	ds_read_b128 v[216:219], v160 offset:55296
	ds_read_b128 v[220:223], v160 offset:56320
	global_load_lds_dwordx4 v[154:155], off
	s_add_i32 m0, s52, 0x2000
	s_add_u32 s48, s48, 0x2b0080
	v_lshl_add_u64 v[154:155], v[224:225], 0, s[14:15]
	s_addc_u32 s49, s49, 0
	s_add_i32 s52, s82, s54
	global_load_lds_dwordx4 v[154:155], off
	v_lshl_add_u64 v[154:155], s[48:49], 0, v[132:133]
	s_mov_b32 m0, s52
	s_nop 0
	global_load_lds_dwordx4 v[154:155], off
	v_lshl_add_u64 v[154:155], s[48:49], 0, v[136:137]
	s_add_i32 m0, s52, 0x2000
	s_nop 0
	global_load_lds_dwordx4 v[154:155], off
	v_lshl_add_u64 v[154:155], v[226:227], 0, s[14:15]
	s_mov_b32 m0, s62
	s_nop 0
	global_load_lds_dwordx4 v[154:155], off
	v_lshl_add_u64 v[154:155], v[228:229], 0, s[14:15]
	s_mov_b32 m0, s63
	s_nop 0
	global_load_lds_dwordx4 v[154:155], off
	s_nop 0
	s_waitcnt vmcnt(8)
	s_waitcnt lgkmcnt(0)
	s_barrier
	s_setprio 1
	v_mfma_f32_16x16x32_bf16 v[60:63], v[150:153], v[190:193], v[60:63]
	v_mfma_f32_16x16x32_bf16 v[56:59], v[166:169], v[190:193], v[56:59]
	v_mfma_f32_16x16x32_bf16 v[44:47], v[150:153], v[200:203], v[44:47]
	v_mfma_f32_16x16x32_bf16 v[40:43], v[166:169], v[200:203], v[40:43]
	v_mfma_f32_16x16x32_bf16 v[28:31], v[150:153], v[208:211], v[28:31]
	v_mfma_f32_16x16x32_bf16 v[24:27], v[166:169], v[208:211], v[24:27]
	v_mfma_f32_16x16x32_bf16 v[12:15], v[150:153], v[216:219], v[12:15]
	v_mfma_f32_16x16x32_bf16 v[8:11], v[166:169], v[216:219], v[8:11]
	v_mfma_f32_16x16x32_bf16 v[60:63], v[162:165], v[196:199], v[60:63]
	v_mfma_f32_16x16x32_bf16 v[56:59], v[170:173], v[196:199], v[56:59]
	v_mfma_f32_16x16x32_bf16 v[44:47], v[162:165], v[204:207], v[44:47]
	v_mfma_f32_16x16x32_bf16 v[40:43], v[170:173], v[204:207], v[40:43]
	v_mfma_f32_16x16x32_bf16 v[28:31], v[162:165], v[212:215], v[28:31]
	v_mfma_f32_16x16x32_bf16 v[24:27], v[170:173], v[212:215], v[24:27]
	v_mfma_f32_16x16x32_bf16 v[12:15], v[162:165], v[220:223], v[12:15]
	v_mfma_f32_16x16x32_bf16 v[8:11], v[170:173], v[220:223], v[8:11]
	v_mfma_f32_16x16x32_bf16 v[52:55], v[174:177], v[190:193], v[52:55]
	v_mfma_f32_16x16x32_bf16 v[48:51], v[182:185], v[190:193], v[48:51]
	v_mfma_f32_16x16x32_bf16 v[36:39], v[174:177], v[200:203], v[36:39]
	v_mfma_f32_16x16x32_bf16 v[32:35], v[182:185], v[200:203], v[32:35]
	v_mfma_f32_16x16x32_bf16 v[20:23], v[174:177], v[208:211], v[20:23]
	v_mfma_f32_16x16x32_bf16 v[16:19], v[182:185], v[208:211], v[16:19]
	v_mfma_f32_16x16x32_bf16 v[4:7], v[174:177], v[216:219], v[4:7]
	v_mfma_f32_16x16x32_bf16 v[0:3], v[182:185], v[216:219], v[0:3]
	v_mfma_f32_16x16x32_bf16 v[52:55], v[178:181], v[196:199], v[52:55]
	v_mfma_f32_16x16x32_bf16 v[48:51], v[186:189], v[196:199], v[48:51]
	v_mfma_f32_16x16x32_bf16 v[36:39], v[178:181], v[204:207], v[36:39]
	v_mfma_f32_16x16x32_bf16 v[32:35], v[186:189], v[204:207], v[32:35]
	v_mfma_f32_16x16x32_bf16 v[20:23], v[178:181], v[212:215], v[20:23]
	v_mfma_f32_16x16x32_bf16 v[16:19], v[186:189], v[212:215], v[16:19]
	v_mfma_f32_16x16x32_bf16 v[4:7], v[178:181], v[220:223], v[4:7]
	v_mfma_f32_16x16x32_bf16 v[0:3], v[186:189], v[220:223], v[0:3]
	s_setprio 0
	s_barrier
	s_add_u32 s50, s50, 0x100
	s_addc_u32 s51, s51, 0
	s_add_u32 s78, s78, 0x100
	s_addc_u32 s79, s79, 0
	s_cmp_ge_i32 s80, s76
	s_mov_b32 s48, s80
	s_cbranch_scc0 .LBB0_4304
	s_and_b64 vcc, exec, s[16:17]
	s_cbranch_vccz .LBB0_4307
	s_barrier
